# v011 + MoBA own-block next-tile K/V prefetch into spare VGPRs + packed f32 ops in attention code split into plain ops (bit-identical)
# speedup vs baseline: 1.0056x; 1.0053x over previous
; __device__ __forceinline__ unsigned pk2(float lo, float hi) { return pg8::cvt_pk_bf16(lo, hi); }
; #define WG_BAR() __syncthreads()
; __device__ __forceinline__ void attn_store(bf16* yrow, const f32x16& o0, const f32x16& o1, float inv, int hi) {
; #pragma unroll
;     for (int rg = 0; rg < 4; ++rg) {
;         u32x2 w0, w1;
;         w0.x = pk2(o0[4 * rg] * inv, o0[4 * rg + 1] * inv); w0.y = pk2(o0[4 * rg + 2] * inv, o0[4 * rg + 3] * inv);
;         w1.x = pk2(o1[4 * rg] * inv, o1[4 * rg + 1] * inv); w1.y = pk2(o1[4 * rg + 2] * inv, o1[4 * rg + 3] * inv);
;         *(u32x2*)(yrow + 8 * rg + 4 * hi) = w0; *(u32x2*)(yrow + 32 + 8 * rg + 4 * hi) = w1;
;     }
; __device__ __forceinline__ void moba_unit(int b, int h, int qb, const bf16* qkv, const bf16* KF, const bf16* VF, bf16* Y, const float* kmean, LAS unsigned char* lds) {
;     ...
;         attn_store(Y + row * 1536 + 1024 + h * 64, o0, o1, 1.f / den, hi);
;     }
;     WG_BAR();
.LBB0_189:
	s_or_b64 exec, exec, s[0:1]
	v_readlane_b32 s0, v252, 9
	v_readlane_b32 s1, v252, 10
	s_movk_i32 s2, 0xc00
	s_lshl_b32 s46, s19, 1
	v_mov_b64_e32 v[14:15], s[0:1]
	v_mad_u64_u32 v[14:15], s[0:1], v114, s2, v[14:15]
	v_mov_b32_e32 v12, v15
	v_mad_u64_u32 v[24:25], s[0:1], v115, s2, v[12:13]
	v_div_scale_f32 v12, s[0:1], v13, v13, 1.0
	v_rcp_f32_e32 v25, v12
	v_mov_b32_e32 v15, v24
	v_lshl_add_u64 v[14:15], v[14:15], 0, s[46:47]
	s_add_i32 s18, s18, 1
	v_fma_f32 v24, -v12, v25, 1.0
	v_fmac_f32_e32 v25, v24, v25
	v_div_scale_f32 v24, vcc, 1.0, v13, 1.0
	v_mul_f32_e32 v26, v24, v25
	v_fma_f32 v27, -v12, v26, v24
	v_fmac_f32_e32 v26, v27, v25
	v_fma_f32 v12, -v12, v26, v24
	v_div_fmas_f32 v12, v12, v25, v26
	v_div_fixup_f32 v12, v12, v13, 1.0
	v_mul_f32_e32 v24, v40, v12
	v_mul_f32_e32 v25, v41, v12
	v_mul_f32_e32 v26, v42, v12
	v_mul_f32_e32 v27, v43, v12
	v_cvt_pk_bf16_f32 v24, v24, v25
	v_cvt_pk_bf16_f32 v25, v26, v27
	v_mul_f32_e32 v26, v36, v12
	v_mul_f32_e32 v27, v37, v12
	v_mul_f32_e32 v28, v38, v12
	v_mul_f32_e32 v29, v39, v12
	v_lshl_add_u64 v[14:15], v[14:15], 0, v[64:65]
	v_cvt_pk_bf16_f32 v26, v26, v27
	v_cvt_pk_bf16_f32 v27, v28, v29
	s_add_u32 s8, s8, 0x2000
	global_store_dwordx2 v[14:15], v[24:25], off offset:2048
	global_store_dwordx2 v[14:15], v[26:27], off offset:2112
	v_mul_f32_e32 v24, v32, v12
	v_mul_f32_e32 v25, v33, v12
	v_mul_f32_e32 v26, v34, v12
	v_mul_f32_e32 v27, v35, v12
	v_mul_f32_e32 v16, v16, v12
	v_mul_f32_e32 v17, v17, v12
	v_mul_f32_e32 v18, v18, v12
	v_mul_f32_e32 v19, v19, v12
	v_mul_f32_e32 v4, v4, v12
	v_mul_f32_e32 v5, v5, v12
	v_mul_f32_e32 v6, v6, v12
	v_mul_f32_e32 v7, v7, v12
	s_addc_u32 s9, s9, 0
	v_cvt_pk_bf16_f32 v24, v24, v25
	v_cvt_pk_bf16_f32 v25, v26, v27
	v_mul_f32_e32 v20, v20, v12
	v_mul_f32_e32 v21, v21, v12
	v_mul_f32_e32 v22, v22, v12
	v_mul_f32_e32 v23, v23, v12
	v_cvt_pk_bf16_f32 v16, v16, v17
	v_cvt_pk_bf16_f32 v17, v18, v19
	v_mul_f32_e32 v8, v8, v12
	v_mul_f32_e32 v9, v9, v12
	v_mul_f32_e32 v10, v10, v12
	v_mul_f32_e32 v11, v11, v12
	v_cvt_pk_bf16_f32 v4, v4, v5
	v_cvt_pk_bf16_f32 v5, v6, v7
	v_mul_f32_e32 v0, v0, v12
	v_mul_f32_e32 v1, v1, v12
	v_mul_f32_e32 v2, v2, v12
	v_mul_f32_e32 v3, v3, v12
	s_cmp_eq_u32 s18, 8
	v_cvt_pk_bf16_f32 v20, v20, v21
	v_cvt_pk_bf16_f32 v21, v22, v23
	global_store_dwordx2 v[14:15], v[24:25], off offset:2064
	global_store_dwordx2 v[14:15], v[20:21], off offset:2128
	v_cvt_pk_bf16_f32 v8, v8, v9
	v_cvt_pk_bf16_f32 v9, v10, v11
	global_store_dwordx2 v[14:15], v[16:17], off offset:2080
	global_store_dwordx2 v[14:15], v[8:9], off offset:2144
	v_cvt_pk_bf16_f32 v0, v0, v1
	v_cvt_pk_bf16_f32 v1, v2, v3
	global_store_dwordx2 v[14:15], v[4:5], off offset:2096
	global_store_dwordx2 v[14:15], v[0:1], off offset:2160
	s_barrier
	s_cbranch_scc1 .LBB0_379

; #define LAS __attribute__((address_space(3)))
; __device__ __forceinline__ float bflo(unsigned u) { return __uint_as_float(u << 16); }
; __device__ __forceinline__ float bfhi(unsigned u) { return __uint_as_float(u & 0xffff0000u); }
; __device__ __forceinline__ void moba_unit(int b, int h, int qb, const bf16* qkv, const bf16* KF, const bf16* VF, bf16* Y, const float* kmean, LAS unsigned char* lds) {
;     ...
;         for (int n = 0; n < qb; ++n) {
;             float part = 0.f;
; #pragma unroll
;             for (int d0 = 0; d0 < 4; ++d0) {
;                 const f32x4 ka = *(LAS const f32x4*)(KM + n * 64 + 16 * d0 + 8 * hi), kb = *(LAS const f32x4*)(KM + n * 64 + 16 * d0 + 8 * hi + 4);
;                 const u32x4 q = __builtin_bit_cast(u32x4, qf[d0]);
;                 part += bflo(q.x) * ka.x + bfhi(q.x) * ka.y + bflo(q.y) * ka.z + bfhi(q.y) * ka.w + bflo(q.z) * kb.x + bfhi(q.z) * kb.y + bflo(q.w) * kb.z + bfhi(q.w) * kb.w;
;             }
;             const float g = part + __shfl_xor(part, 32);
;             if (g > v1) { v3 = v2; i3 = i2; v2 = v1; i2 = i1; v1 = g; i1 = n; }
;             else if (g > v2) { v3 = v2; i3 = i2; v2 = g; i2 = n; }
;             else if (g > v3) { v3 = g; i3 = n; }
;         }
.LBB0_197:
	ds_read_b128 v[42:45], v36
	ds_read_b128 v[46:49], v36 offset:64
	ds_read_b128 v[50:53], v36 offset:16
	ds_read_b128 v[54:57], v36 offset:80
	s_waitcnt lgkmcnt(3)
	v_mov_b32_e32 v58, v42
	s_waitcnt lgkmcnt(2)
	v_mov_b32_e32 v59, v46
	v_mov_b32_e32 v46, v43
	v_mul_f32_e32 v42, v46, v18
	v_mul_f32_e32 v43, v47, v19
	v_mov_b32_e32 v46, v44
	v_fma_f32 v42, v58, v16, v42
	v_fma_f32 v43, v59, v17, v43
	v_mov_b32_e32 v47, v48
	v_fma_f32 v42, v46, v20, v42
	v_fma_f32 v43, v47, v21, v43
	v_mov_b32_e32 v48, v45
	v_fma_f32 v42, v48, v8, v42
	v_fma_f32 v43, v49, v9, v43
	s_waitcnt lgkmcnt(1)
	v_mov_b32_e32 v44, v50
	s_waitcnt lgkmcnt(0)
	v_mov_b32_e32 v45, v54
	v_fma_f32 v42, v44, v12, v42
	v_fma_f32 v43, v45, v13, v43
	v_mov_b32_e32 v54, v51
	v_fma_f32 v42, v54, v22, v42
	v_fma_f32 v43, v55, v23, v43
	v_mov_b32_e32 v44, v52
	v_mov_b32_e32 v45, v56
	v_fma_f32 v42, v44, v24, v42
	v_fma_f32 v43, v45, v25, v43
	v_mov_b32_e32 v56, v53
	v_fma_f32 v50, v56, v10, v42
	v_fma_f32 v51, v57, v11, v43
	ds_read_b128 v[42:45], v36 offset:128
	ds_read_b128 v[46:49], v36 offset:192
	v_add_f32_e32 v50, 0, v50
	v_add_f32_e32 v60, v50, v51
	ds_read_b128 v[50:53], v36 offset:144
	ds_read_b128 v[54:57], v36 offset:208
	s_waitcnt lgkmcnt(3)
	v_mov_b32_e32 v58, v42
	s_waitcnt lgkmcnt(2)
	v_mov_b32_e32 v59, v46
	v_mov_b32_e32 v46, v43
	v_mul_f32_e32 v42, v46, v26
	v_mul_f32_e32 v43, v47, v27
	v_mov_b32_e32 v46, v44
	v_fma_f32 v42, v58, v14, v42
	v_fma_f32 v43, v59, v15, v43
	v_mov_b32_e32 v47, v48
	v_fma_f32 v42, v46, v28, v42
	v_fma_f32 v43, v47, v29, v43
	v_mov_b32_e32 v48, v45
	v_fma_f32 v42, v48, v4, v42
	v_fma_f32 v43, v49, v5, v43
	s_waitcnt lgkmcnt(1)
	v_mov_b32_e32 v44, v50
	s_waitcnt lgkmcnt(0)
	v_mov_b32_e32 v45, v54
	v_fma_f32 v42, v44, v0, v42
	v_fma_f32 v43, v45, v1, v43
	v_mov_b32_e32 v54, v51
	v_fma_f32 v42, v54, v30, v42
	v_fma_f32 v43, v55, v31, v43
	v_mov_b32_e32 v44, v52
	v_mov_b32_e32 v45, v56
	v_fma_f32 v42, v44, v32, v42
	v_fma_f32 v43, v45, v33, v43
	v_mov_b32_e32 v56, v53
	v_fma_f32 v42, v56, v6, v42
	v_fma_f32 v43, v57, v7, v43
	v_mov_b32_e32 v45, v3
	v_add_f32_e32 v42, v60, v42
	v_add_f32_e32 v42, v42, v43
	ds_bpermute_b32 v43, v37, v42
	s_waitcnt lgkmcnt(0)
	v_add_f32_e32 v44, v42, v43
	v_cmp_ngt_f32_e32 vcc, v44, v3
	v_mov_b32_e32 v43, s12
	v_mov_b32_e32 v42, v38
	s_and_saveexec_b64 s[0:1], vcc
	s_cbranch_execz .LBB0_203
	v_cmp_ngt_f32_e32 vcc, v44, v39
	v_mov_b32_e32 v42, s12
	s_and_saveexec_b64 s[6:7], vcc
	s_cbranch_execz .LBB0_202
	v_cmp_gt_f32_e32 vcc, v44, v41
	s_and_saveexec_b64 s[10:11], vcc
	v_mov_b32_e32 v2, s12
	v_mov_b32_e32 v41, v44
	s_or_b64 exec, exec, s[10:11]
	v_mov_b32_e32 v44, v39
	v_mov_b32_e32 v39, v41
	v_mov_b32_e32 v42, v40
	v_mov_b32_e32 v40, v2

; #define SB_() __builtin_amdgcn_sched_barrier(0)
; __device__ __forceinline__ void tile_qk_fast(const KFr& f, const bf16x8 (&qf)[4], const bf16x8& kx0, const bf16x8& kx1, const bf16x8& qx, u32x4 (&pw)[4],
;                                              f32x16& o0, f32x16& o1, float& m, float& l, float off) {
;     ...
;     p0 = __builtin_amdgcn_mfma_f32_32x32x16_bf16(kx0, qx, p0, 0, 0, 0);
;     p1 = __builtin_amdgcn_mfma_f32_32x32x16_bf16(kx1, qx, p1, 0, 0, 0);
; #pragma unroll
;     for (int d0 = 0; d0 < 4; ++d0) {
;         p0 = __builtin_amdgcn_mfma_f32_32x32x16_bf16(f.a[0][d0], qf[d0], p0, 0, 0, 0);
;         p1 = __builtin_amdgcn_mfma_f32_32x32x16_bf16(f.a[1][d0], qf[d0], p1, 0, 0, 0);
;     }
;     constexpr float C2 = 0.125f * LOG2E;
;     float mr = fmaxf(p0[0], p1[0]);
; #pragma unroll
;     for (int r = 1; r < 16; ++r) mr = fmaxf(fmaxf(mr, p0[r]), p1[r]);
;     float mx = fmaf(mr, C2, off);
;     mx = fmaxf(mx, __shfl_xor(mx, 32));
;     const float mn = fmaxf(m, mx);
;     if (__ballot(mn > m) != 0ull) {
;         const float alpha = __builtin_amdgcn_exp2f(m - mn); l *= alpha;
; #pragma unroll
;         for (int r = 0; r < 16; ++r) { o0[r] *= alpha; o1[r] *= alpha; }
;     }
;     m = mn;
;     const float sh = off - mn;
;     float rs = 0.f;
; #pragma unroll
;     for (int r = 0; r < 16; ++r) { p0[r] = __builtin_amdgcn_exp2f(fmaf(p0[r], C2, sh)); p1[r] = __builtin_amdgcn_exp2f(fmaf(p1[r], C2, sh)); rs += p0[r] + p1[r]; }
;     l += rs;
; __device__ __forceinline__ void moba_unit(int b, int h, int qb, const bf16* qkv, const bf16* KF, const bf16* VF, bf16* Y, const float* kmean, LAS unsigned char* lds) {
;     ...
;             const int n_c = n; const bool valid_c = valid; const int q2_c = q2;
;             vp = (const char*)VFh + (size_t)(4 * n_c) * 8192 + lane * 16; asm volatile("" : "+v"(vp));
;             float m2 = -1e30f, l2 = 0.f; f32x16 a0, a1;
; #pragma unroll
;             for (int r = 0; r < 16; ++r) { a0[r] = 0.f; a1[r] = 0.f; }
;             const int kq0 = 256 * n_c - (256 * qb + q2_c);
;             TASK_ADV();
;             loadV(v0, vp); SB_();
;             loadK(k1, kp); SB_(); tile_qk_fast(k0, qg, kx0, kx1, qx, pw, a0, a1, m2, l2, sl2 * (float)(kq0)); SB_();
.LBB0_254:
	global_load_dwordx4 v[162:165], v[0:1], off
	global_load_dwordx4 v[154:157], v[0:1], off offset:1024
	global_load_dwordx4 v[146:149], v[0:1], off offset:2048
	global_load_dwordx4 v[142:145], v[0:1], off offset:3072
	v_lshl_add_u64 v[0:1], v[0:1], 0, s[56:57]
	global_load_dwordx4 v[170:173], v[0:1], off
	global_load_dwordx4 v[166:169], v[0:1], off offset:1024
	global_load_dwordx4 v[158:161], v[0:1], off offset:2048
	global_load_dwordx4 v[150:153], v[0:1], off offset:3072
	s_sub_i32 s2, s26, s20
	s_lshl_b32 s2, s2, 8
	v_sub_u32_e32 v236, s2, v234
	v_lshl_add_u64 v[216:217], v[0:1], 0, s[56:57]
	v_lshl_add_u64 v[0:1], v[214:215], 0, s[56:57]
	global_load_dwordx4 v[194:197], v[214:215], off
	global_load_dwordx4 v[186:189], v[214:215], off offset:1024
	global_load_dwordx4 v[182:185], v[214:215], off offset:2048
	global_load_dwordx4 v[174:177], v[214:215], off offset:3072
	global_load_dwordx4 v[202:205], v[0:1], off
	global_load_dwordx4 v[198:201], v[0:1], off offset:1024
	global_load_dwordx4 v[190:193], v[0:1], off offset:2048
	global_load_dwordx4 v[178:181], v[0:1], off offset:3072
	v_lshl_add_u64 v[218:219], v[0:1], 0, s[56:57]
	v_mfma_f32_32x32x16_bf16 v[48:63], v[70:73], v[66:69], 0
	v_cvt_f32_i32_e32 v64, v236
	s_mov_b32 s2, 0xf149f2ca
	s_waitcnt lgkmcnt(0)
	v_mfma_f32_32x32x16_bf16 v[32:47], v[74:77], v[66:69], 0
	s_waitcnt lgkmcnt(0)
	v_mfma_f32_32x32x16_bf16 v[16:31], v[106:109], v[138:141], v[48:63]
	v_mfma_f32_32x32x16_bf16 v[0:15], v[122:125], v[138:141], v[32:47]
	v_mfma_f32_32x32x16_bf16 v[16:31], v[102:105], v[134:137], v[16:31]
	v_mfma_f32_32x32x16_bf16 v[0:15], v[118:121], v[134:137], v[0:15]
	v_mfma_f32_32x32x16_bf16 v[16:31], v[98:101], v[130:133], v[16:31]
	v_mul_f32_e32 v98, v230, v64
	v_mfma_f32_32x32x16_bf16 v[0:15], v[114:117], v[130:133], v[0:15]
	v_mfma_f32_32x32x16_bf16 v[0:15], v[110:113], v[126:129], v[0:15]
	v_mfma_f32_32x32x16_bf16 v[16:31], v[94:97], v[126:129], v[16:31]
	s_nop 10
	v_max_f32_e32 v99, v0, v0
	v_max_f32_e32 v94, v16, v16
	v_max_f32_e32 v94, v94, v99
	v_max3_f32 v94, v94, v17, v1
	v_max3_f32 v94, v94, v18, v2
	v_max3_f32 v94, v94, v19, v3
	v_max3_f32 v94, v94, v20, v4
	v_max3_f32 v94, v94, v21, v5
	v_max3_f32 v94, v94, v22, v6
	v_max3_f32 v94, v94, v23, v7
	v_max3_f32 v94, v94, v24, v8
	v_max3_f32 v94, v94, v25, v9
	v_max3_f32 v94, v94, v26, v10
	v_max3_f32 v94, v94, v27, v11
	v_max3_f32 v94, v94, v28, v12
	v_max3_f32 v94, v94, v29, v13
	v_max3_f32 v94, v94, v30, v14
	v_max3_f32 v94, v94, v31, v15
	v_fmac_f32_e32 v98, 0x3e38aa3b, v94
	v_mbcnt_hi_u32_b32 v94, -1, v220
	v_and_b32_e32 v96, 64, v94
	v_xor_b32_e32 v95, 32, v94
	v_add_u32_e32 v96, 64, v96
	v_cmp_lt_i32_e32 vcc, v95, v96
	s_nop 1
	v_cndmask_b32_e32 v94, v94, v95, vcc
	v_lshlrev_b32_e32 v235, 2, v94
	ds_bpermute_b32 v94, v235, v98
	s_waitcnt lgkmcnt(0)
	v_max3_f32 v238, v98, v94, s2
	v_fma_f32 v110, v230, v64, -v238
	v_fmamk_f32 v0, v0, 0x3e38aa3b, v110
	v_sub_f32_e32 v94, 0xf149f2ca, v238
	v_fmamk_f32 v16, v16, 0x3e38aa3b, v110
	v_exp_f32_e32 v112, v0
	v_fmamk_f32 v0, v17, 0x3e38aa3b, v110
	v_exp_f32_e32 v94, v94
	v_exp_f32_e32 v111, v16
	v_exp_f32_e32 v64, v0
	v_fmamk_f32 v0, v1, 0x3e38aa3b, v110
	v_exp_f32_e32 v16, v0
	v_cmp_lt_f32_e32 vcc, s2, v238
	s_cmp_lg_u64 vcc, 0
	v_mul_f32_e32 v94, 0, v94
	s_cselect_b64 vcc, -1, 0
	v_add_f32_e32 v17, v112, v111
	v_cndmask_b32_e32 v0, 0, v94, vcc
	v_add_f32_e32 v94, v16, v64
	v_add_f32_e32 v95, v17, v65
	v_fmamk_f32 v2, v2, 0x3e38aa3b, v110
	v_add_f32_e32 v96, v94, v94
	v_add_f32_e32 v97, v94, v95
	v_fmamk_f32 v17, v18, 0x3e38aa3b, v110
	v_exp_f32_e32 v113, v2
	v_fmamk_f32 v2, v19, 0x3e38aa3b, v110
	v_exp_f32_e32 v17, v17
	v_exp_f32_e32 v96, v2
	v_fmamk_f32 v2, v3, 0x3e38aa3b, v110
	v_exp_f32_e32 v18, v2
	v_add_f32_e32 v19, v113, v17
	v_fmamk_f32 v4, v4, 0x3e38aa3b, v110
	v_exp_f32_e32 v114, v4
	v_add_f32_e32 v94, v18, v96
	v_add_f32_e32 v95, v19, v97
	v_fmamk_f32 v19, v20, 0x3e38aa3b, v110
	v_add_f32_e32 v98, v94, v94
	v_add_f32_e32 v99, v94, v95
	v_exp_f32_e32 v19, v19
	v_fmamk_f32 v4, v21, 0x3e38aa3b, v110
	v_fmamk_f32 v5, v5, 0x3e38aa3b, v110
	v_exp_f32_e32 v98, v4
	v_exp_f32_e32 v20, v5
	v_add_f32_e32 v21, v114, v19
	v_fmamk_f32 v6, v6, 0x3e38aa3b, v110
	v_exp_f32_e32 v115, v6
	v_add_f32_e32 v94, v20, v98
	v_add_f32_e32 v95, v21, v99
	v_fmamk_f32 v21, v22, 0x3e38aa3b, v110
	v_add_f32_e32 v100, v94, v94
	v_add_f32_e32 v101, v94, v95
	v_fmamk_f32 v6, v23, 0x3e38aa3b, v110
	v_exp_f32_e32 v21, v21
	v_exp_f32_e32 v100, v6
	v_fmamk_f32 v6, v7, 0x3e38aa3b, v110
	v_exp_f32_e32 v22, v6
	v_add_f32_e32 v23, v115, v21
	v_fmamk_f32 v8, v8, 0x3e38aa3b, v110
	v_exp_f32_e32 v116, v8
	v_add_f32_e32 v94, v22, v100
	v_add_f32_e32 v95, v23, v101
	v_fmamk_f32 v23, v24, 0x3e38aa3b, v110
	v_add_f32_e32 v102, v94, v94
	v_add_f32_e32 v103, v94, v95
	v_fmamk_f32 v8, v25, 0x3e38aa3b, v110
	v_exp_f32_e32 v23, v23
	v_exp_f32_e32 v102, v8
	v_fmamk_f32 v8, v9, 0x3e38aa3b, v110
	v_exp_f32_e32 v24, v8
	v_add_f32_e32 v25, v116, v23
	v_fmamk_f32 v10, v10, 0x3e38aa3b, v110
	v_exp_f32_e32 v117, v10
	v_add_f32_e32 v94, v24, v102
	v_add_f32_e32 v95, v25, v103
	v_fmamk_f32 v25, v26, 0x3e38aa3b, v110
	v_add_f32_e32 v104, v94, v94
	v_add_f32_e32 v105, v94, v95
	v_fmamk_f32 v10, v27, 0x3e38aa3b, v110
	v_exp_f32_e32 v25, v25
	v_exp_f32_e32 v104, v10
	v_fmamk_f32 v10, v11, 0x3e38aa3b, v110
	v_exp_f32_e32 v26, v10
	v_add_f32_e32 v27, v117, v25
	v_fmamk_f32 v12, v12, 0x3e38aa3b, v110
	v_exp_f32_e32 v118, v12
	v_add_f32_e32 v94, v26, v104
	v_add_f32_e32 v95, v27, v105
	v_fmamk_f32 v27, v28, 0x3e38aa3b, v110
	v_add_f32_e32 v106, v94, v94
	v_add_f32_e32 v107, v94, v95
	v_fmamk_f32 v12, v29, 0x3e38aa3b, v110
	v_exp_f32_e32 v27, v27
; __device__ __forceinline__ unsigned pk2(float lo, float hi) { return pg8::cvt_pk_bf16(lo, hi); }
; #define SB_() __builtin_amdgcn_sched_barrier(0)
; __device__ __forceinline__ void tile_qk_fast(const KFr& f, const bf16x8 (&qf)[4], const bf16x8& kx0, const bf16x8& kx1, const bf16x8& qx, u32x4 (&pw)[4],
;                                              f32x16& o0, f32x16& o1, float& m, float& l, float off) {
;     ...
;     if (__ballot(mn > m) != 0ull) {
;         const float alpha = __builtin_amdgcn_exp2f(m - mn); l *= alpha;
; #pragma unroll
;         for (int r = 0; r < 16; ++r) { o0[r] *= alpha; o1[r] *= alpha; }
;     }
;     m = mn;
;     const float sh = off - mn;
;     float rs = 0.f;
; #pragma unroll
;     for (int r = 0; r < 16; ++r) { p0[r] = __builtin_amdgcn_exp2f(fmaf(p0[r], C2, sh)); p1[r] = __builtin_amdgcn_exp2f(fmaf(p1[r], C2, sh)); rs += p0[r] + p1[r]; }
;     l += rs;
;     pw[0] = (u32x4){pk2(p0[0], p0[1]), pk2(p0[2], p0[3]), pk2(p0[4], p0[5]), pk2(p0[6], p0[7])};
;     pw[1] = (u32x4){pk2(p0[8], p0[9]), pk2(p0[10], p0[11]), pk2(p0[12], p0[13]), pk2(p0[14], p0[15])};
;     pw[2] = (u32x4){pk2(p1[0], p1[1]), pk2(p1[2], p1[3]), pk2(p1[4], p1[5]), pk2(p1[6], p1[7])};
;     pw[3] = (u32x4){pk2(p1[8], p1[9]), pk2(p1[10], p1[11]), pk2(p1[12], p1[13]), pk2(p1[14], p1[15])};
; }
; __device__ __forceinline__ void tile_pv(const VFr& f, const u32x4 (&pw)[4], f32x16& o0, f32x16& o1) {
; #pragma unroll
;     for (int ks = 0; ks < 4; ++ks) {
;         const bf16x8 P = __builtin_bit_cast(bf16x8, pw[ks]);
;         o0 = __builtin_amdgcn_mfma_f32_32x32x16_bf16(f.a[0][ks], P, o0, 0, 0, 0);
;         o1 = __builtin_amdgcn_mfma_f32_32x32x16_bf16(f.a[1][ks], P, o1, 0, 0, 0);
; __device__ __forceinline__ void moba_unit(int b, int h, int qb, const bf16* qkv, const bf16* KF, const bf16* VF, bf16* Y, const float* kmean, LAS unsigned char* lds) {
;     ...
;             loadK(k1, kp); SB_(); tile_qk_fast(k0, qg, kx0, kx1, qx, pw, a0, a1, m2, l2, sl2 * (float)(kq0)); SB_();
;             tile_pv(v0, pw, a0, a1); SB_();
;             loadV(v0, vp); loadK(k0, kp); SB_(); tile_qk_fast(k1, qg, kx0, kx1, qx, pw, a0, a1, m2, l2, sl2 * (float)(kq0 + 64)); SB_();
	v_exp_f32_e32 v106, v12
	v_fmamk_f32 v12, v13, 0x3e38aa3b, v110
	v_exp_f32_e32 v28, v12
	v_add_f32_e32 v29, v118, v27
	v_fmamk_f32 v14, v14, 0x3e38aa3b, v110
	v_exp_f32_e32 v119, v14
	v_add_f32_e32 v94, v28, v106
	v_add_f32_e32 v95, v29, v107
	v_fmamk_f32 v29, v30, 0x3e38aa3b, v110
	v_add_f32_e32 v108, v94, v94
	v_add_f32_e32 v109, v94, v95
	v_exp_f32_e32 v29, v29
	v_fmamk_f32 v14, v31, 0x3e38aa3b, v110
	v_fmac_f32_e32 v110, 0x3e38aa3b, v15
	v_exp_f32_e32 v108, v14
	v_exp_f32_e32 v30, v110
	v_add_f32_e32 v31, v119, v29
	v_mov_b32_e32 v1, v0
	v_mov_b32_e32 v2, v0
	v_add_f32_e32 v94, v30, v108
	v_add_f32_e32 v95, v31, v109
	v_mov_b32_e32 v3, v0
	v_add_f32_e32 v31, v94, v95
	v_mov_b32_e32 v4, v0
	v_mov_b32_e32 v5, v0
	v_mov_b32_e32 v6, v0
	v_mov_b32_e32 v7, v0
	v_mov_b32_e32 v8, v0
	v_mov_b32_e32 v9, v0
	v_mov_b32_e32 v10, v0
	v_mov_b32_e32 v11, v0
	v_mov_b32_e32 v12, v0
	v_mov_b32_e32 v13, v0
	v_mov_b32_e32 v14, v0
	v_mov_b32_e32 v15, v0
	v_add_f32_e32 v237, v0, v31
	v_cvt_pk_bf16_f32 v94, v111, v64
	v_cvt_pk_bf16_f32 v95, v17, v96
	v_cvt_pk_bf16_f32 v96, v19, v98
	v_cvt_pk_bf16_f32 v97, v21, v100
	v_cvt_pk_bf16_f32 v98, v23, v102
	v_cvt_pk_bf16_f32 v99, v25, v104
	v_cvt_pk_bf16_f32 v100, v27, v106
	v_cvt_pk_bf16_f32 v101, v29, v108
	v_cvt_pk_bf16_f32 v102, v112, v16
	v_cvt_pk_bf16_f32 v103, v113, v18
	v_cvt_pk_bf16_f32 v104, v114, v20
	v_cvt_pk_bf16_f32 v105, v115, v22
	v_cvt_pk_bf16_f32 v106, v116, v24
	v_cvt_pk_bf16_f32 v107, v117, v26
	v_cvt_pk_bf16_f32 v108, v118, v28
	v_cvt_pk_bf16_f32 v109, v119, v30
	s_waitcnt vmcnt(0)
	v_mfma_f32_32x32x16_bf16 v[16:31], v[162:165], v[94:97], v[0:15]
	v_mfma_f32_32x32x16_bf16 v[0:15], v[170:173], v[94:97], v[0:15]
	v_mfma_f32_32x32x16_bf16 v[16:31], v[154:157], v[98:101], v[16:31]
	v_mfma_f32_32x32x16_bf16 v[0:15], v[166:169], v[98:101], v[0:15]
	v_mfma_f32_32x32x16_bf16 v[16:31], v[146:149], v[102:105], v[16:31]
	v_mfma_f32_32x32x16_bf16 v[0:15], v[158:161], v[102:105], v[0:15]
	v_mfma_f32_32x32x16_bf16 v[16:31], v[142:145], v[106:109], v[16:31]
	v_mfma_f32_32x32x16_bf16 v[0:15], v[150:153], v[106:109], v[0:15]
	v_lshl_add_u64 v[94:95], v[216:217], 0, s[56:57]
	global_load_dwordx4 v[162:165], v[216:217], off
	global_load_dwordx4 v[154:157], v[216:217], off offset:1024
	global_load_dwordx4 v[146:149], v[216:217], off offset:2048
	global_load_dwordx4 v[142:145], v[216:217], off offset:3072
	v_lshl_add_u64 v[216:217], v[218:219], 0, s[56:57]
	v_lshl_add_u64 v[214:215], v[94:95], 0, s[56:57]
	global_load_dwordx4 v[170:173], v[94:95], off
	global_load_dwordx4 v[166:169], v[94:95], off offset:1024
	global_load_dwordx4 v[158:161], v[94:95], off offset:2048
	global_load_dwordx4 v[150:153], v[94:95], off offset:3072
	global_load_dwordx4 v[106:109], v[218:219], off
	global_load_dwordx4 v[102:105], v[218:219], off offset:1024
	global_load_dwordx4 v[98:101], v[218:219], off offset:2048
	global_load_dwordx4 v[94:97], v[218:219], off offset:3072
	global_load_dwordx4 v[122:125], v[216:217], off
	global_load_dwordx4 v[118:121], v[216:217], off offset:1024
	global_load_dwordx4 v[114:117], v[216:217], off offset:2048
	global_load_dwordx4 v[110:113], v[216:217], off offset:3072
	v_lshl_add_u64 v[216:217], v[216:217], 0, s[56:57]
	v_mfma_f32_32x32x16_bf16 v[48:63], v[194:197], v[138:141], v[48:63]
	v_add_u32_e32 v64, 64, v236
	v_cvt_f32_i32_e32 v64, v64
	v_mul_f32_e32 v64, v230, v64
	v_mfma_f32_32x32x16_bf16 v[32:47], v[202:205], v[138:141], v[32:47]
	v_mfma_f32_32x32x16_bf16 v[48:63], v[186:189], v[134:137], v[48:63]
	v_mfma_f32_32x32x16_bf16 v[32:47], v[198:201], v[134:137], v[32:47]
	v_mfma_f32_32x32x16_bf16 v[48:63], v[182:185], v[130:133], v[48:63]
	v_mfma_f32_32x32x16_bf16 v[32:47], v[190:193], v[130:133], v[32:47]
	v_mfma_f32_32x32x16_bf16 v[48:63], v[174:177], v[126:129], v[48:63]
	v_mfma_f32_32x32x16_bf16 v[32:47], v[178:181], v[126:129], v[32:47]
	s_nop 10
	v_max_f32_e32 v174, v48, v48
	v_max_f32_e32 v175, v32, v32
	v_max_f32_e32 v174, v174, v175
	v_max3_f32 v174, v174, v49, v33
	v_max3_f32 v174, v174, v50, v34
	v_max3_f32 v174, v174, v51, v35
	v_max3_f32 v174, v174, v52, v36
	v_max3_f32 v174, v174, v53, v37
	v_max3_f32 v174, v174, v54, v38
	v_max3_f32 v174, v174, v55, v39
	v_max3_f32 v174, v174, v56, v40
	v_max3_f32 v174, v174, v57, v41
	v_max3_f32 v174, v174, v58, v42
	v_max3_f32 v174, v174, v59, v43
	v_max3_f32 v174, v174, v60, v44
	v_max3_f32 v174, v174, v61, v45
	v_max3_f32 v174, v174, v62, v46
	v_max3_f32 v174, v174, v63, v47
	v_fmamk_f32 v174, v174, 0x3e38aa3b, v64
	ds_bpermute_b32 v175, v235, v174
	s_waitcnt lgkmcnt(0)
	v_max3_f32 v213, v238, v174, v175
	v_cmp_gt_f32_e32 vcc, v213, v238
	s_cbranch_vccz .LBB0_256
	v_sub_f32_e32 v174, v238, v213
	v_exp_f32_e32 v174, v174
	s_nop 0
	v_mul_f32_e32 v237, v237, v174
	v_mul_f32_e32 v30, v30, v174
	v_mul_f32_e32 v31, v31, v174
	v_mul_f32_e32 v28, v28, v174
	v_mul_f32_e32 v29, v29, v174
	v_mul_f32_e32 v26, v26, v174
	v_mul_f32_e32 v27, v27, v174
	v_mul_f32_e32 v24, v24, v174
	v_mul_f32_e32 v25, v25, v174
	v_mul_f32_e32 v22, v22, v174
	v_mul_f32_e32 v23, v23, v174
	v_mul_f32_e32 v20, v20, v174
	v_mul_f32_e32 v21, v21, v174
	v_mul_f32_e32 v18, v18, v174
	v_mul_f32_e32 v19, v19, v174
	v_mul_f32_e32 v16, v16, v174
	v_mul_f32_e32 v17, v17, v174
	v_mul_f32_e32 v14, v14, v174
	v_mul_f32_e32 v15, v15, v174
	v_mul_f32_e32 v12, v12, v174
	v_mul_f32_e32 v13, v13, v174
	v_mul_f32_e32 v10, v10, v174
	v_mul_f32_e32 v11, v11, v174
	v_mul_f32_e32 v8, v8, v174
	v_mul_f32_e32 v9, v9, v174
	v_mul_f32_e32 v6, v6, v174
	v_mul_f32_e32 v7, v7, v174
	v_mul_f32_e32 v4, v4, v174
	v_mul_f32_e32 v5, v5, v174
	v_mul_f32_e32 v2, v2, v174
	v_mul_f32_e32 v3, v3, v174
	v_mul_f32_e32 v0, v0, v174
	v_mul_f32_e32 v1, v1, v174
; __device__ __forceinline__ unsigned pk2(float lo, float hi) { return pg8::cvt_pk_bf16(lo, hi); }
; #define SB_() __builtin_amdgcn_sched_barrier(0)
; __device__ __forceinline__ void tile_qk_fast(const KFr& f, const bf16x8 (&qf)[4], const bf16x8& kx0, const bf16x8& kx1, const bf16x8& qx, u32x4 (&pw)[4],
;                                              f32x16& o0, f32x16& o1, float& m, float& l, float off) {
;     ...
;     const float sh = off - mn;
;     float rs = 0.f;
; #pragma unroll
;     for (int r = 0; r < 16; ++r) { p0[r] = __builtin_amdgcn_exp2f(fmaf(p0[r], C2, sh)); p1[r] = __builtin_amdgcn_exp2f(fmaf(p1[r], C2, sh)); rs += p0[r] + p1[r]; }
;     l += rs;
;     pw[0] = (u32x4){pk2(p0[0], p0[1]), pk2(p0[2], p0[3]), pk2(p0[4], p0[5]), pk2(p0[6], p0[7])};
;     pw[1] = (u32x4){pk2(p0[8], p0[9]), pk2(p0[10], p0[11]), pk2(p0[12], p0[13]), pk2(p0[14], p0[15])};
;     pw[2] = (u32x4){pk2(p1[0], p1[1]), pk2(p1[2], p1[3]), pk2(p1[4], p1[5]), pk2(p1[6], p1[7])};
;     pw[3] = (u32x4){pk2(p1[8], p1[9]), pk2(p1[10], p1[11]), pk2(p1[12], p1[13]), pk2(p1[14], p1[15])};
; }
; __device__ __forceinline__ void tile_pv(const VFr& f, const u32x4 (&pw)[4], f32x16& o0, f32x16& o1) {
; #pragma unroll
;     for (int ks = 0; ks < 4; ++ks) {
;         const bf16x8 P = __builtin_bit_cast(bf16x8, pw[ks]);
;         o0 = __builtin_amdgcn_mfma_f32_32x32x16_bf16(f.a[0][ks], P, o0, 0, 0, 0);
;         o1 = __builtin_amdgcn_mfma_f32_32x32x16_bf16(f.a[1][ks], P, o1, 0, 0, 0);
; __device__ __forceinline__ void moba_unit(int b, int h, int qb, const bf16* qkv, const bf16* KF, const bf16* VF, bf16* Y, const float* kmean, LAS unsigned char* lds) {
;     ...
;             loadV(v0, vp); loadK(k0, kp); SB_(); tile_qk_fast(k1, qg, kx0, kx1, qx, pw, a0, a1, m2, l2, sl2 * (float)(kq0 + 64)); SB_();
;             tile_pv(v0, pw, a0, a1); SB_();
;             loadV(v0, vp); loadK(k1, kp); SB_(); tile_qk_fast(k0, qg, kx0, kx1, qx, pw, a0, a1, m2, l2, sl2 * (float)(kq0 + 128)); SB_();
.LBB0_256:
	v_sub_f32_e32 v176, v64, v213
	v_fmamk_f32 v32, v32, 0x3e38aa3b, v176
	v_fmamk_f32 v48, v48, 0x3e38aa3b, v176
	v_exp_f32_e32 v178, v32
	v_fmamk_f32 v32, v49, 0x3e38aa3b, v176
	v_exp_f32_e32 v177, v48
	v_exp_f32_e32 v64, v32
	v_fmamk_f32 v32, v33, 0x3e38aa3b, v176
	v_exp_f32_e32 v48, v32
	v_add_f32_e32 v49, v178, v177
	v_add_f32_e32 v32, v48, v64
	v_add_f32_e32 v33, v49, v65
	s_nop 0
	v_add_f32_e32 v174, v32, v32
	v_add_f32_e32 v175, v32, v33
	v_fmamk_f32 v32, v50, 0x3e38aa3b, v176
	v_exp_f32_e32 v49, v32
	v_fmamk_f32 v32, v34, 0x3e38aa3b, v176
	v_exp_f32_e32 v179, v32
	v_fmamk_f32 v32, v51, 0x3e38aa3b, v176
	v_exp_f32_e32 v174, v32
	v_fmamk_f32 v32, v35, 0x3e38aa3b, v176
	v_exp_f32_e32 v50, v32
	v_add_f32_e32 v51, v179, v49
	v_add_f32_e32 v32, v50, v174
	v_add_f32_e32 v33, v51, v175
	s_nop 0
	v_add_f32_e32 v34, v32, v32
	v_add_f32_e32 v35, v32, v33
	v_fmamk_f32 v32, v52, 0x3e38aa3b, v176
	v_exp_f32_e32 v51, v32
	v_fmamk_f32 v32, v36, 0x3e38aa3b, v176
	v_exp_f32_e32 v175, v32
	v_fmamk_f32 v32, v53, 0x3e38aa3b, v176
	v_exp_f32_e32 v34, v32
	v_fmamk_f32 v32, v37, 0x3e38aa3b, v176
	v_exp_f32_e32 v52, v32
	v_add_f32_e32 v53, v175, v51
	v_add_f32_e32 v32, v52, v34
	v_add_f32_e32 v33, v53, v35
	s_nop 0
	v_add_f32_e32 v36, v32, v32
	v_add_f32_e32 v37, v32, v33
	v_fmamk_f32 v32, v54, 0x3e38aa3b, v176
	v_exp_f32_e32 v35, v32
	v_fmamk_f32 v32, v38, 0x3e38aa3b, v176
	v_exp_f32_e32 v53, v32
	v_fmamk_f32 v32, v55, 0x3e38aa3b, v176
	v_exp_f32_e32 v36, v32
	v_fmamk_f32 v32, v39, 0x3e38aa3b, v176
	v_exp_f32_e32 v54, v32
	v_add_f32_e32 v55, v53, v35
	v_cvt_pk_bf16_f32 v34, v51, v34
	v_cvt_pk_bf16_f32 v35, v35, v36
	v_add_f32_e32 v32, v54, v36
	v_add_f32_e32 v33, v55, v37
	s_nop 0
	v_add_f32_e32 v38, v32, v32
	v_add_f32_e32 v39, v32, v33
	v_fmamk_f32 v32, v56, 0x3e38aa3b, v176
	v_exp_f32_e32 v37, v32
	v_fmamk_f32 v32, v40, 0x3e38aa3b, v176
	v_exp_f32_e32 v55, v32
	v_fmamk_f32 v32, v57, 0x3e38aa3b, v176
	v_exp_f32_e32 v38, v32
	v_fmamk_f32 v32, v41, 0x3e38aa3b, v176
	v_exp_f32_e32 v56, v32
	v_add_f32_e32 v57, v55, v37
	v_cvt_pk_bf16_f32 v36, v37, v38
	v_add_f32_e32 v32, v56, v38
	v_add_f32_e32 v33, v57, v39
	s_nop 0
	v_add_f32_e32 v40, v32, v32
	v_add_f32_e32 v41, v32, v33
	v_fmamk_f32 v32, v58, 0x3e38aa3b, v176
	v_exp_f32_e32 v39, v32
	v_fmamk_f32 v32, v42, 0x3e38aa3b, v176
	v_exp_f32_e32 v57, v32
	v_fmamk_f32 v32, v59, 0x3e38aa3b, v176
	v_exp_f32_e32 v40, v32
	v_fmamk_f32 v32, v43, 0x3e38aa3b, v176
	v_exp_f32_e32 v58, v32
	v_add_f32_e32 v59, v57, v39
	v_cvt_pk_bf16_f32 v37, v39, v40
	v_add_f32_e32 v32, v58, v40
	v_add_f32_e32 v33, v59, v41
	s_nop 0
	v_add_f32_e32 v42, v32, v32
	v_add_f32_e32 v43, v32, v33
	v_fmamk_f32 v32, v60, 0x3e38aa3b, v176
	v_exp_f32_e32 v41, v32
	v_fmamk_f32 v32, v44, 0x3e38aa3b, v176
	v_exp_f32_e32 v59, v32
	v_fmamk_f32 v32, v61, 0x3e38aa3b, v176
	v_exp_f32_e32 v42, v32
	v_fmamk_f32 v32, v45, 0x3e38aa3b, v176
	v_exp_f32_e32 v60, v32
	v_add_f32_e32 v61, v59, v41
	v_cvt_pk_bf16_f32 v38, v41, v42
	v_cvt_pk_bf16_f32 v40, v178, v48
	v_add_f32_e32 v32, v60, v42
	v_add_f32_e32 v33, v61, v43
	v_cvt_pk_bf16_f32 v41, v179, v50
	v_add_f32_e32 v44, v32, v32
	v_add_f32_e32 v45, v32, v33
	v_fmamk_f32 v32, v62, 0x3e38aa3b, v176
	v_exp_f32_e32 v43, v32
	v_fmamk_f32 v32, v46, 0x3e38aa3b, v176
	v_exp_f32_e32 v61, v32
	v_fmamk_f32 v32, v63, 0x3e38aa3b, v176
	v_fmac_f32_e32 v176, 0x3e38aa3b, v47
	v_exp_f32_e32 v44, v32
	v_exp_f32_e32 v62, v176
	v_add_f32_e32 v63, v61, v43
	v_cvt_pk_bf16_f32 v42, v175, v52
	v_cvt_pk_bf16_f32 v39, v43, v44
	v_add_f32_e32 v32, v62, v44
	v_add_f32_e32 v33, v63, v45
	v_cvt_pk_bf16_f32 v43, v53, v54
	v_add_f32_e32 v32, v32, v33
	v_add_f32_e32 v237, v32, v237
	v_cvt_pk_bf16_f32 v32, v177, v64
	v_cvt_pk_bf16_f32 v33, v49, v174
	v_cvt_pk_bf16_f32 v44, v55, v56
	v_cvt_pk_bf16_f32 v45, v57, v58
	v_cvt_pk_bf16_f32 v46, v59, v60
	v_cvt_pk_bf16_f32 v47, v61, v62
	s_waitcnt vmcnt(0)
	v_mfma_f32_32x32x16_bf16 v[16:31], v[162:165], v[32:35], v[16:31]
	v_mfma_f32_32x32x16_bf16 v[0:15], v[170:173], v[32:35], v[0:15]
	v_mfma_f32_32x32x16_bf16 v[16:31], v[154:157], v[36:39], v[16:31]
	v_mfma_f32_32x32x16_bf16 v[0:15], v[166:169], v[36:39], v[0:15]
	v_mfma_f32_32x32x16_bf16 v[16:31], v[146:149], v[40:43], v[16:31]
	v_mfma_f32_32x32x16_bf16 v[0:15], v[158:161], v[40:43], v[0:15]
	v_mfma_f32_32x32x16_bf16 v[16:31], v[142:145], v[44:47], v[16:31]
	v_mfma_f32_32x32x16_bf16 v[0:15], v[150:153], v[44:47], v[0:15]
	v_lshl_add_u64 v[32:33], v[214:215], 0, s[56:57]
	global_load_dwordx4 v[162:165], v[214:215], off
	global_load_dwordx4 v[154:157], v[214:215], off offset:1024
	global_load_dwordx4 v[146:149], v[214:215], off offset:2048
	global_load_dwordx4 v[142:145], v[214:215], off offset:3072
	global_load_dwordx4 v[174:177], v[32:33], off
	global_load_dwordx4 v[166:169], v[32:33], off offset:1024
	global_load_dwordx4 v[158:161], v[32:33], off offset:2048
	global_load_dwordx4 v[150:153], v[32:33], off offset:3072
	v_lshl_add_u64 v[218:219], v[32:33], 0, s[56:57]
	v_lshl_add_u64 v[32:33], v[216:217], 0, s[56:57]
	global_load_dwordx4 v[194:197], v[216:217], off
	global_load_dwordx4 v[186:189], v[216:217], off offset:1024
	global_load_dwordx4 v[178:181], v[216:217], off offset:2048
	global_load_dwordx4 v[170:173], v[216:217], off offset:3072
	global_load_dwordx4 v[202:205], v[32:33], off
	global_load_dwordx4 v[198:201], v[32:33], off offset:1024
	global_load_dwordx4 v[190:193], v[32:33], off offset:2048
	global_load_dwordx4 v[182:185], v[32:33], off offset:3072
	v_lshl_add_u64 v[214:215], v[32:33], 0, s[56:57]
	v_mfma_f32_32x32x16_bf16 v[48:63], v[70:73], v[66:69], 0
	v_add_u32_e32 v64, 0x80, v236
	v_cvt_f32_i32_e32 v64, v64
	v_mul_f32_e32 v216, v230, v64
	v_mfma_f32_32x32x16_bf16 v[32:47], v[74:77], v[66:69], 0
	v_mfma_f32_32x32x16_bf16 v[48:63], v[106:109], v[138:141], v[48:63]
	v_mfma_f32_32x32x16_bf16 v[32:47], v[122:125], v[138:141], v[32:47]
	v_mfma_f32_32x32x16_bf16 v[48:63], v[102:105], v[134:137], v[48:63]
	v_mfma_f32_32x32x16_bf16 v[32:47], v[118:121], v[134:137], v[32:47]
	v_mfma_f32_32x32x16_bf16 v[48:63], v[98:101], v[130:133], v[48:63]
	v_mfma_f32_32x32x16_bf16 v[32:47], v[114:117], v[130:133], v[32:47]
	v_mfma_f32_32x32x16_bf16 v[32:47], v[110:113], v[126:129], v[32:47]
	v_mfma_f32_32x32x16_bf16 v[48:63], v[94:97], v[126:129], v[48:63]
	s_nop 10
	v_max_f32_e32 v64, v32, v32
	v_max_f32_e32 v217, v48, v48
	v_max_f32_e32 v64, v217, v64
	v_max3_f32 v64, v64, v49, v33
	v_max3_f32 v64, v64, v50, v34
	v_max3_f32 v64, v64, v51, v35
	v_max3_f32 v64, v64, v52, v36
	v_max3_f32 v64, v64, v53, v37
	v_max3_f32 v64, v64, v54, v38
	v_max3_f32 v64, v64, v55, v39
	v_max3_f32 v64, v64, v56, v40
	v_max3_f32 v64, v64, v57, v41
	v_max3_f32 v64, v64, v58, v42
	v_max3_f32 v64, v64, v59, v43
	v_max3_f32 v64, v64, v60, v44
	v_max3_f32 v64, v64, v61, v45
	v_max3_f32 v64, v64, v62, v46
	v_max3_f32 v64, v64, v63, v47
	v_fmamk_f32 v64, v64, 0x3e38aa3b, v216
	ds_bpermute_b32 v217, v235, v64
	s_waitcnt lgkmcnt(0)
	v_max3_f32 v64, v213, v64, v217
	v_cmp_gt_f32_e32 vcc, v64, v213
	s_cbranch_vccz .LBB0_258
; __device__ __forceinline__ void tile_qk_fast(const KFr& f, const bf16x8 (&qf)[4], const bf16x8& kx0, const bf16x8& kx1, const bf16x8& qx, u32x4 (&pw)[4],
;                                              f32x16& o0, f32x16& o1, float& m, float& l, float off) {
;     ...
;     if (__ballot(mn > m) != 0ull) {
;         const float alpha = __builtin_amdgcn_exp2f(m - mn); l *= alpha;
; #pragma unroll
;         for (int r = 0; r < 16; ++r) { o0[r] *= alpha; o1[r] *= alpha; }
;     }
	v_sub_f32_e32 v213, v213, v64
	v_exp_f32_e32 v222, v213
	s_nop 0
	v_mul_f32_e32 v237, v237, v222
	v_mul_f32_e32 v30, v30, v222
	v_mul_f32_e32 v31, v31, v222
	v_mul_f32_e32 v28, v28, v222
	v_mul_f32_e32 v29, v29, v222
	v_mul_f32_e32 v26, v26, v222
	v_mul_f32_e32 v27, v27, v222
	v_mul_f32_e32 v24, v24, v222
	v_mul_f32_e32 v25, v25, v222
	v_mul_f32_e32 v22, v22, v222
	v_mul_f32_e32 v23, v23, v222
	v_mul_f32_e32 v20, v20, v222
	v_mul_f32_e32 v21, v21, v222
	v_mul_f32_e32 v18, v18, v222
	v_mul_f32_e32 v19, v19, v222
	v_mul_f32_e32 v16, v16, v222
	v_mul_f32_e32 v17, v17, v222
	v_mul_f32_e32 v14, v14, v222
	v_mul_f32_e32 v15, v15, v222
	v_mul_f32_e32 v12, v12, v222
	v_mul_f32_e32 v13, v13, v222
	v_mul_f32_e32 v10, v10, v222
	v_mul_f32_e32 v11, v11, v222
	v_mul_f32_e32 v8, v8, v222
	v_mul_f32_e32 v9, v9, v222
	v_mul_f32_e32 v6, v6, v222
	v_mul_f32_e32 v7, v7, v222
	v_mul_f32_e32 v4, v4, v222
	v_mul_f32_e32 v5, v5, v222
	v_mul_f32_e32 v2, v2, v222
	v_mul_f32_e32 v3, v3, v222
	v_mul_f32_e32 v0, v0, v222
	v_mul_f32_e32 v1, v1, v222

; #define TASK_Q(Q2, VALID, QG) do { const int idx_ = ch * 32 + r32; VALID = idx_ < c; Q2 = (int)LIST[n * 256 + (VALID ? idx_ : ch * 32)]; \
;                         const bf16* qp_ = qkv + ((size_t)b * SEQ + 256 * qb + Q2) * PA + C_CQ + h * 64 + hi * 8; \
;                         _Pragma("unroll") for (int d0 = 0; d0 < 4; ++d0) QG[d0] = *(const bf16x8*)(qp_ + 16 * d0); } while (0)
; #define SB_() __builtin_amdgcn_sched_barrier(0)
; __device__ __forceinline__ void tile_qk_fast(const KFr& f, const bf16x8 (&qf)[4], const bf16x8& kx0, const bf16x8& kx1, const bf16x8& qx, u32x4 (&pw)[4],
;                                              f32x16& o0, f32x16& o1, float& m, float& l, float off) {
;     ...
;     float mr = fmaxf(p0[0], p1[0]);
; #pragma unroll
;     for (int r = 1; r < 16; ++r) mr = fmaxf(fmaxf(mr, p0[r]), p1[r]);
;     float mx = fmaf(mr, C2, off);
;     mx = fmaxf(mx, __shfl_xor(mx, 32));
;     const float mn = fmaxf(m, mx);
;     if (__ballot(mn > m) != 0ull) {
;         const float alpha = __builtin_amdgcn_exp2f(m - mn); l *= alpha;
; #pragma unroll
;         for (int r = 0; r < 16; ++r) { o0[r] *= alpha; o1[r] *= alpha; }
;     }
;     m = mn;
;     const float sh = off - mn;
;     float rs = 0.f;
; #pragma unroll
;     for (int r = 0; r < 16; ++r) { p0[r] = __builtin_amdgcn_exp2f(fmaf(p0[r], C2, sh)); p1[r] = __builtin_amdgcn_exp2f(fmaf(p1[r], C2, sh)); rs += p0[r] + p1[r]; }
;     l += rs;
; __device__ __forceinline__ void moba_unit(int b, int h, int qb, const bf16* qkv, const bf16* KF, const bf16* VF, bf16* Y, const float* kmean, LAS unsigned char* lds) {
;     ...
;             loadV(v0, vp);
;             if (have) { TASK_Q(q2n, validn, qn); kp = (const char*)KFh + (size_t)(4 * n) * 8192 + lane * 16; asm volatile("" : "+v"(kp)); loadK(k0, kp); }
;             SB_(); tile_qk_fast(k1, qg, kx0, kx1, qx, pw, a0, a1, m2, l2, sl2 * (float)(kq0 + 192)); SB_();
.LBB0_261:
	v_add_f32_e32 v32, v32, v48
	v_add_f32_e32 v32, 0, v32
	v_add_f32_e32 v33, v33, v49
	v_add_f32_e32 v32, v33, v32
	v_add_f32_e32 v33, v34, v50
	v_add_f32_e32 v32, v33, v32
	v_add_f32_e32 v33, v35, v51
	v_add_f32_e32 v32, v33, v32
	v_add_f32_e32 v33, v36, v52
	v_add_f32_e32 v32, v33, v32
	v_add_f32_e32 v33, v37, v53
	v_add_f32_e32 v32, v33, v32
	v_add_f32_e32 v33, v38, v54
	v_add_f32_e32 v32, v33, v32
	v_add_f32_e32 v33, v39, v55
	v_add_f32_e32 v32, v33, v32
	v_add_f32_e32 v33, v40, v56
	v_add_f32_e32 v32, v33, v32
	v_add_f32_e32 v33, v41, v57
	v_add_f32_e32 v32, v33, v32
	v_add_f32_e32 v33, v42, v58
	v_add_f32_e32 v32, v33, v32
	v_add_f32_e32 v33, v43, v59
	v_add_f32_e32 v32, v33, v32
	v_add_f32_e32 v33, v44, v60
	v_add_f32_e32 v32, v33, v32
	v_add_f32_e32 v33, v45, v61
	v_add_f32_e32 v32, v33, v32
	v_add_f32_e32 v33, v46, v62
	v_add_f32_e32 v32, v33, v32
	v_add_f32_e32 v33, v47, v63
	v_add_f32_e32 v32, v33, v32
	v_add_f32_e32 v213, v32, v237
	v_mfma_f32_32x32x16_bf16 v[48:63], v[70:73], v[66:69], 0
	v_mfma_f32_32x32x16_bf16 v[32:47], v[74:77], v[66:69], 0
	v_mfma_f32_32x32x16_bf16 v[48:63], v[194:197], v[138:141], v[48:63]
	v_mfma_f32_32x32x16_bf16 v[32:47], v[202:205], v[138:141], v[32:47]
	v_mfma_f32_32x32x16_bf16 v[48:63], v[186:189], v[134:137], v[48:63]
	v_mfma_f32_32x32x16_bf16 v[32:47], v[198:201], v[134:137], v[32:47]
	v_mfma_f32_32x32x16_bf16 v[48:63], v[178:181], v[130:133], v[48:63]
	v_mfma_f32_32x32x16_bf16 v[32:47], v[190:193], v[130:133], v[32:47]
	v_add_u32_e32 v130, 0xc0, v236
	v_cvt_f32_i32_e32 v130, v130
	v_mul_f32_e32 v130, v230, v130
	v_mfma_f32_32x32x16_bf16 v[32:47], v[182:185], v[126:129], v[32:47]
	v_mfma_f32_32x32x16_bf16 v[48:63], v[170:173], v[126:129], v[48:63]
	s_nop 10
	v_max_f32_e32 v131, v32, v32
	v_max_f32_e32 v126, v48, v48
	v_max_f32_e32 v126, v126, v131
	v_max3_f32 v126, v126, v49, v33
	v_max3_f32 v126, v126, v50, v34
	v_max3_f32 v126, v126, v51, v35
	v_max3_f32 v126, v126, v52, v36
	v_max3_f32 v126, v126, v53, v37
	v_max3_f32 v126, v126, v54, v38
	v_max3_f32 v126, v126, v55, v39
	v_max3_f32 v126, v126, v56, v40
	v_max3_f32 v126, v126, v57, v41
	v_max3_f32 v126, v126, v58, v42
	v_max3_f32 v126, v126, v59, v43
	v_max3_f32 v126, v126, v60, v44
	v_max3_f32 v126, v126, v61, v45
	v_max3_f32 v126, v126, v62, v46
	v_max3_f32 v126, v126, v63, v47
	v_fmamk_f32 v126, v126, 0x3e38aa3b, v130
	ds_bpermute_b32 v127, v235, v126
	s_waitcnt lgkmcnt(0)
	v_max3_f32 v126, v64, v126, v127
	v_cmp_gt_f32_e32 vcc, v126, v64
	s_cbranch_vccz .LBB0_263
	v_sub_f32_e32 v64, v64, v126
	v_exp_f32_e32 v64, v64
	s_nop 0
	v_mul_f32_e32 v213, v213, v64
	v_mul_f32_e32 v30, v30, v64
	v_mul_f32_e32 v31, v31, v64
	v_mul_f32_e32 v28, v28, v64
	v_mul_f32_e32 v29, v29, v64
	v_mul_f32_e32 v26, v26, v64
	v_mul_f32_e32 v27, v27, v64
	v_mul_f32_e32 v24, v24, v64
	v_mul_f32_e32 v25, v25, v64
	v_mul_f32_e32 v22, v22, v64
	v_mul_f32_e32 v23, v23, v64
	v_mul_f32_e32 v20, v20, v64
	v_mul_f32_e32 v21, v21, v64
	v_mul_f32_e32 v18, v18, v64
	v_mul_f32_e32 v19, v19, v64
	v_mul_f32_e32 v16, v16, v64
	v_mul_f32_e32 v17, v17, v64
	v_mul_f32_e32 v14, v14, v64
	v_mul_f32_e32 v15, v15, v64
	v_mul_f32_e32 v12, v12, v64
	v_mul_f32_e32 v13, v13, v64
	v_mul_f32_e32 v10, v10, v64
	v_mul_f32_e32 v11, v11, v64
	v_mul_f32_e32 v8, v8, v64
	v_mul_f32_e32 v9, v9, v64
	v_mul_f32_e32 v6, v6, v64
	v_mul_f32_e32 v7, v7, v64
	v_mul_f32_e32 v4, v4, v64
	v_mul_f32_e32 v5, v5, v64
	v_mul_f32_e32 v2, v2, v64
	v_mul_f32_e32 v3, v3, v64
	v_mul_f32_e32 v0, v0, v64
	v_mul_f32_e32 v1, v1, v64
.LBB0_263:
	v_sub_f32_e32 v64, v130, v126
	v_fmamk_f32 v32, v32, 0x3e38aa3b, v64
	v_fmamk_f32 v48, v48, 0x3e38aa3b, v64
	v_exp_f32_e32 v127, v32
	v_fmamk_f32 v32, v49, 0x3e38aa3b, v64
	v_exp_f32_e32 v48, v48
	v_exp_f32_e32 v49, v32
	v_fmamk_f32 v32, v33, 0x3e38aa3b, v64
	v_exp_f32_e32 v33, v32
	v_fmamk_f32 v34, v34, 0x3e38aa3b, v64
	v_exp_f32_e32 v129, v34
	v_fmamk_f32 v34, v51, 0x3e38aa3b, v64
	v_add_f32_e32 v32, v127, v48
	v_exp_f32_e32 v51, v34
	v_fmamk_f32 v34, v35, 0x3e38aa3b, v64
	v_fmamk_f32 v35, v52, 0x3e38aa3b, v64
	v_add_f32_e32 v32, 0, v32
	v_add_f32_e32 v128, v33, v49
	v_exp_f32_e32 v52, v35
	v_fmamk_f32 v35, v36, 0x3e38aa3b, v64
	v_add_f32_e32 v32, v128, v32
	v_exp_f32_e32 v128, v35
	v_fmamk_f32 v35, v53, 0x3e38aa3b, v64
	v_exp_f32_e32 v36, v35
	v_fmamk_f32 v35, v37, 0x3e38aa3b, v64
	v_exp_f32_e32 v53, v35
	v_fmamk_f32 v35, v54, 0x3e38aa3b, v64
	v_exp_f32_e32 v37, v35
	v_fmamk_f32 v35, v38, 0x3e38aa3b, v64
	v_exp_f32_e32 v54, v35
	v_fmamk_f32 v35, v55, 0x3e38aa3b, v64
	v_exp_f32_e32 v38, v35
	v_fmamk_f32 v35, v39, 0x3e38aa3b, v64
	v_exp_f32_e32 v55, v35
	v_fmamk_f32 v35, v56, 0x3e38aa3b, v64
	v_fmamk_f32 v50, v50, 0x3e38aa3b, v64
	v_exp_f32_e32 v39, v35
	v_fmamk_f32 v35, v40, 0x3e38aa3b, v64
	v_exp_f32_e32 v50, v50
	v_exp_f32_e32 v56, v35
	v_fmamk_f32 v35, v57, 0x3e38aa3b, v64
	v_exp_f32_e32 v130, v34
	v_exp_f32_e32 v40, v35
	v_fmamk_f32 v35, v41, 0x3e38aa3b, v64
	v_exp_f32_e32 v57, v35
	v_fmamk_f32 v35, v58, 0x3e38aa3b, v64
	v_exp_f32_e32 v41, v35
	v_fmamk_f32 v35, v42, 0x3e38aa3b, v64
	v_add_f32_e32 v34, v129, v50
	v_exp_f32_e32 v58, v35
	v_fmamk_f32 v35, v59, 0x3e38aa3b, v64
	v_add_f32_e32 v32, v34, v32
	v_add_f32_e32 v34, v130, v51
	v_exp_f32_e32 v42, v35
	v_fmamk_f32 v35, v43, 0x3e38aa3b, v64
	v_add_f32_e32 v32, v34, v32
	v_add_f32_e32 v34, v128, v52
	v_exp_f32_e32 v59, v35
	v_fmamk_f32 v35, v60, 0x3e38aa3b, v64
	v_add_f32_e32 v32, v34, v32
	v_add_f32_e32 v34, v53, v36
	v_exp_f32_e32 v43, v35
	v_fmamk_f32 v35, v44, 0x3e38aa3b, v64
	v_add_f32_e32 v32, v34, v32
	v_add_f32_e32 v34, v54, v37
	v_exp_f32_e32 v60, v35
	v_fmamk_f32 v35, v61, 0x3e38aa3b, v64
	v_add_f32_e32 v32, v34, v32
; #define LAS __attribute__((address_space(3)))
; __device__ __forceinline__ unsigned pk2(float lo, float hi) { return pg8::cvt_pk_bf16(lo, hi); }
; __device__ __forceinline__ void tile_qk_fast(const KFr& f, const bf16x8 (&qf)[4], const bf16x8& kx0, const bf16x8& kx1, const bf16x8& qx, u32x4 (&pw)[4],
;                                              f32x16& o0, f32x16& o1, float& m, float& l, float off) {
;     ...
;     const float sh = off - mn;
;     float rs = 0.f;
; #pragma unroll
;     for (int r = 0; r < 16; ++r) { p0[r] = __builtin_amdgcn_exp2f(fmaf(p0[r], C2, sh)); p1[r] = __builtin_amdgcn_exp2f(fmaf(p1[r], C2, sh)); rs += p0[r] + p1[r]; }
;     l += rs;
;     pw[0] = (u32x4){pk2(p0[0], p0[1]), pk2(p0[2], p0[3]), pk2(p0[4], p0[5]), pk2(p0[6], p0[7])};
;     pw[1] = (u32x4){pk2(p0[8], p0[9]), pk2(p0[10], p0[11]), pk2(p0[12], p0[13]), pk2(p0[14], p0[15])};
;     pw[2] = (u32x4){pk2(p1[0], p1[1]), pk2(p1[2], p1[3]), pk2(p1[4], p1[5]), pk2(p1[6], p1[7])};
;     pw[3] = (u32x4){pk2(p1[8], p1[9]), pk2(p1[10], p1[11]), pk2(p1[12], p1[13]), pk2(p1[14], p1[15])};
; __device__ __forceinline__ void moba_unit(int b, int h, int qb, const bf16* qkv, const bf16* KF, const bf16* VF, bf16* Y, const float* kmean, LAS unsigned char* lds) {
;     ...
;             tile_pv(v0, pw, a0, a1);
;             const float l2t = l2 + __shfl_xor(l2, 32), inv = 1.f / l2t;
;             if (valid_c) {
;                 const unsigned sm = SEL[q2_c]; const int slot = __builtin_popcount(sm & ((1u << n_c) - 1u));
;                 LAS unsigned char* op = lds + MB_OP + (slot * 256 + q2_c) * MB_OPROW + 8 * hi;
; #pragma unroll
;                 for (int rg = 0; rg < 4; ++rg) {
;                     *(LAS u32x2*)(op + 16 * rg) = (u32x2){pk2(a0[4 * rg] * inv, a0[4 * rg + 1] * inv), pk2(a0[4 * rg + 2] * inv, a0[4 * rg + 3] * inv)};
;                     *(LAS u32x2*)(op + 64 + 16 * rg) = (u32x2){pk2(a1[4 * rg] * inv, a1[4 * rg + 1] * inv), pk2(a1[4 * rg + 2] * inv, a1[4 * rg + 3] * inv)}; }
;                 if (hi == 0) *(LAS f32x2v*)(lds + MB_ML + (slot * 256 + q2_c) * 8) = (f32x2v){m2, l2t};
;             }
	v_add_f32_e32 v34, v55, v38
	v_exp_f32_e32 v44, v35
	v_fmamk_f32 v35, v45, 0x3e38aa3b, v64
	v_add_f32_e32 v32, v34, v32
	v_add_f32_e32 v34, v56, v39
	v_exp_f32_e32 v61, v35
	v_fmamk_f32 v35, v62, 0x3e38aa3b, v64
	v_add_f32_e32 v32, v34, v32
	v_add_f32_e32 v34, v57, v40
	v_exp_f32_e32 v45, v35
	v_fmamk_f32 v35, v46, 0x3e38aa3b, v64
	v_add_f32_e32 v32, v34, v32
	v_add_f32_e32 v34, v58, v41
	v_exp_f32_e32 v62, v35
	v_fmamk_f32 v35, v63, 0x3e38aa3b, v64
	v_fmac_f32_e32 v64, 0x3e38aa3b, v47
	v_add_f32_e32 v32, v34, v32
	v_add_f32_e32 v34, v59, v42
	v_exp_f32_e32 v46, v35
	v_exp_f32_e32 v63, v64
	v_add_f32_e32 v32, v34, v32
	v_add_f32_e32 v34, v60, v43
	v_add_f32_e32 v32, v34, v32
	v_add_f32_e32 v34, v61, v44
	v_add_f32_e32 v32, v34, v32
	v_add_f32_e32 v34, v62, v45
	v_add_f32_e32 v32, v34, v32
	v_add_f32_e32 v34, v63, v46
	v_add_f32_e32 v32, v34, v32
	v_add_f32_e32 v32, v32, v213
	v_cvt_pk_bf16_f32 v34, v48, v49
	v_cvt_pk_bf16_f32 v35, v50, v51
	v_cvt_pk_bf16_f32 v36, v52, v36
	v_cvt_pk_bf16_f32 v37, v37, v38
	v_cvt_pk_bf16_f32 v38, v39, v40
	v_cvt_pk_bf16_f32 v39, v41, v42
	v_cvt_pk_bf16_f32 v40, v43, v44
	v_cvt_pk_bf16_f32 v41, v45, v46
	v_cvt_pk_bf16_f32 v42, v127, v33
	v_cvt_pk_bf16_f32 v43, v129, v130
	v_cvt_pk_bf16_f32 v44, v128, v53
	v_cvt_pk_bf16_f32 v45, v54, v55
	v_cvt_pk_bf16_f32 v46, v56, v57
	v_cvt_pk_bf16_f32 v47, v58, v59
	v_cvt_pk_bf16_f32 v48, v60, v61
	v_cvt_pk_bf16_f32 v49, v62, v63
	s_waitcnt vmcnt(0)
	v_mfma_f32_32x32x16_bf16 v[16:31], v[162:165], v[34:37], v[16:31]
	ds_bpermute_b32 v33, v235, v32
	v_mfma_f32_32x32x16_bf16 v[0:15], v[174:177], v[34:37], v[0:15]
	v_mfma_f32_32x32x16_bf16 v[16:31], v[154:157], v[38:41], v[16:31]
	v_mfma_f32_32x32x16_bf16 v[0:15], v[166:169], v[38:41], v[0:15]
	v_mfma_f32_32x32x16_bf16 v[16:31], v[146:149], v[42:45], v[16:31]
	v_mfma_f32_32x32x16_bf16 v[0:15], v[158:161], v[42:45], v[0:15]
	v_mfma_f32_32x32x16_bf16 v[16:31], v[142:145], v[46:49], v[16:31]
	v_mfma_f32_32x32x16_bf16 v[0:15], v[150:153], v[46:49], v[0:15]
	s_and_saveexec_b64 s[16:17], s[12:13]
	s_cbranch_execz .LBB0_234
	s_waitcnt lgkmcnt(0)
	v_add_f32_e32 v127, v32, v33
	v_div_scale_f32 v32, s[12:13], v127, v127, 1.0
	v_rcp_f32_e32 v33, v32
	s_movk_i32 s12, 0x88
	v_fma_f32 v34, -v32, v33, 1.0
	v_fmac_f32_e32 v33, v34, v33
	v_div_scale_f32 v34, vcc, 1.0, v127, 1.0
	v_mul_f32_e32 v35, v34, v33
	v_fma_f32 v36, -v32, v35, v34
	v_fmac_f32_e32 v35, v36, v33
	v_fma_f32 v32, -v32, v35, v34
	v_div_fmas_f32 v32, v32, v33, v35
	v_div_fixup_f32 v34, v32, v127, 1.0
	v_lshl_add_u32 v32, v234, 2, 0
	v_add_u32_e32 v32, 0x1d080, v32
	ds_read_b32 v32, v32
	v_mul_f32_e32 v16, v16, v34
	v_mul_f32_e32 v17, v17, v34
	v_mul_f32_e32 v18, v18, v34
	v_mul_f32_e32 v19, v19, v34
	v_mul_f32_e32 v0, v0, v34
	v_mul_f32_e32 v1, v1, v34
	v_mul_f32_e32 v2, v2, v34
	v_mul_f32_e32 v3, v3, v34
	s_waitcnt lgkmcnt(0)
	v_bfe_u32 v32, v32, 0, s26
	v_bcnt_u32_b32 v32, v32, 0
	v_lshl_add_u32 v32, v32, 8, v234
	v_cvt_pk_bf16_f32 v16, v16, v17
	v_cvt_pk_bf16_f32 v17, v18, v19
	v_cvt_pk_bf16_f32 v0, v0, v1
	v_cvt_pk_bf16_f32 v1, v2, v3
	v_mul_f32_e32 v2, v20, v34
	v_mul_f32_e32 v3, v21, v34
	v_mul_f32_e32 v18, v22, v34
	v_mul_f32_e32 v19, v23, v34
	v_mad_i32_i24 v33, v32, s12, v233
	v_cvt_pk_bf16_f32 v2, v2, v3
	v_cvt_pk_bf16_f32 v3, v18, v19
	ds_write2_b64 v33, v[16:17], v[2:3] offset1:2
	v_mul_f32_e32 v2, v4, v34
	v_mul_f32_e32 v3, v5, v34
	v_mul_f32_e32 v4, v6, v34
	v_mul_f32_e32 v5, v7, v34
	v_cvt_pk_bf16_f32 v2, v2, v3
	v_cvt_pk_bf16_f32 v3, v4, v5
	ds_write2_b64 v33, v[0:1], v[2:3] offset0:8 offset1:10
	v_mul_f32_e32 v0, v24, v34
	v_mul_f32_e32 v1, v25, v34
	v_mul_f32_e32 v2, v26, v34
	v_mul_f32_e32 v3, v27, v34
	v_cvt_pk_bf16_f32 v0, v0, v1
	v_cvt_pk_bf16_f32 v1, v2, v3
	v_mul_f32_e32 v2, v8, v34
	v_mul_f32_e32 v3, v9, v34
	v_mul_f32_e32 v4, v10, v34
	v_mul_f32_e32 v5, v11, v34
	v_cvt_pk_bf16_f32 v2, v2, v3
	v_cvt_pk_bf16_f32 v3, v4, v5
	v_mul_f32_e32 v4, v28, v34
	v_mul_f32_e32 v5, v29, v34
	v_mul_f32_e32 v6, v30, v34
	v_mul_f32_e32 v7, v31, v34
	v_cvt_pk_bf16_f32 v4, v4, v5
	v_cvt_pk_bf16_f32 v5, v6, v7
	ds_write2_b64 v33, v[0:1], v[4:5] offset0:4 offset1:6
	v_mul_f32_e32 v0, v12, v34
	v_mul_f32_e32 v1, v13, v34
	v_mul_f32_e32 v4, v14, v34
	v_mul_f32_e32 v5, v15, v34
	v_cvt_pk_bf16_f32 v0, v0, v1
	v_cvt_pk_bf16_f32 v1, v4, v5
	ds_write2_b64 v33, v[2:3], v[0:1] offset0:12 offset1:14
	s_and_b64 exec, exec, s[0:1]
	s_cbranch_execz .LBB0_234
	v_lshl_add_u32 v0, v32, 3, 0
	v_add_u32_e32 v0, 0x19800, v0
	ds_write_b64 v0, v[126:127]
	s_branch .LBB0_234
; __device__ __forceinline__ void loadK(KFr& f, const char*& p) {
; #pragma unroll
;     for (int kh = 0; kh < 2; ++kh) {
; #pragma unroll
;         for (int d0 = 0; d0 < 4; ++d0) f.a[kh][d0] = *(const bf16x8*)(p + d0 * 1024);
;         p += 4096; asm volatile("" : "+v"(p));
;     }
; }
; __device__ __forceinline__ void loadV(VFr& f, const char*& p) {
; #pragma unroll
;     for (int dh = 0; dh < 2; ++dh) {
; #pragma unroll
;         for (int ks = 0; ks < 4; ++ks) f.a[dh][ks] = *(const bf16x8*)(p + ks * 1024);
;         p += 4096; asm volatile("" : "+v"(p));
;     }
; }
; __device__ __forceinline__ void moba_unit(int b, int h, int qb, const bf16* qkv, const bf16* KF, const bf16* VF, bf16* Y, const float* kmean, LAS unsigned char* lds) {
;     ...
;     const int lane = tc_ & 63, wave = __builtin_amdgcn_readfirstlane(tc_ >> 6), r32 = lane & 31, hi = lane >> 5;
;     const int qloc = 32 * wave + r32; const size_t row = (size_t)b * SEQ + 256 * qb + qloc;
;     const unsigned selmask = SEL[qloc];
;     float m = -1e30f, l = 0.f;
;     f32x16 o0, o1;
; #pragma unroll
;     for (int r = 0; r < 16; ++r) { o0[r] = 0.f; o1[r] = 0.f; }
;     {
;         const char* kp = (const char*)(KFh + (size_t)(4 * qb) * 4096) + lane * 16; const char* vp = (const char*)(VFh + (size_t)(4 * qb) * 4096) + lane * 16; const int nown = (wave >> 1) + 1;
;         asm volatile("" : "+v"(kp)); asm volatile("" : "+v"(vp));
;         bf16x8 qo[4];
;         { const bf16* qp = qkv + row * PA + C_CQ + h * 64 + hi * 8;
; #pragma unroll
;           for (int d0 = 0; d0 < 4; ++d0) qo[d0] = *(const bf16x8*)(qp + 16 * d0); }
;         KFr k0; VFr v0; u32x4 pw[4];
; #pragma unroll 1
;         for (int i = 0; i < nown; ++i) {
;             loadK(k0, kp); loadV(v0, vp);
;             tile_qk<1>(k0, qo, pw, o0, o1, m, l, 64 * i - qloc, sl2, lane); tile_pv(v0, pw, o0, o1);
;         }
.LBB0_266:
	s_nop 5
	v_mov_b32_e32 v0, v206
	v_readlane_b32 s0, v252, 59
	v_readfirstlane_b32 s3, v0
	s_ashr_i32 s2, s3, 1
	v_mov_b32_e32 v1, s2
	v_bfi_b32 v116, s75, v1, v0
	v_lshl_add_u32 v1, v116, 2, 0
	v_ashrrev_i32_e32 v117, 31, v116
	v_add_u32_e32 v1, 0x1d080, v1
	v_readlane_b32 s1, v252, 60
	s_or_b32 s0, s0, s21
	s_lshl_b32 s12, s20, 15
	ds_read_b32 v122, v1
	v_and_b32_e32 v1, 63, v0
	v_lshl_add_u64 v[114:115], s[0:1], 0, v[116:117]
	s_add_u32 s0, s10, s12
	s_addc_u32 s1, s11, 0
	v_lshlrev_b32_e32 v64, 4, v1
	v_lshl_add_u64 v[118:119], s[0:1], 0, v[64:65]
	s_add_u32 s0, s6, s12
	s_waitcnt lgkmcnt(1)
	v_bfe_u32 v2, v0, 5, 1
	s_addc_u32 s1, s7, 0
	s_ashr_i32 s3, s3, 7
	v_lshl_add_u64 v[120:121], s[0:1], 0, v[64:65]
	v_lshlrev_b32_e32 v64, 3, v2
	s_cmp_gt_i32 s3, -1
	s_mov_b64 s[0:1], -1
	s_cbranch_scc0 .LBB0_270
	v_mov_b64_e32 v[2:3], s[36:37]
	s_movk_i32 s6, 0x1e00
	v_mad_u64_u32 v[2:3], s[0:1], v114, s6, v[2:3]
	s_waitcnt vmcnt(0)
	v_mov_b32_e32 v4, v3
	v_mad_u64_u32 v[4:5], s[0:1], v115, s6, v[4:5]
	v_mov_b32_e32 v3, v4
	s_lshl_b32 s46, s19, 1
	v_lshl_add_u64 v[2:3], v[2:3], 0, s[46:47]
	v_lshlrev_b32_e32 v4, 1, v64
	v_mov_b32_e32 v5, v65
	v_lshl_add_u64 v[2:3], v[2:3], 0, v[4:5]
	s_mov_b64 s[0:1], 0x1200
	v_lshl_add_u64 v[4:5], v[2:3], 0, s[0:1]
	v_add_co_u32_e32 v2, vcc, 0x1000, v2
	global_load_dwordx4 v[66:69], v[4:5], off offset:64
	global_load_dwordx4 v[70:73], v[4:5], off offset:32
	v_addc_co_u32_e32 v3, vcc, 0, v3, vcc
	global_load_dwordx4 v[74:77], v[4:5], off offset:96
	global_load_dwordx4 v[78:81], v[2:3], off offset:512
	v_and_b32_e32 v1, 31, v0
	v_lshrrev_b32_e32 v0, 3, v0
	v_and_b32_e32 v0, 4, v0
	s_andn2_b32 s2, s2, 31
	v_sub_u32_e32 v0, v0, v1
	v_mov_b32_e32 v50, 0
	s_add_i32 s0, s3, 1
	v_subrev_u32_e32 v117, s2, v0
	v_mov_b32_e32 v32, 0xf149f2ca
	v_mov_b32_e32 v0, 0
	v_mov_b32_e32 v1, v50
	v_mov_b32_e32 v2, v50
	v_mov_b32_e32 v3, v50
	v_mov_b32_e32 v4, v50
	v_mov_b32_e32 v5, v50
	v_mov_b32_e32 v6, v50
	v_mov_b32_e32 v7, v50
	v_mov_b32_e32 v8, v50
	v_mov_b32_e32 v9, v50
	v_mov_b32_e32 v10, v50
	v_mov_b32_e32 v11, v50
	v_mov_b32_e32 v12, v50
	v_mov_b32_e32 v13, v50
	v_mov_b32_e32 v14, v50
	v_mov_b32_e32 v15, v50
	v_mov_b32_e32 v16, 0
	v_mov_b32_e32 v17, v50
	v_mov_b32_e32 v18, v50
	v_mov_b32_e32 v19, v50
	v_mov_b32_e32 v20, v50
	v_mov_b32_e32 v21, v50
	v_mov_b32_e32 v22, v50
	v_mov_b32_e32 v23, v50
	v_mov_b32_e32 v24, v50
	v_mov_b32_e32 v25, v50
	v_mov_b32_e32 v26, v50
	v_mov_b32_e32 v27, v50
	v_mov_b32_e32 v28, v50
	v_mov_b32_e32 v29, v50
	v_mov_b32_e32 v30, v50
	v_mov_b32_e32 v31, v50
	s_mov_b32 s1, 0xff800000
	s_movk_i32 s2, 0xffe1
	s_movk_i32 s3, 0xffd9
	v_lshl_add_u64 v[40:41], v[118:119], 0, s[56:57]
	global_load_dwordx4 v[150:153], v[118:119], off
	global_load_dwordx4 v[154:157], v[118:119], off offset:1024
	global_load_dwordx4 v[158:161], v[118:119], off offset:2048
	global_load_dwordx4 v[162:165], v[118:119], off offset:3072
	global_load_dwordx4 v[166:169], v[40:41], off
	global_load_dwordx4 v[170:173], v[40:41], off offset:1024
	global_load_dwordx4 v[174:177], v[40:41], off offset:2048
	global_load_dwordx4 v[178:181], v[40:41], off offset:3072
	v_lshl_add_u64 v[118:119], v[40:41], 0, s[56:57]
	v_lshl_add_u64 v[40:41], v[120:121], 0, s[56:57]
	global_load_dwordx4 v[182:185], v[120:121], off
	global_load_dwordx4 v[186:189], v[120:121], off offset:1024
	global_load_dwordx4 v[190:193], v[120:121], off offset:2048
	global_load_dwordx4 v[194:197], v[120:121], off offset:3072
	global_load_dwordx4 v[198:201], v[40:41], off
	global_load_dwordx4 v[202:205], v[40:41], off offset:1024
	global_load_dwordx4 v[208:211], v[40:41], off offset:2048
	global_load_dwordx4 v[212:215], v[40:41], off offset:3072
	v_lshl_add_u64 v[120:121], v[40:41], 0, s[56:57]
.LBB0_268:
	v_mov_b32_e32 v124, v32
	v_mov_b32_e32 v123, v50
	s_waitcnt vmcnt(0)
	v_mov_b32_e32 v32, v150
	v_mov_b32_e32 v33, v151
	v_mov_b32_e32 v34, v152
	v_mov_b32_e32 v35, v153
	v_mov_b32_e32 v126, v154
	v_mov_b32_e32 v127, v155
	v_mov_b32_e32 v128, v156
	v_mov_b32_e32 v129, v157
	v_mov_b32_e32 v130, v158
	v_mov_b32_e32 v131, v159
	v_mov_b32_e32 v132, v160
	v_mov_b32_e32 v133, v161
	v_mov_b32_e32 v134, v162
	v_mov_b32_e32 v135, v163
	v_mov_b32_e32 v136, v164
	v_mov_b32_e32 v137, v165
	v_mov_b32_e32 v36, v166
	v_mov_b32_e32 v37, v167
	v_mov_b32_e32 v38, v168
	v_mov_b32_e32 v39, v169
	v_mov_b32_e32 v138, v170
	v_mov_b32_e32 v139, v171
	v_mov_b32_e32 v140, v172
	v_mov_b32_e32 v141, v173
	v_mov_b32_e32 v142, v174
	v_mov_b32_e32 v143, v175
	v_mov_b32_e32 v144, v176
	v_mov_b32_e32 v145, v177
	v_mov_b32_e32 v146, v178
	v_mov_b32_e32 v147, v179
	v_mov_b32_e32 v148, v180
	v_mov_b32_e32 v149, v181
	v_mov_b32_e32 v94, v182
	v_mov_b32_e32 v95, v183
	v_mov_b32_e32 v96, v184
	v_mov_b32_e32 v97, v185
	v_mov_b32_e32 v90, v186
	v_mov_b32_e32 v91, v187
	v_mov_b32_e32 v92, v188
	v_mov_b32_e32 v93, v189
	v_mov_b32_e32 v86, v190
	v_mov_b32_e32 v87, v191
	v_mov_b32_e32 v88, v192
	v_mov_b32_e32 v89, v193
	v_mov_b32_e32 v82, v194
	v_mov_b32_e32 v83, v195
	v_mov_b32_e32 v84, v196
	v_mov_b32_e32 v85, v197
	v_mov_b32_e32 v110, v198
	v_mov_b32_e32 v111, v199
	v_mov_b32_e32 v112, v200
	v_mov_b32_e32 v113, v201
	v_mov_b32_e32 v106, v202
	v_mov_b32_e32 v107, v203
	v_mov_b32_e32 v108, v204
	v_mov_b32_e32 v109, v205
	v_mov_b32_e32 v102, v208
	v_mov_b32_e32 v103, v209
	v_mov_b32_e32 v104, v210
	v_mov_b32_e32 v105, v211
	v_mov_b32_e32 v98, v212
	v_mov_b32_e32 v99, v213
	v_mov_b32_e32 v100, v214
	v_mov_b32_e32 v101, v215
	v_cmp_gt_i32_e32 vcc, 1, v117
	s_add_i32 s0, s0, -1
	s_cmp_eq_u32 s0, 0
	s_cbranch_scc1 .Lmy_ob_nopf_268
	v_lshl_add_u64 v[40:41], v[118:119], 0, s[56:57]
	global_load_dwordx4 v[150:153], v[118:119], off
	global_load_dwordx4 v[154:157], v[118:119], off offset:1024
	global_load_dwordx4 v[158:161], v[118:119], off offset:2048
	global_load_dwordx4 v[162:165], v[118:119], off offset:3072
	global_load_dwordx4 v[166:169], v[40:41], off
	global_load_dwordx4 v[170:173], v[40:41], off offset:1024
	global_load_dwordx4 v[174:177], v[40:41], off offset:2048
	global_load_dwordx4 v[178:181], v[40:41], off offset:3072
	v_lshl_add_u64 v[118:119], v[40:41], 0, s[56:57]
	v_lshl_add_u64 v[40:41], v[120:121], 0, s[56:57]
	global_load_dwordx4 v[182:185], v[120:121], off
	global_load_dwordx4 v[186:189], v[120:121], off offset:1024
	global_load_dwordx4 v[190:193], v[120:121], off offset:2048
	global_load_dwordx4 v[194:197], v[120:121], off offset:3072
	global_load_dwordx4 v[198:201], v[40:41], off
	global_load_dwordx4 v[202:205], v[40:41], off offset:1024
	global_load_dwordx4 v[208:211], v[40:41], off offset:2048
	global_load_dwordx4 v[212:215], v[40:41], off offset:3072
	v_lshl_add_u64 v[120:121], v[40:41], 0, s[56:57]
; template <int MASK>
; __device__ __forceinline__ void tile_qk(const KFr& f, const bf16x8 (&qf)[4], u32x4 (&pw)[4], f32x16& o0, f32x16& o1, float& m, float& l, int kq, float sl2, int lane) {
;     const int hi = lane >> 5;
;     f32x16 p0, p1;
; #pragma unroll
;     for (int r = 0; r < 16; ++r) { p0[r] = 0.f; p1[r] = 0.f; }
; #pragma unroll
;     for (int d0 = 0; d0 < 4; ++d0) {
;         p0 = __builtin_amdgcn_mfma_f32_32x32x16_bf16(f.a[0][d0], qf[d0], p0, 0, 0, 0);
;         p1 = __builtin_amdgcn_mfma_f32_32x32x16_bf16(f.a[1][d0], qf[d0], p1, 0, 0, 0);
;     }
;     constexpr float C2 = 0.125f * LOG2E;
;     const int dk0 = kq + 4 * hi;
;     float sl = sl2; asm volatile("" : "+v"(sl));
;     const float base = sl * (float)dk0;
;     const float NEG = -INFINITY;
;     float mx = NEG;
; #pragma unroll
;     for (int r = 0; r < 16; ++r) {
;         const int kk = (r & 3) + 8 * (r >> 2);
;         float t0 = fmaf(p0[r], C2, fmaf((float)kk, sl, base)), t1 = fmaf(p1[r], C2, fmaf((float)(kk + 32), sl, base));
;         if (MASK == 1) { if (dk0 + kk > 0) t0 = NEG; if (dk0 + kk + 32 > 0) t1 = NEG; }
;         p0[r] = t0; p1[r] = t1; mx = fmaxf(mx, fmaxf(t0, t1));
;     }
;     mx = fmaxf(mx, __shfl_xor(mx, 32));
.Lmy_ob_nopf_268:
	s_waitcnt lgkmcnt(0)
	v_mfma_f32_32x32x16_bf16 v[48:63], v[32:35], v[78:81], 0
	v_mfma_f32_32x32x16_bf16 v[32:47], v[36:39], v[78:81], 0
	v_mfma_f32_32x32x16_bf16 v[48:63], v[126:129], v[70:73], v[48:63]
	v_cvt_f32_i32_e32 v126, v117
	v_mov_b32_e32 v129, v230
	v_mfma_f32_32x32x16_bf16 v[32:47], v[138:141], v[70:73], v[32:47]
	v_mfma_f32_32x32x16_bf16 v[48:63], v[130:133], v[66:69], v[48:63]
	v_mul_f32_e32 v130, v129, v126
	v_fma_f32 v125, 0, v129, v130
	v_fmamk_f32 v127, v129, 0x42000000, v130
	v_fma_f32 v126, v129, v126, v129
	v_fmamk_f32 v128, v129, 0x420c0000, v130
	v_mfma_f32_32x32x16_bf16 v[32:47], v[142:145], v[66:69], v[32:47]
	v_mfma_f32_32x32x16_bf16 v[48:63], v[134:137], v[74:77], v[48:63]
	v_mfma_f32_32x32x16_bf16 v[32:47], v[146:149], v[74:77], v[32:47]
	s_nop 10
	v_fmac_f32_e32 v125, 0x3e38aa3b, v48
	v_cndmask_b32_e32 v48, v228, v125, vcc
	v_cmp_gt_i32_e32 vcc, s2, v117
	v_fmac_f32_e32 v126, 0x3e38aa3b, v49
	v_fmac_f32_e32 v127, 0x3e38aa3b, v32
	v_cndmask_b32_e32 v125, v228, v127, vcc
	v_fmamk_f32 v127, v129, 0x42040000, v130
	v_cmp_gt_i32_e32 vcc, 0, v117
	v_fmac_f32_e32 v127, 0x3e38aa3b, v33
	v_max_f32_e32 v32, v48, v125
	v_cndmask_b32_e32 v49, v228, v126, vcc
	v_cmp_gt_i32_e32 vcc, s75, v117
	v_fmac_f32_e32 v128, 0x3e38aa3b, v35
	v_fmamk_f32 v35, v129, 0x42240000, v130
	v_cndmask_b32_e32 v126, v228, v127, vcc
	v_max_f32_e32 v33, v49, v126
	v_max3_f32 v32, v32, s1, v33
	v_fma_f32 v33, 2.0, v129, v130
	v_fmac_f32_e32 v33, 0x3e38aa3b, v50
	v_fmamk_f32 v127, v129, 0x42080000, v130
	v_cmp_gt_i32_e32 vcc, -1, v117
	v_fmac_f32_e32 v127, 0x3e38aa3b, v34
	v_fmamk_f32 v34, v129, 0x40400000, v130
	v_cndmask_b32_e32 v50, v228, v33, vcc
	v_cmp_gt_i32_e32 vcc, s72, v117
	v_fmac_f32_e32 v34, 0x3e38aa3b, v51
	v_fmac_f32_e32 v35, 0x3e38aa3b, v37
	v_cndmask_b32_e32 v127, v228, v127, vcc
	v_cmp_gt_i32_e32 vcc, -2, v117
	v_max_f32_e32 v33, v50, v127
	s_nop 0
	v_cndmask_b32_e32 v51, v228, v34, vcc
	v_cmp_gt_i32_e32 vcc, s74, v117
	s_nop 1
	v_cndmask_b32_e32 v128, v228, v128, vcc
	v_max_f32_e32 v34, v51, v128
	v_max3_f32 v32, v32, v33, v34
	v_fmamk_f32 v33, v129, 0x41000000, v130
	v_fmac_f32_e32 v33, 0x3e38aa3b, v52
	v_fmamk_f32 v34, v129, 0x42200000, v130
	v_cmp_gt_i32_e32 vcc, -7, v117
	v_fmac_f32_e32 v34, 0x3e38aa3b, v36
	s_nop 0
	v_cndmask_b32_e32 v36, v228, v33, vcc
	v_cmp_gt_i32_e32 vcc, s3, v117
	s_nop 1
	v_cndmask_b32_e32 v52, v228, v34, vcc
	v_fmamk_f32 v34, v129, 0x41100000, v130
	v_fmac_f32_e32 v34, 0x3e38aa3b, v53
	v_cmp_gt_i32_e32 vcc, -8, v117
	v_max_f32_e32 v33, v36, v52
	s_nop 0
	v_cndmask_b32_e32 v37, v228, v34, vcc
	v_cmp_gt_i32_e32 vcc, s78, v117
	s_nop 1
	v_cndmask_b32_e32 v53, v228, v35, vcc
	v_max_f32_e32 v34, v37, v53
	v_max3_f32 v32, v32, v33, v34
	v_fmamk_f32 v33, v129, 0x41200000, v130
	v_fmac_f32_e32 v33, 0x3e38aa3b, v54
	v_fmamk_f32 v34, v129, 0x42280000, v130
	v_cmp_gt_i32_e32 vcc, -9, v117
	v_fmac_f32_e32 v34, 0x3e38aa3b, v38
	v_fmamk_f32 v35, v129, 0x422c0000, v130
	v_cndmask_b32_e32 v38, v228, v33, vcc
	v_cmp_gt_i32_e32 vcc, s80, v117
	v_fmac_f32_e32 v35, 0x3e38aa3b, v39
	s_nop 0
	v_cndmask_b32_e32 v54, v228, v34, vcc
	v_fmamk_f32 v34, v129, 0x41300000, v130
	v_fmac_f32_e32 v34, 0x3e38aa3b, v55
	v_cmp_gt_i32_e32 vcc, -10, v117
	v_max_f32_e32 v33, v38, v54
	s_nop 0
	v_cndmask_b32_e32 v39, v228, v34, vcc
	v_cmp_gt_i32_e32 vcc, s73, v117
	s_nop 1
	v_cndmask_b32_e32 v55, v228, v35, vcc
	v_max_f32_e32 v34, v39, v55
	v_max3_f32 v32, v32, v33, v34
	v_fmamk_f32 v33, v129, 0x41800000, v130
	v_fmac_f32_e32 v33, 0x3e38aa3b, v56
	v_fmamk_f32 v34, v129, 0x42400000, v130
	v_cmp_gt_i32_e32 vcc, -15, v117
	v_fmac_f32_e32 v34, 0x3e38aa3b, v40
	v_fmamk_f32 v35, v129, 0x42440000, v130
	v_cndmask_b32_e32 v40, v228, v33, vcc
	v_cmp_gt_i32_e32 vcc, s44, v117
	v_fmac_f32_e32 v35, 0x3e38aa3b, v41
	s_nop 0
	v_cndmask_b32_e32 v56, v228, v34, vcc
	v_fmamk_f32 v34, v129, 0x41880000, v130
	v_fmac_f32_e32 v34, 0x3e38aa3b, v57
	v_cmp_gt_i32_e32 vcc, -16, v117
	v_max_f32_e32 v33, v40, v56
	s_nop 0
	v_cndmask_b32_e32 v41, v228, v34, vcc
	v_cmp_gt_i32_e32 vcc, s76, v117
	s_nop 1
	v_cndmask_b32_e32 v57, v228, v35, vcc
	v_max_f32_e32 v34, v41, v57
	v_max3_f32 v32, v32, v33, v34
	v_fmamk_f32 v33, v129, 0x41900000, v130
	v_fmac_f32_e32 v33, 0x3e38aa3b, v58
	v_fmamk_f32 v34, v129, 0x42480000, v130
	v_cmp_gt_i32_e32 vcc, s88, v117
	v_fmac_f32_e32 v34, 0x3e38aa3b, v42
	v_fmamk_f32 v35, v129, 0x424c0000, v130
	v_cndmask_b32_e32 v42, v228, v33, vcc
	v_cmp_gt_i32_e32 vcc, s77, v117
	v_fmac_f32_e32 v35, 0x3e38aa3b, v43
	s_nop 0
	v_cndmask_b32_e32 v58, v228, v34, vcc
	v_fmamk_f32 v34, v129, 0x41980000, v130
	v_fmac_f32_e32 v34, 0x3e38aa3b, v59
	v_cmp_gt_i32_e32 vcc, s90, v117
	v_max_f32_e32 v33, v42, v58
	s_nop 0
	v_cndmask_b32_e32 v43, v228, v34, vcc
	v_cmp_gt_i32_e32 vcc, s79, v117
	s_nop 1
	v_cndmask_b32_e32 v59, v228, v35, vcc
	v_max_f32_e32 v34, v43, v59
	v_max3_f32 v32, v32, v33, v34
	v_fmamk_f32 v33, v129, 0x41c00000, v130
	v_fmac_f32_e32 v33, 0x3e38aa3b, v60
	v_fmamk_f32 v34, v129, 0x42600000, v130
	v_cmp_gt_i32_e32 vcc, s45, v117
	v_fmac_f32_e32 v34, 0x3e38aa3b, v44
	v_fmamk_f32 v35, v129, 0x42640000, v130
	v_cndmask_b32_e32 v44, v228, v33, vcc
	v_cmp_gt_i32_e32 vcc, s52, v117
	v_fmac_f32_e32 v35, 0x3e38aa3b, v45
	s_nop 0
	v_cndmask_b32_e32 v60, v228, v34, vcc
	v_fmamk_f32 v34, v129, 0x41c80000, v130
	v_fmac_f32_e32 v34, 0x3e38aa3b, v61
	v_cmp_gt_i32_e32 vcc, s94, v117
	v_max_f32_e32 v33, v44, v60
	s_nop 0
	v_cndmask_b32_e32 v45, v228, v34, vcc
	v_cmp_gt_i32_e32 vcc, s81, v117
	s_nop 1
	v_cndmask_b32_e32 v61, v228, v35, vcc
	v_max_f32_e32 v34, v45, v61
	v_max3_f32 v32, v32, v33, v34
	v_fmamk_f32 v33, v129, 0x41d00000, v130
	v_fmac_f32_e32 v33, 0x3e38aa3b, v62
	v_fmamk_f32 v34, v129, 0x42680000, v130
	v_cmp_gt_i32_e32 vcc, s96, v117
	v_fmac_f32_e32 v34, 0x3e38aa3b, v46
	s_nop 0
	v_cndmask_b32_e32 v46, v228, v33, vcc
	v_cmp_gt_i32_e32 vcc, s82, v117
	s_nop 1
	v_cndmask_b32_e32 v62, v228, v34, vcc
	v_fmamk_f32 v34, v129, 0x41d80000, v130
	v_fmac_f32_e32 v34, 0x3e38aa3b, v63
	v_fmac_f32_e32 v130, 0x426c0000, v129
	v_cmp_gt_i32_e32 vcc, s83, v117
	v_fmac_f32_e32 v130, 0x3e38aa3b, v47
	v_max_f32_e32 v33, v46, v62
	v_cndmask_b32_e32 v47, v228, v34, vcc
	v_cmp_gt_i32_e32 vcc, s84, v117
	v_add_u32_e32 v117, 64, v117
	s_nop 0
	v_cndmask_b32_e32 v63, v228, v130, vcc
	v_max_f32_e32 v34, v47, v63
	v_max3_f32 v32, v32, v33, v34
	v_mbcnt_hi_u32_b32 v34, -1, v220
	v_and_b32_e32 v35, 64, v34
	v_xor_b32_e32 v33, 32, v34
	v_add_u32_e32 v35, 64, v35
	v_cmp_lt_i32_e32 vcc, v33, v35
	s_nop 1
	v_cndmask_b32_e32 v129, v34, v33, vcc
	v_lshlrev_b32_e32 v129, 2, v129
	ds_bpermute_b32 v129, v129, v32
	s_waitcnt lgkmcnt(0)
; __device__ __forceinline__ unsigned pk2(float lo, float hi) { return pg8::cvt_pk_bf16(lo, hi); }
; template <int MASK>
; __device__ __forceinline__ void tile_qk(const KFr& f, const bf16x8 (&qf)[4], u32x4 (&pw)[4], f32x16& o0, f32x16& o1, float& m, float& l, int kq, float sl2, int lane) {
;     ...
;     mx = fmaxf(mx, __shfl_xor(mx, 32));
;     const float mn = fmaxf(m, mx), alpha = __builtin_amdgcn_exp2f(m - mn); m = mn;
;     float rs = 0.f;
; #pragma unroll
;     for (int r = 0; r < 16; ++r) { p0[r] = __builtin_amdgcn_exp2f(p0[r] - mn); p1[r] = __builtin_amdgcn_exp2f(p1[r] - mn); rs += p0[r] + p1[r]; }
;     l = l * alpha + rs;
; #pragma unroll
;     for (int r = 0; r < 16; ++r) { o0[r] *= alpha; o1[r] *= alpha; }
;     pw[0] = (u32x4){pk2(p0[0], p0[1]), pk2(p0[2], p0[3]), pk2(p0[4], p0[5]), pk2(p0[6], p0[7])};
;     pw[1] = (u32x4){pk2(p0[8], p0[9]), pk2(p0[10], p0[11]), pk2(p0[12], p0[13]), pk2(p0[14], p0[15])};
;     pw[2] = (u32x4){pk2(p1[0], p1[1]), pk2(p1[2], p1[3]), pk2(p1[4], p1[5]), pk2(p1[6], p1[7])};
;     pw[3] = (u32x4){pk2(p1[8], p1[9]), pk2(p1[10], p1[11]), pk2(p1[12], p1[13]), pk2(p1[14], p1[15])};
; __device__ __forceinline__ void tile_pv(const VFr& f, const u32x4 (&pw)[4], f32x16& o0, f32x16& o1) {
; #pragma unroll
;     for (int ks = 0; ks < 4; ++ks) {
;         const bf16x8 P = __builtin_bit_cast(bf16x8, pw[ks]);
;         o0 = __builtin_amdgcn_mfma_f32_32x32x16_bf16(f.a[0][ks], P, o0, 0, 0, 0);
;         o1 = __builtin_amdgcn_mfma_f32_32x32x16_bf16(f.a[1][ks], P, o1, 0, 0, 0);
;     }
; }
	v_max3_f32 v32, v124, v32, v129
	v_sub_f32_e32 v48, v48, v32
	v_exp_f32_e32 v130, v48
	v_sub_f32_e32 v48, v125, v32
	v_sub_f32_e32 v49, v49, v32
	v_exp_f32_e32 v131, v48
	v_exp_f32_e32 v132, v49
	v_sub_f32_e32 v49, v126, v32
	v_exp_f32_e32 v133, v49
	v_add_f32_e32 v48, v131, v130
	v_add_f32_e32 v48, 0, v48
	v_sub_f32_e32 v36, v36, v32
	v_add_f32_e32 v49, v133, v132
	v_add_f32_e32 v48, v49, v48
	v_sub_f32_e32 v49, v50, v32
	v_exp_f32_e32 v134, v49
	v_sub_f32_e32 v49, v127, v32
	v_exp_f32_e32 v135, v49
	v_sub_f32_e32 v129, v124, v32
	v_add_f32_e32 v49, v135, v134
	v_add_f32_e32 v48, v49, v48
	v_sub_f32_e32 v49, v51, v32
	v_exp_f32_e32 v51, v49
	v_sub_f32_e32 v49, v128, v32
	v_exp_f32_e32 v128, v49
	s_nop 0
	v_add_f32_e32 v49, v128, v51
	v_add_f32_e32 v50, v49, v48
	v_exp_f32_e32 v49, v36
	v_sub_f32_e32 v36, v52, v32
	v_exp_f32_e32 v125, v36
	v_sub_f32_e32 v36, v37, v32
	v_exp_f32_e32 v48, v36
	v_sub_f32_e32 v36, v53, v32
	v_exp_f32_e32 v124, v36
	s_nop 0
	v_add_f32_e32 v36, v124, v48
	v_add_f32_e32 v37, v125, v49
	s_nop 0
	v_add_f32_e32 v37, v37, v50
	v_add_f32_e32 v50, v36, v37
	v_sub_f32_e32 v36, v38, v32
	v_exp_f32_e32 v37, v36
	v_sub_f32_e32 v36, v54, v32
	v_exp_f32_e32 v53, v36
	v_sub_f32_e32 v36, v39, v32
	v_sub_f32_e32 v38, v55, v32
	v_exp_f32_e32 v36, v36
	v_exp_f32_e32 v52, v38
	s_nop 0
	v_add_f32_e32 v38, v52, v36
	v_add_f32_e32 v39, v53, v37
	s_nop 0
	v_add_f32_e32 v39, v39, v50
	v_add_f32_e32 v50, v38, v39
	v_sub_f32_e32 v38, v40, v32
	v_exp_f32_e32 v39, v38
	v_sub_f32_e32 v38, v56, v32
	v_exp_f32_e32 v55, v38
	v_sub_f32_e32 v38, v41, v32
	v_sub_f32_e32 v40, v57, v32
	v_exp_f32_e32 v38, v38
	v_exp_f32_e32 v54, v40
	v_pk_mov_b32 v[52:53], v[52:53], v[52:53] op_sel:[1,0]
	v_add_f32_e32 v40, v54, v38
	v_add_f32_e32 v41, v55, v39
	s_nop 0
	v_add_f32_e32 v41, v41, v50
	v_add_f32_e32 v50, v40, v41
	v_sub_f32_e32 v40, v42, v32
	v_exp_f32_e32 v41, v40
	v_sub_f32_e32 v40, v58, v32
	v_exp_f32_e32 v57, v40
	v_sub_f32_e32 v40, v43, v32
	v_sub_f32_e32 v42, v59, v32
	v_exp_f32_e32 v40, v40
	v_exp_f32_e32 v56, v42
	v_pk_mov_b32 v[54:55], v[54:55], v[54:55] op_sel:[1,0]
	v_pk_mov_b32 v[126:127], v[40:41], v[40:41] op_sel:[1,0]
	v_add_f32_e32 v42, v56, v40
	v_add_f32_e32 v43, v57, v41
	v_cvt_pk_bf16_f32 v41, v126, v127
	v_add_f32_e32 v43, v43, v50
	v_add_f32_e32 v50, v42, v43
	v_sub_f32_e32 v42, v44, v32
	v_exp_f32_e32 v43, v42
	v_sub_f32_e32 v42, v60, v32
	v_exp_f32_e32 v59, v42
	v_sub_f32_e32 v42, v45, v32
	v_sub_f32_e32 v44, v61, v32
	v_exp_f32_e32 v42, v42
	v_exp_f32_e32 v58, v44
	v_pk_mov_b32 v[56:57], v[56:57], v[56:57] op_sel:[1,0]
	v_add_f32_e32 v44, v58, v42
	v_add_f32_e32 v45, v59, v43
	s_nop 0
	v_add_f32_e32 v45, v45, v50
	v_add_f32_e32 v50, v44, v45
	v_sub_f32_e32 v44, v46, v32
	v_exp_f32_e32 v45, v44
	v_sub_f32_e32 v44, v62, v32
	v_exp_f32_e32 v61, v44
	v_sub_f32_e32 v44, v47, v32
	v_sub_f32_e32 v46, v63, v32
	v_exp_f32_e32 v44, v44
	v_exp_f32_e32 v60, v46
	v_pk_mov_b32 v[62:63], v[36:37], v[36:37] op_sel:[1,0]
	v_cvt_pk_bf16_f32 v36, v130, v132
	v_cvt_pk_bf16_f32 v37, v134, v51
	v_add_f32_e32 v46, v60, v44
	v_add_f32_e32 v47, v61, v45
	v_pk_mov_b32 v[42:43], v[42:43], v[42:43] op_sel:[1,0]
	v_add_f32_e32 v47, v47, v50
	v_add_f32_e32 v50, v46, v47
	v_exp_f32_e32 v46, v129
	v_pk_mov_b32 v[44:45], v[44:45], v[44:45] op_sel:[1,0]
	v_cvt_pk_bf16_f32 v42, v42, v43
	v_cvt_pk_bf16_f32 v43, v44, v45
	v_fmac_f32_e32 v50, v123, v46
	v_mul_f32_e32 v30, v30, v46
	v_mul_f32_e32 v31, v31, v46
	v_mul_f32_e32 v28, v28, v46
	v_mul_f32_e32 v29, v29, v46
	v_mul_f32_e32 v26, v26, v46
	v_mul_f32_e32 v27, v27, v46
	v_mul_f32_e32 v24, v24, v46
	v_mul_f32_e32 v25, v25, v46
	v_mul_f32_e32 v22, v22, v46
	v_mul_f32_e32 v23, v23, v46
	v_mul_f32_e32 v20, v20, v46
	v_mul_f32_e32 v21, v21, v46
	v_mul_f32_e32 v18, v18, v46
	v_mul_f32_e32 v19, v19, v46
	v_mul_f32_e32 v16, v16, v46
	v_mul_f32_e32 v17, v17, v46
	v_mul_f32_e32 v14, v14, v46
	v_mul_f32_e32 v15, v15, v46
	v_mul_f32_e32 v12, v12, v46
	v_mul_f32_e32 v13, v13, v46
	v_mul_f32_e32 v10, v10, v46
	v_mul_f32_e32 v11, v11, v46
	v_mul_f32_e32 v8, v8, v46
	v_mul_f32_e32 v9, v9, v46
	v_mul_f32_e32 v6, v6, v46
	v_mul_f32_e32 v7, v7, v46
	v_mul_f32_e32 v4, v4, v46
	v_mul_f32_e32 v5, v5, v46
	v_mul_f32_e32 v2, v2, v46
	v_mul_f32_e32 v3, v3, v46
	v_mul_f32_e32 v0, v0, v46
	v_mul_f32_e32 v1, v1, v46
	v_pk_mov_b32 v[46:47], v[48:49], v[48:49] op_sel:[1,0]
	v_pk_mov_b32 v[48:49], v[124:125], v[124:125] op_sel:[1,0]
	v_pk_mov_b32 v[124:125], v[38:39], v[38:39] op_sel:[1,0]
	v_cvt_pk_bf16_f32 v38, v46, v47
	v_cvt_pk_bf16_f32 v39, v62, v63
	v_cvt_pk_bf16_f32 v40, v124, v125
	v_cvt_pk_bf16_f32 v44, v131, v133
	v_mfma_f32_32x32x16_bf16 v[16:31], v[94:97], v[36:39], v[16:31]
	v_cvt_pk_bf16_f32 v45, v135, v128
	v_cvt_pk_bf16_f32 v46, v48, v49
	v_cvt_pk_bf16_f32 v47, v52, v53
	v_pk_mov_b32 v[58:59], v[58:59], v[58:59] op_sel:[1,0]
	v_pk_mov_b32 v[60:61], v[60:61], v[60:61] op_sel:[1,0]
	v_cvt_pk_bf16_f32 v52, v54, v55
	v_cvt_pk_bf16_f32 v53, v56, v57
	v_mfma_f32_32x32x16_bf16 v[0:15], v[110:113], v[36:39], v[0:15]
	v_cvt_pk_bf16_f32 v54, v58, v59
	v_cvt_pk_bf16_f32 v55, v60, v61
	v_mfma_f32_32x32x16_bf16 v[16:31], v[90:93], v[40:43], v[16:31]
	v_mfma_f32_32x32x16_bf16 v[0:15], v[106:109], v[40:43], v[0:15]
	v_mfma_f32_32x32x16_bf16 v[16:31], v[86:89], v[44:47], v[16:31]
	v_mfma_f32_32x32x16_bf16 v[0:15], v[102:105], v[44:47], v[0:15]
	v_mfma_f32_32x32x16_bf16 v[16:31], v[82:85], v[52:55], v[16:31]
	v_mfma_f32_32x32x16_bf16 v[0:15], v[98:101], v[52:55], v[0:15]
	s_cbranch_scc0 .LBB0_268
	s_mov_b64 s[0:1], 0

; #define LAS __attribute__((address_space(3)))
; #define WG_BAR() __syncthreads()
; __device__ __forceinline__ void moba_unit(int b, int h, int qb, const bf16* qkv, const bf16* KF, const bf16* VF, bf16* Y, const float* kmean, LAS unsigned char* lds) {
;     ...
;     WG_BAR();
;     {
;         const float lt = l + __shfl_xor(l, 32);
;         const int nsel = __builtin_popcount(selmask);
;         float mj[3], lj[3]; float M = m;
; #pragma unroll
;         for (int j = 0; j < 3; ++j) { mj[j] = -1e30f; lj[j] = 0.f;
;             if (j < nsel) { const f32x2v v = *(LAS const f32x2v*)(lds + MB_ML + (j * 256 + qloc) * 8); mj[j] = v.x; lj[j] = v.y; }
;             M = fmaxf(M, mj[j]); }
;         const float w0 = __builtin_amdgcn_exp2f(m - M); float den = lt * w0;
; #pragma unroll
;         for (int r = 0; r < 16; ++r) { o0[r] *= w0; o1[r] *= w0; }
.LBB0_272:
	v_cmp_lt_i32_e32 vcc, v33, v35
	s_waitcnt lgkmcnt(0)
	v_cmp_ne_u32_e64 s[6:7], 0, v122
	v_mov_b32_e32 v47, 0
	v_cndmask_b32_e32 v33, v34, v33, vcc
	v_lshlrev_b32_e32 v33, 2, v33
	ds_bpermute_b32 v52, v33, v50
	v_lshlrev_b32_e32 v33, 3, v116
	v_mov_b32_e32 v46, 0xf149f2ca
	v_mov_b32_e32 v48, 0xf149f2ca
	v_mov_b32_e32 v49, 0
	s_waitcnt lgkmcnt(0)
	s_barrier
	s_and_saveexec_b64 s[0:1], s[6:7]
	v_add_u32_e32 v34, 0, v33
	v_add_u32_e32 v34, 0x19800, v34
	ds_read_b64 v[48:49], v34
	s_or_b64 exec, exec, s[0:1]
	v_bcnt_u32_b32 v34, v122, 0
	v_cmp_lt_u32_e64 s[0:1], 1, v34
	s_and_saveexec_b64 s[2:3], s[0:1]
	s_add_i32 s10, 0, 0x19800
	v_add_u32_e32 v35, s10, v33
	ds_read_b64 v[46:47], v35 offset:2048
	s_or_b64 exec, exec, s[2:3]
	v_cmp_lt_u32_e32 vcc, 2, v34
	v_mov_b32_e32 v45, 0
	v_mov_b32_e32 v44, 0xf149f2ca
	s_and_saveexec_b64 s[2:3], vcc
	s_add_i32 s10, 0, 0x19800
	v_add_u32_e32 v33, s10, v33
	ds_read_b64 v[44:45], v33 offset:4096
	s_or_b64 exec, exec, s[2:3]
	s_waitcnt lgkmcnt(0)
	v_max_f32_e32 v33, v48, v48
	v_max_f32_e32 v34, v32, v32
	v_max_f32_e32 v33, v34, v33
	v_max3_f32 v51, v33, v46, v44
	v_sub_f32_e32 v32, v32, v51
	v_exp_f32_e32 v54, v32
	s_nop 0
	v_mul_f32_e32 v36, v0, v54
	v_mul_f32_e32 v37, v1, v54
	s_waitcnt vmcnt(1)
	v_mul_f32_e32 v0, v12, v54
	v_mul_f32_e32 v1, v13, v54
	v_add_f32_e32 v12, v50, v52
	v_mul_f32_e32 v40, v16, v54
	v_mul_f32_e32 v41, v17, v54
	v_mul_f32_e32 v42, v18, v54
	v_mul_f32_e32 v43, v19, v54
	v_mul_f32_e32 v38, v2, v54
	v_mul_f32_e32 v39, v3, v54
	v_mul_f32_e32 v32, v20, v54
	v_mul_f32_e32 v33, v21, v54
	s_waitcnt vmcnt(0)
	v_mul_f32_e32 v20, v4, v54
	v_mul_f32_e32 v21, v5, v54
	v_mul_f32_e32 v34, v22, v54
	v_mul_f32_e32 v35, v23, v54
	v_mul_f32_e32 v22, v6, v54
	v_mul_f32_e32 v23, v7, v54
	v_mul_f32_e32 v16, v24, v54
	v_mul_f32_e32 v17, v25, v54
	v_mul_f32_e32 v8, v8, v54
	v_mul_f32_e32 v9, v9, v54
	v_mul_f32_e32 v18, v26, v54
	v_mul_f32_e32 v19, v27, v54
	v_mul_f32_e32 v10, v10, v54
	v_mul_f32_e32 v11, v11, v54
	v_mul_f32_e32 v4, v28, v54
	v_mul_f32_e32 v5, v29, v54
	v_mul_f32_e32 v6, v30, v54
	v_mul_f32_e32 v7, v31, v54
	v_mul_f32_e32 v2, v14, v54
	v_mul_f32_e32 v3, v15, v54
	v_mul_f32_e32 v13, v12, v54
	v_add_u32_e32 v12, 0, v64
	s_and_saveexec_b64 s[2:3], s[6:7]
	s_cbranch_execnz .LBB0_281
	s_or_b64 exec, exec, s[2:3]
	s_and_saveexec_b64 s[2:3], s[0:1]
	s_cbranch_execnz .LBB0_282

; #define LAS __attribute__((address_space(3)))
; __device__ __forceinline__ float bflo(unsigned u) { return __uint_as_float(u << 16); }
; __device__ __forceinline__ float bfhi(unsigned u) { return __uint_as_float(u & 0xffff0000u); }
; __device__ __forceinline__ void moba_unit(int b, int h, int qb, const bf16* qkv, const bf16* KF, const bf16* VF, bf16* Y, const float* kmean, LAS unsigned char* lds) {
;     ...
; #pragma unroll
;         for (int j = 0; j < 3; ++j) {
;             if (j < nsel) {
;                 const float wj = lj[j] * __builtin_amdgcn_exp2f(mj[j] - M); den += wj;
;                 LAS const unsigned char* op = lds + MB_OP + (j * 256 + qloc) * MB_OPROW + 8 * hi;
; #pragma unroll
;                 for (int rg = 0; rg < 4; ++rg) {
;                     const u32x2 x0 = *(LAS const u32x2*)(op + 16 * rg), x1 = *(LAS const u32x2*)(op + 64 + 16 * rg);
;                     o0[4 * rg] += wj * bflo(x0.x); o0[4 * rg + 1] += wj * bfhi(x0.x); o0[4 * rg + 2] += wj * bflo(x0.y); o0[4 * rg + 3] += wj * bfhi(x0.y);
;                     o1[4 * rg] += wj * bflo(x1.x); o1[4 * rg + 1] += wj * bfhi(x1.x); o1[4 * rg + 2] += wj * bflo(x1.y); o1[4 * rg + 3] += wj * bfhi(x1.y); }
;             }
.LBB0_281:
	v_sub_f32_e32 v14, v48, v51
	s_movk_i32 s6, 0x88
	v_exp_f32_e32 v50, v14
	v_mad_u64_u32 v[14:15], s[6:7], v116, s6, v[12:13]
	ds_read2_b64 v[24:27], v14 offset1:2
	ds_read2_b64 v[28:31], v14 offset0:8 offset1:10
	ds_read2_b64 v[52:55], v14 offset0:4 offset1:6
	v_mul_f32_e32 v48, v49, v50
	v_fmac_f32_e32 v13, v49, v50
	s_waitcnt lgkmcnt(2)
	v_lshlrev_b32_e32 v56, 16, v24
	v_and_b32_e32 v57, 0xffff0000, v24
	v_lshlrev_b32_e32 v24, 16, v25
	v_and_b32_e32 v25, 0xffff0000, v25
	v_fma_f32 v42, v48, v24, v42
	v_fma_f32 v43, v48, v25, v43
	s_waitcnt lgkmcnt(1)
	v_lshlrev_b32_e32 v24, 16, v28
	v_and_b32_e32 v25, 0xffff0000, v28
	v_fma_f32 v36, v48, v24, v36
	v_fma_f32 v37, v48, v25, v37
	v_lshlrev_b32_e32 v24, 16, v29
	v_and_b32_e32 v25, 0xffff0000, v29
	v_fma_f32 v38, v48, v24, v38
	v_fma_f32 v39, v48, v25, v39
	v_lshlrev_b32_e32 v24, 16, v26
	v_and_b32_e32 v25, 0xffff0000, v26
	v_fma_f32 v32, v48, v24, v32
	v_fma_f32 v33, v48, v25, v33
	v_lshlrev_b32_e32 v24, 16, v27
	v_and_b32_e32 v25, 0xffff0000, v27
	v_fma_f32 v34, v48, v24, v34
	v_fma_f32 v35, v48, v25, v35
	v_lshlrev_b32_e32 v24, 16, v30
	v_and_b32_e32 v25, 0xffff0000, v30
	v_fma_f32 v20, v48, v24, v20
	v_fma_f32 v21, v48, v25, v21
	v_lshlrev_b32_e32 v24, 16, v31
	v_and_b32_e32 v25, 0xffff0000, v31
	v_fma_f32 v22, v48, v24, v22
	v_fma_f32 v23, v48, v25, v23
	ds_read2_b64 v[24:27], v14 offset0:12 offset1:14
	s_waitcnt lgkmcnt(1)
	v_lshlrev_b32_e32 v14, 16, v52
	v_and_b32_e32 v15, 0xffff0000, v52
	v_fma_f32 v16, v48, v14, v16
	v_fma_f32 v17, v48, v15, v17
	v_lshlrev_b32_e32 v14, 16, v53
	v_and_b32_e32 v15, 0xffff0000, v53
	v_fma_f32 v18, v48, v14, v18
	v_fma_f32 v19, v48, v15, v19
	s_waitcnt lgkmcnt(0)
	v_lshlrev_b32_e32 v14, 16, v24
	v_and_b32_e32 v15, 0xffff0000, v24
	v_fma_f32 v8, v48, v14, v8
	v_fma_f32 v9, v48, v15, v9
	v_lshlrev_b32_e32 v14, 16, v25
	v_and_b32_e32 v15, 0xffff0000, v25
	v_fma_f32 v10, v48, v14, v10
	v_fma_f32 v11, v48, v15, v11
	v_lshlrev_b32_e32 v14, 16, v54
	v_and_b32_e32 v15, 0xffff0000, v54
	v_fma_f32 v4, v48, v14, v4
	v_fma_f32 v5, v48, v15, v5
	v_lshlrev_b32_e32 v14, 16, v55
	v_and_b32_e32 v15, 0xffff0000, v55
	v_fma_f32 v6, v48, v14, v6
	v_fma_f32 v7, v48, v15, v7
	v_lshlrev_b32_e32 v14, 16, v26
	v_and_b32_e32 v15, 0xffff0000, v26
	v_fma_f32 v0, v48, v14, v0
	v_fma_f32 v1, v48, v15, v1
	v_lshlrev_b32_e32 v14, 16, v27
	v_and_b32_e32 v15, 0xffff0000, v27
	v_fma_f32 v40, v48, v56, v40
	v_fma_f32 v41, v48, v57, v41
	v_fma_f32 v2, v48, v14, v2
	v_fma_f32 v3, v48, v15, v3
	s_or_b64 exec, exec, s[2:3]
	s_and_saveexec_b64 s[2:3], s[0:1]
	s_cbranch_execz .LBB0_280
.LBB0_282:
	v_sub_f32_e32 v14, v46, v51
	s_movk_i32 s0, 0x88
	v_exp_f32_e32 v46, v14
	v_mad_u64_u32 v[14:15], s[0:1], v116, s0, v[12:13]
	v_add_u32_e32 v15, 0x8800, v14
	ds_read2_b64 v[24:27], v15 offset1:2
	ds_read2_b64 v[28:31], v15 offset0:8 offset1:10
	ds_read2_b64 v[52:55], v15 offset0:4 offset1:6
	v_mul_f32_e32 v14, v47, v46
	v_fmac_f32_e32 v13, v47, v46
	s_waitcnt lgkmcnt(2)
	v_lshlrev_b32_e32 v48, 16, v24
	v_and_b32_e32 v49, 0xffff0000, v24
	v_lshlrev_b32_e32 v24, 16, v25
	v_and_b32_e32 v25, 0xffff0000, v25
	v_fma_f32 v42, v14, v24, v42
	v_fma_f32 v43, v14, v25, v43
	s_waitcnt lgkmcnt(1)
	v_lshlrev_b32_e32 v24, 16, v28
	v_and_b32_e32 v25, 0xffff0000, v28
	v_fma_f32 v36, v14, v24, v36
	v_fma_f32 v37, v14, v25, v37
	v_lshlrev_b32_e32 v24, 16, v29
	v_and_b32_e32 v25, 0xffff0000, v29
	v_fma_f32 v38, v14, v24, v38
	v_fma_f32 v39, v14, v25, v39
	v_lshlrev_b32_e32 v24, 16, v26
	v_and_b32_e32 v25, 0xffff0000, v26
	v_fma_f32 v32, v14, v24, v32
	v_fma_f32 v33, v14, v25, v33
	v_lshlrev_b32_e32 v24, 16, v27
	v_and_b32_e32 v25, 0xffff0000, v27
	v_fma_f32 v34, v14, v24, v34
	v_fma_f32 v35, v14, v25, v35
	v_lshlrev_b32_e32 v24, 16, v30
	v_and_b32_e32 v25, 0xffff0000, v30
	v_fma_f32 v20, v14, v24, v20
	v_fma_f32 v21, v14, v25, v21
	v_lshlrev_b32_e32 v24, 16, v31
	v_and_b32_e32 v25, 0xffff0000, v31
	v_fma_f32 v22, v14, v24, v22
	v_fma_f32 v23, v14, v25, v23
	ds_read2_b64 v[24:27], v15 offset0:12 offset1:14
	s_waitcnt lgkmcnt(1)
	v_lshlrev_b32_e32 v28, 16, v52
	v_and_b32_e32 v29, 0xffff0000, v52
	v_fma_f32 v16, v14, v28, v16
	v_fma_f32 v17, v14, v29, v17
	v_lshlrev_b32_e32 v28, 16, v53
	v_and_b32_e32 v29, 0xffff0000, v53
	v_fma_f32 v18, v14, v28, v18
	v_fma_f32 v19, v14, v29, v19
	s_waitcnt lgkmcnt(0)
	v_lshlrev_b32_e32 v28, 16, v24
	v_and_b32_e32 v29, 0xffff0000, v24
	v_lshlrev_b32_e32 v24, 16, v25
	v_and_b32_e32 v25, 0xffff0000, v25
	v_fma_f32 v10, v14, v24, v10
	v_fma_f32 v11, v14, v25, v11
	v_lshlrev_b32_e32 v24, 16, v54
	v_and_b32_e32 v25, 0xffff0000, v54
	v_fma_f32 v4, v14, v24, v4
	v_fma_f32 v5, v14, v25, v5
	v_lshlrev_b32_e32 v24, 16, v55
	v_and_b32_e32 v25, 0xffff0000, v55
	v_fma_f32 v6, v14, v24, v6
	v_fma_f32 v7, v14, v25, v7
	v_lshlrev_b32_e32 v24, 16, v26
	v_and_b32_e32 v25, 0xffff0000, v26
	v_fma_f32 v0, v14, v24, v0
	v_fma_f32 v1, v14, v25, v1
	v_lshlrev_b32_e32 v24, 16, v27
	v_and_b32_e32 v25, 0xffff0000, v27
	v_fma_f32 v40, v14, v48, v40
	v_fma_f32 v41, v14, v49, v41
	v_fma_f32 v8, v14, v28, v8
	v_fma_f32 v9, v14, v29, v9
	v_fma_f32 v2, v14, v24, v2
	v_fma_f32 v3, v14, v25, v3
	s_or_b64 exec, exec, s[2:3]
	s_and_saveexec_b64 s[0:1], vcc
	s_cbranch_execz .LBB0_189
; #define LAS __attribute__((address_space(3)))
; __device__ __forceinline__ unsigned pk2(float lo, float hi) { return pg8::cvt_pk_bf16(lo, hi); }
; __device__ __forceinline__ float bflo(unsigned u) { return __uint_as_float(u << 16); }
; __device__ __forceinline__ float bfhi(unsigned u) { return __uint_as_float(u & 0xffff0000u); }
; #define WG_BAR() __syncthreads()
; __device__ __forceinline__ void attn_store(bf16* yrow, const f32x16& o0, const f32x16& o1, float inv, int hi) {
; #pragma unroll
;     for (int rg = 0; rg < 4; ++rg) {
;         u32x2 w0, w1;
;         w0.x = pk2(o0[4 * rg] * inv, o0[4 * rg + 1] * inv); w0.y = pk2(o0[4 * rg + 2] * inv, o0[4 * rg + 3] * inv);
;         w1.x = pk2(o1[4 * rg] * inv, o1[4 * rg + 1] * inv); w1.y = pk2(o1[4 * rg + 2] * inv, o1[4 * rg + 3] * inv);
;         *(u32x2*)(yrow + 8 * rg + 4 * hi) = w0; *(u32x2*)(yrow + 32 + 8 * rg + 4 * hi) = w1;
;     }
; }
; __device__ __forceinline__ void moba_unit(int b, int h, int qb, const bf16* qkv, const bf16* KF, const bf16* VF, bf16* Y, const float* kmean, LAS unsigned char* lds) {
;     ...
;         for (int j = 0; j < 3; ++j) {
;             if (j < nsel) {
;                 const float wj = lj[j] * __builtin_amdgcn_exp2f(mj[j] - M); den += wj;
;                 LAS const unsigned char* op = lds + MB_OP + (j * 256 + qloc) * MB_OPROW + 8 * hi;
; #pragma unroll
;                 for (int rg = 0; rg < 4; ++rg) {
;                     const u32x2 x0 = *(LAS const u32x2*)(op + 16 * rg), x1 = *(LAS const u32x2*)(op + 64 + 16 * rg);
;                     o0[4 * rg] += wj * bflo(x0.x); o0[4 * rg + 1] += wj * bfhi(x0.x); o0[4 * rg + 2] += wj * bflo(x0.y); o0[4 * rg + 3] += wj * bfhi(x0.y);
;                     o1[4 * rg] += wj * bflo(x1.x); o1[4 * rg + 1] += wj * bfhi(x1.x); o1[4 * rg + 2] += wj * bflo(x1.y); o1[4 * rg + 3] += wj * bfhi(x1.y); }
;             }
;         }
;         attn_store(Y + row * 1536 + 1024 + h * 64, o0, o1, 1.f / den, hi);
;     }
;     WG_BAR();
.LBB0_283:
	s_movk_i32 s2, 0x88
	v_mad_u64_u32 v[24:25], s[2:3], v116, s2, v[12:13]
	v_sub_f32_e32 v14, v44, v51
	v_add_u32_e32 v12, 0x11000, v24
	v_exp_f32_e32 v15, v14
	v_add_u32_e32 v25, 0x11040, v24
	ds_read_b64 v[26:27], v12
	ds_read_b64 v[28:29], v25
	v_add_u32_e32 v12, 0x11010, v24
	v_mul_f32_e32 v14, v45, v15
	v_fmac_f32_e32 v13, v45, v15
	s_waitcnt lgkmcnt(1)
	v_lshlrev_b32_e32 v30, 16, v26
	v_and_b32_e32 v31, 0xffff0000, v26
	v_lshlrev_b32_e32 v26, 16, v27
	v_and_b32_e32 v27, 0xffff0000, v27
	v_fma_f32 v42, v14, v26, v42
	v_fma_f32 v43, v14, v27, v43
	s_waitcnt lgkmcnt(0)
	v_lshlrev_b32_e32 v26, 16, v28
	v_and_b32_e32 v27, 0xffff0000, v28
	v_fma_f32 v36, v14, v26, v36
	v_fma_f32 v37, v14, v27, v37
	v_lshlrev_b32_e32 v26, 16, v29
	v_and_b32_e32 v27, 0xffff0000, v29
	v_fma_f32 v38, v14, v26, v38
	v_fma_f32 v39, v14, v27, v39
	ds_read_b64 v[26:27], v12
	v_add_u32_e32 v12, 0x11050, v24
	ds_read_b64 v[28:29], v12
	v_fma_f32 v40, v14, v30, v40
	v_fma_f32 v41, v14, v31, v41
	v_add_u32_e32 v12, 0x11020, v24
	s_waitcnt lgkmcnt(1)
	v_lshlrev_b32_e32 v30, 16, v26
	v_and_b32_e32 v31, 0xffff0000, v26
	v_lshlrev_b32_e32 v26, 16, v27
	v_and_b32_e32 v27, 0xffff0000, v27
	v_fma_f32 v34, v14, v26, v34
	v_fma_f32 v35, v14, v27, v35
	s_waitcnt lgkmcnt(0)
	v_lshlrev_b32_e32 v26, 16, v28
	v_and_b32_e32 v27, 0xffff0000, v28
	v_fma_f32 v20, v14, v26, v20
	v_fma_f32 v21, v14, v27, v21
	v_lshlrev_b32_e32 v26, 16, v29
	v_and_b32_e32 v27, 0xffff0000, v29
	v_fma_f32 v22, v14, v26, v22
	v_fma_f32 v23, v14, v27, v23
	ds_read_b64 v[26:27], v12
	v_add_u32_e32 v12, 0x11060, v24
	ds_read_b64 v[28:29], v12
	v_fma_f32 v32, v14, v30, v32
	v_fma_f32 v33, v14, v31, v33
	v_add_u32_e32 v12, 0x11030, v24
	s_waitcnt lgkmcnt(1)
	v_lshlrev_b32_e32 v30, 16, v26
	v_and_b32_e32 v31, 0xffff0000, v26
	v_lshlrev_b32_e32 v26, 16, v27
	v_and_b32_e32 v27, 0xffff0000, v27
	v_fma_f32 v18, v14, v26, v18
	v_fma_f32 v19, v14, v27, v19
	s_waitcnt lgkmcnt(0)
	v_lshlrev_b32_e32 v26, 16, v28
	v_and_b32_e32 v27, 0xffff0000, v28
	v_fma_f32 v8, v14, v26, v8
	v_fma_f32 v9, v14, v27, v9
	v_lshlrev_b32_e32 v26, 16, v29
	v_and_b32_e32 v27, 0xffff0000, v29
	v_fma_f32 v10, v14, v26, v10
	v_fma_f32 v11, v14, v27, v11
	ds_read_b64 v[26:27], v12
	v_add_u32_e32 v12, 0x11070, v24
	ds_read_b64 v[24:25], v12
	v_fma_f32 v16, v14, v30, v16
	v_fma_f32 v17, v14, v31, v17
	s_waitcnt lgkmcnt(1)
	v_lshlrev_b32_e32 v28, 16, v26
	v_and_b32_e32 v29, 0xffff0000, v26
	v_lshlrev_b32_e32 v26, 16, v27
	v_and_b32_e32 v27, 0xffff0000, v27
	v_fma_f32 v6, v14, v26, v6
	v_fma_f32 v7, v14, v27, v7
	s_waitcnt lgkmcnt(0)
	v_lshlrev_b32_e32 v26, 16, v24
	v_and_b32_e32 v27, 0xffff0000, v24
	v_lshlrev_b32_e32 v24, 16, v25
	v_and_b32_e32 v25, 0xffff0000, v25
	v_fma_f32 v4, v14, v28, v4
	v_fma_f32 v5, v14, v29, v5
	v_fma_f32 v0, v14, v26, v0
	v_fma_f32 v1, v14, v27, v1
	v_fma_f32 v2, v14, v24, v2
	v_fma_f32 v3, v14, v25, v3
	s_branch .LBB0_189
.LBB0_284:
	s_or_b64 exec, exec, s[0:1]
	v_readlane_b32 s0, v252, 9
	v_readlane_b32 s1, v252, 10
	s_movk_i32 s2, 0xc00
	s_lshl_b32 s46, s20, 1
	v_mov_b64_e32 v[14:15], s[0:1]
	v_mad_u64_u32 v[14:15], s[0:1], v114, s2, v[14:15]
	v_mov_b32_e32 v12, v15
	v_mad_u64_u32 v[24:25], s[0:1], v115, s2, v[12:13]
	v_div_scale_f32 v12, s[0:1], v13, v13, 1.0
	v_rcp_f32_e32 v25, v12
	v_mov_b32_e32 v15, v24
	v_lshl_add_u64 v[14:15], v[14:15], 0, s[46:47]
	v_lshl_add_u64 v[14:15], v[14:15], 0, v[64:65]
	v_fma_f32 v24, -v12, v25, 1.0
	v_fmac_f32_e32 v25, v24, v25
	v_div_scale_f32 v24, vcc, 1.0, v13, 1.0
	v_mul_f32_e32 v26, v24, v25
	v_fma_f32 v27, -v12, v26, v24
	v_fmac_f32_e32 v26, v27, v25
	v_fma_f32 v12, -v12, v26, v24
	v_div_fmas_f32 v12, v12, v25, v26
	v_div_fixup_f32 v12, v12, v13, 1.0
	v_mul_f32_e32 v24, v40, v12
	v_mul_f32_e32 v25, v41, v12
	v_mul_f32_e32 v26, v42, v12
	v_mul_f32_e32 v27, v43, v12
	v_cvt_pk_bf16_f32 v24, v24, v25
	v_cvt_pk_bf16_f32 v25, v26, v27
	v_mul_f32_e32 v26, v36, v12
	v_mul_f32_e32 v27, v37, v12
	v_mul_f32_e32 v28, v38, v12
	v_mul_f32_e32 v29, v39, v12
	v_cvt_pk_bf16_f32 v26, v26, v27
	v_cvt_pk_bf16_f32 v27, v28, v29
	v_readlane_b32 s0, v253, 51
	global_store_dwordx2 v[14:15], v[24:25], off offset:2048
	global_store_dwordx2 v[14:15], v[26:27], off offset:2112
	v_mul_f32_e32 v24, v32, v12
	v_mul_f32_e32 v25, v33, v12
	v_mul_f32_e32 v26, v34, v12
	v_mul_f32_e32 v27, v35, v12
	v_mul_f32_e32 v16, v16, v12
	v_mul_f32_e32 v17, v17, v12
	v_mul_f32_e32 v18, v18, v12
	v_mul_f32_e32 v19, v19, v12
	v_mul_f32_e32 v4, v4, v12
	v_mul_f32_e32 v5, v5, v12
	v_mul_f32_e32 v6, v6, v12
	v_mul_f32_e32 v7, v7, v12
	s_add_i32 s19, s19, s0
	s_add_i32 s18, s18, s0
	v_cvt_pk_bf16_f32 v24, v24, v25
	v_cvt_pk_bf16_f32 v25, v26, v27
	v_mul_f32_e32 v20, v20, v12
	v_mul_f32_e32 v21, v21, v12
	v_mul_f32_e32 v22, v22, v12
	v_mul_f32_e32 v23, v23, v12
	v_cvt_pk_bf16_f32 v16, v16, v17
	v_cvt_pk_bf16_f32 v17, v18, v19
	v_mul_f32_e32 v8, v8, v12
	v_mul_f32_e32 v9, v9, v12
	v_mul_f32_e32 v10, v10, v12
	v_mul_f32_e32 v11, v11, v12
	v_cvt_pk_bf16_f32 v4, v4, v5
	v_cvt_pk_bf16_f32 v5, v6, v7
	v_mul_f32_e32 v0, v0, v12
	v_mul_f32_e32 v1, v1, v12
	v_mul_f32_e32 v2, v2, v12
	v_mul_f32_e32 v3, v3, v12
	s_cmpk_lt_i32 s19, 0x800
	v_cvt_pk_bf16_f32 v20, v20, v21
	v_cvt_pk_bf16_f32 v21, v22, v23
	global_store_dwordx2 v[14:15], v[24:25], off offset:2064
	global_store_dwordx2 v[14:15], v[20:21], off offset:2128
	v_cvt_pk_bf16_f32 v8, v8, v9
	v_cvt_pk_bf16_f32 v9, v10, v11
	global_store_dwordx2 v[14:15], v[16:17], off offset:2080
	global_store_dwordx2 v[14:15], v[8:9], off offset:2144
	v_cvt_pk_bf16_f32 v0, v0, v1
	v_cvt_pk_bf16_f32 v1, v2, v3
	global_store_dwordx2 v[14:15], v[4:5], off offset:2096
	global_store_dwordx2 v[14:15], v[0:1], off offset:2160
	s_barrier
	v_readlane_b32 s1, v253, 52
	s_cbranch_scc0 .LBB0_186

; #define LAS __attribute__((address_space(3)))
; __device__ __forceinline__ float bflo(unsigned u) { return __uint_as_float(u << 16); }
; __device__ __forceinline__ float bfhi(unsigned u) { return __uint_as_float(u & 0xffff0000u); }
; __device__ __forceinline__ void moba_unit(int b, int h, int qb, const bf16* qkv, const bf16* KF, const bf16* VF, bf16* Y, const float* kmean, LAS unsigned char* lds) {
;     ...
;         for (int n = 0; n < qb; ++n) {
;             float part = 0.f;
; #pragma unroll
;             for (int d0 = 0; d0 < 4; ++d0) {
;                 const f32x4 ka = *(LAS const f32x4*)(KM + n * 64 + 16 * d0 + 8 * hi), kb = *(LAS const f32x4*)(KM + n * 64 + 16 * d0 + 8 * hi + 4);
;                 const u32x4 q = __builtin_bit_cast(u32x4, qf[d0]);
;                 part += bflo(q.x) * ka.x + bfhi(q.x) * ka.y + bflo(q.y) * ka.z + bfhi(q.y) * ka.w + bflo(q.z) * kb.x + bfhi(q.z) * kb.y + bflo(q.w) * kb.z + bfhi(q.w) * kb.w;
;             }
;             const float g = part + __shfl_xor(part, 32);
;             if (g > v1) { v3 = v2; i3 = i2; v2 = v1; i2 = i1; v1 = g; i1 = n; }
;             else if (g > v2) { v3 = v2; i3 = i2; v2 = g; i2 = n; }
;             else if (g > v3) { v3 = g; i3 = n; }
;         }
.LBB0_292:
	ds_read_b128 v[42:45], v36
	ds_read_b128 v[46:49], v36 offset:64
	ds_read_b128 v[50:53], v36 offset:16
	ds_read_b128 v[54:57], v36 offset:80
	s_waitcnt lgkmcnt(3)
	v_mov_b32_e32 v58, v42
	s_waitcnt lgkmcnt(2)
	v_mov_b32_e32 v59, v46
	v_mov_b32_e32 v46, v43
	v_mul_f32_e32 v42, v46, v18
	v_mul_f32_e32 v43, v47, v19
	v_mov_b32_e32 v46, v44
	v_fma_f32 v42, v58, v16, v42
	v_fma_f32 v43, v59, v17, v43
	v_mov_b32_e32 v47, v48
	v_fma_f32 v42, v46, v20, v42
	v_fma_f32 v43, v47, v21, v43
	v_mov_b32_e32 v48, v45
	v_fma_f32 v42, v48, v12, v42
	v_fma_f32 v43, v49, v13, v43
	s_waitcnt lgkmcnt(1)
	v_mov_b32_e32 v44, v50
	s_waitcnt lgkmcnt(0)
	v_mov_b32_e32 v45, v54
	v_fma_f32 v42, v44, v8, v42
	v_fma_f32 v43, v45, v9, v43
	v_mov_b32_e32 v54, v51
	v_fma_f32 v42, v54, v22, v42
	v_fma_f32 v43, v55, v23, v43
	v_mov_b32_e32 v44, v52
	v_mov_b32_e32 v45, v56
	v_fma_f32 v42, v44, v24, v42
	v_fma_f32 v43, v45, v25, v43
	v_mov_b32_e32 v56, v53
	v_fma_f32 v50, v56, v14, v42
	v_fma_f32 v51, v57, v15, v43
	ds_read_b128 v[42:45], v36 offset:128
	ds_read_b128 v[46:49], v36 offset:192
	v_add_f32_e32 v50, 0, v50
	v_add_f32_e32 v60, v50, v51
	ds_read_b128 v[50:53], v36 offset:144
	ds_read_b128 v[54:57], v36 offset:208
	s_waitcnt lgkmcnt(3)
	v_mov_b32_e32 v58, v42
	s_waitcnt lgkmcnt(2)
	v_mov_b32_e32 v59, v46
	v_mov_b32_e32 v46, v43
	v_mul_f32_e32 v42, v46, v26
	v_mul_f32_e32 v43, v47, v27
	v_mov_b32_e32 v46, v44
	v_fma_f32 v42, v58, v10, v42
	v_fma_f32 v43, v59, v11, v43
	v_mov_b32_e32 v47, v48
	v_fma_f32 v42, v46, v28, v42
	v_fma_f32 v43, v47, v29, v43
	v_mov_b32_e32 v48, v45
	v_fma_f32 v42, v48, v4, v42
	v_fma_f32 v43, v49, v5, v43
	s_waitcnt lgkmcnt(1)
	v_mov_b32_e32 v44, v50
	s_waitcnt lgkmcnt(0)
	v_mov_b32_e32 v45, v54
	v_fma_f32 v42, v44, v0, v42
	v_fma_f32 v43, v45, v1, v43
	v_mov_b32_e32 v54, v51
	v_fma_f32 v42, v54, v30, v42
	v_fma_f32 v43, v55, v31, v43
	v_mov_b32_e32 v44, v52
	v_mov_b32_e32 v45, v56
	v_fma_f32 v42, v44, v32, v42
	v_fma_f32 v43, v45, v33, v43
	v_mov_b32_e32 v56, v53
	v_fma_f32 v42, v56, v6, v42
	v_fma_f32 v43, v57, v7, v43
	v_mov_b32_e32 v45, v3
	v_add_f32_e32 v42, v60, v42
	v_add_f32_e32 v42, v42, v43
	ds_bpermute_b32 v43, v37, v42
	s_waitcnt lgkmcnt(0)
	v_add_f32_e32 v44, v42, v43
	v_cmp_ngt_f32_e32 vcc, v44, v3
	v_mov_b32_e32 v43, s12
	v_mov_b32_e32 v42, v38
	s_and_saveexec_b64 s[0:1], vcc
	s_cbranch_execz .LBB0_298
	v_cmp_ngt_f32_e32 vcc, v44, v39
	v_mov_b32_e32 v42, s12
	s_and_saveexec_b64 s[8:9], vcc
	s_cbranch_execz .LBB0_297
	v_cmp_gt_f32_e32 vcc, v44, v41
	s_and_saveexec_b64 s[10:11], vcc
	v_mov_b32_e32 v2, s12
	v_mov_b32_e32 v41, v44
	s_or_b64 exec, exec, s[10:11]
	v_mov_b32_e32 v44, v39
	v_mov_b32_e32 v39, v41
	v_mov_b32_e32 v42, v40
	v_mov_b32_e32 v40, v2

; #define SB_() __builtin_amdgcn_sched_barrier(0)
; __device__ __forceinline__ void tile_qk_fast(const KFr& f, const bf16x8 (&qf)[4], const bf16x8& kx0, const bf16x8& kx1, const bf16x8& qx, u32x4 (&pw)[4],
;                                              f32x16& o0, f32x16& o1, float& m, float& l, float off) {
;     f32x16 p0, p1;
; #pragma unroll
;     for (int r = 0; r < 16; ++r) { p0[r] = 0.f; p1[r] = 0.f; }
;     p0 = __builtin_amdgcn_mfma_f32_32x32x16_bf16(kx0, qx, p0, 0, 0, 0);
;     p1 = __builtin_amdgcn_mfma_f32_32x32x16_bf16(kx1, qx, p1, 0, 0, 0);
; #pragma unroll
;     for (int d0 = 0; d0 < 4; ++d0) {
;         p0 = __builtin_amdgcn_mfma_f32_32x32x16_bf16(f.a[0][d0], qf[d0], p0, 0, 0, 0);
;         p1 = __builtin_amdgcn_mfma_f32_32x32x16_bf16(f.a[1][d0], qf[d0], p1, 0, 0, 0);
;     }
;     constexpr float C2 = 0.125f * LOG2E;
;     float mr = fmaxf(p0[0], p1[0]);
; #pragma unroll
;     for (int r = 1; r < 16; ++r) mr = fmaxf(fmaxf(mr, p0[r]), p1[r]);
;     float mx = fmaf(mr, C2, off);
;     mx = fmaxf(mx, __shfl_xor(mx, 32));
;     const float mn = fmaxf(m, mx);
;     if (__ballot(mn > m) != 0ull) {
;         const float alpha = __builtin_amdgcn_exp2f(m - mn); l *= alpha;
; #pragma unroll
;         for (int r = 0; r < 16; ++r) { o0[r] *= alpha; o1[r] *= alpha; }
;     }
;     m = mn;
;     const float sh = off - mn;
;     float rs = 0.f;
; #pragma unroll
;     for (int r = 0; r < 16; ++r) { p0[r] = __builtin_amdgcn_exp2f(fmaf(p0[r], C2, sh)); p1[r] = __builtin_amdgcn_exp2f(fmaf(p1[r], C2, sh)); rs += p0[r] + p1[r]; }
; __device__ __forceinline__ void moba_unit(int b, int h, int qb, const bf16* qkv, const bf16* KF, const bf16* VF, bf16* Y, const float* kmean, LAS unsigned char* lds) {
;     ...
;             vp = (const char*)VFh + (size_t)(4 * n_c) * 8192 + lane * 16; asm volatile("" : "+v"(vp));
;             float m2 = -1e30f, l2 = 0.f; f32x16 a0, a1;
; #pragma unroll
;             for (int r = 0; r < 16; ++r) { a0[r] = 0.f; a1[r] = 0.f; }
;             const int kq0 = 256 * n_c - (256 * qb + q2_c);
;             TASK_ADV();
;             loadV(v0, vp); SB_();
;             loadK(k1, kp); SB_(); tile_qk_fast(k0, qg, kx0, kx1, qx, pw, a0, a1, m2, l2, sl2 * (float)(kq0)); SB_();
.LBB0_349:
	global_load_dwordx4 v[162:165], v[0:1], off
	global_load_dwordx4 v[154:157], v[0:1], off offset:1024
	global_load_dwordx4 v[146:149], v[0:1], off offset:2048
	global_load_dwordx4 v[142:145], v[0:1], off offset:3072
	v_lshl_add_u64 v[0:1], v[0:1], 0, s[56:57]
	global_load_dwordx4 v[170:173], v[0:1], off
	global_load_dwordx4 v[166:169], v[0:1], off offset:1024
	global_load_dwordx4 v[158:161], v[0:1], off offset:2048
	global_load_dwordx4 v[150:153], v[0:1], off offset:3072
	s_sub_i32 s2, s27, s21
	s_lshl_b32 s2, s2, 8
	v_sub_u32_e32 v236, s2, v234
	v_lshl_add_u64 v[216:217], v[0:1], 0, s[56:57]
	v_lshl_add_u64 v[0:1], v[214:215], 0, s[56:57]
	global_load_dwordx4 v[194:197], v[214:215], off
	global_load_dwordx4 v[186:189], v[214:215], off offset:1024
	global_load_dwordx4 v[182:185], v[214:215], off offset:2048
	global_load_dwordx4 v[174:177], v[214:215], off offset:3072
	global_load_dwordx4 v[202:205], v[0:1], off
	global_load_dwordx4 v[198:201], v[0:1], off offset:1024
	global_load_dwordx4 v[190:193], v[0:1], off offset:2048
	global_load_dwordx4 v[178:181], v[0:1], off offset:3072
	v_lshl_add_u64 v[218:219], v[0:1], 0, s[56:57]
	v_mfma_f32_32x32x16_bf16 v[48:63], v[70:73], v[66:69], 0
	v_cvt_f32_i32_e32 v64, v236
	s_mov_b32 s2, 0xf149f2ca
	s_waitcnt lgkmcnt(0)
	v_mfma_f32_32x32x16_bf16 v[32:47], v[74:77], v[66:69], 0
	s_waitcnt lgkmcnt(0)
	v_mfma_f32_32x32x16_bf16 v[16:31], v[106:109], v[138:141], v[48:63]
	v_mfma_f32_32x32x16_bf16 v[0:15], v[122:125], v[138:141], v[32:47]
	v_mfma_f32_32x32x16_bf16 v[16:31], v[102:105], v[134:137], v[16:31]
	v_mfma_f32_32x32x16_bf16 v[0:15], v[118:121], v[134:137], v[0:15]
	v_mfma_f32_32x32x16_bf16 v[16:31], v[98:101], v[130:133], v[16:31]
	v_mul_f32_e32 v98, v230, v64
	v_mfma_f32_32x32x16_bf16 v[0:15], v[114:117], v[130:133], v[0:15]
	v_mfma_f32_32x32x16_bf16 v[0:15], v[110:113], v[126:129], v[0:15]
	v_mfma_f32_32x32x16_bf16 v[16:31], v[94:97], v[126:129], v[16:31]
	s_nop 10
	v_max_f32_e32 v99, v0, v0
	v_max_f32_e32 v94, v16, v16
	v_max_f32_e32 v94, v94, v99
	v_max3_f32 v94, v94, v17, v1
	v_max3_f32 v94, v94, v18, v2
	v_max3_f32 v94, v94, v19, v3
	v_max3_f32 v94, v94, v20, v4
	v_max3_f32 v94, v94, v21, v5
	v_max3_f32 v94, v94, v22, v6
	v_max3_f32 v94, v94, v23, v7
	v_max3_f32 v94, v94, v24, v8
	v_max3_f32 v94, v94, v25, v9
	v_max3_f32 v94, v94, v26, v10
	v_max3_f32 v94, v94, v27, v11
	v_max3_f32 v94, v94, v28, v12
	v_max3_f32 v94, v94, v29, v13
	v_max3_f32 v94, v94, v30, v14
	v_max3_f32 v94, v94, v31, v15
	v_fmac_f32_e32 v98, 0x3e38aa3b, v94
	v_mbcnt_hi_u32_b32 v94, -1, v220
	v_and_b32_e32 v96, 64, v94
	v_xor_b32_e32 v95, 32, v94
	v_add_u32_e32 v96, 64, v96
	v_cmp_lt_i32_e32 vcc, v95, v96
	s_nop 1
	v_cndmask_b32_e32 v94, v94, v95, vcc
	v_lshlrev_b32_e32 v235, 2, v94
	ds_bpermute_b32 v94, v235, v98
	s_waitcnt lgkmcnt(0)
	v_max3_f32 v238, v98, v94, s2
	v_fma_f32 v110, v230, v64, -v238
	v_fmamk_f32 v0, v0, 0x3e38aa3b, v110
	v_sub_f32_e32 v94, 0xf149f2ca, v238
	v_fmamk_f32 v16, v16, 0x3e38aa3b, v110
	v_exp_f32_e32 v112, v0
	v_fmamk_f32 v0, v17, 0x3e38aa3b, v110
	v_exp_f32_e32 v94, v94
	v_exp_f32_e32 v111, v16
	v_exp_f32_e32 v64, v0
	v_fmamk_f32 v0, v1, 0x3e38aa3b, v110
	v_exp_f32_e32 v16, v0
	v_cmp_lt_f32_e32 vcc, s2, v238
	s_cmp_lg_u64 vcc, 0
	v_mul_f32_e32 v94, 0, v94
	s_cselect_b64 vcc, -1, 0
	v_add_f32_e32 v17, v112, v111
	v_cndmask_b32_e32 v0, 0, v94, vcc
	v_add_f32_e32 v94, v16, v64
	v_add_f32_e32 v95, v17, v65
	v_fmamk_f32 v2, v2, 0x3e38aa3b, v110
	v_add_f32_e32 v96, v94, v94
	v_add_f32_e32 v97, v94, v95
	v_fmamk_f32 v17, v18, 0x3e38aa3b, v110
	v_exp_f32_e32 v113, v2
	v_fmamk_f32 v2, v19, 0x3e38aa3b, v110
	v_exp_f32_e32 v17, v17
	v_exp_f32_e32 v96, v2
	v_fmamk_f32 v2, v3, 0x3e38aa3b, v110
	v_exp_f32_e32 v18, v2
	v_add_f32_e32 v19, v113, v17
	v_fmamk_f32 v4, v4, 0x3e38aa3b, v110
	v_exp_f32_e32 v114, v4
	v_add_f32_e32 v94, v18, v96
	v_add_f32_e32 v95, v19, v97
	v_fmamk_f32 v19, v20, 0x3e38aa3b, v110
	v_add_f32_e32 v98, v94, v94
	v_add_f32_e32 v99, v94, v95
	v_exp_f32_e32 v19, v19
	v_fmamk_f32 v4, v21, 0x3e38aa3b, v110
	v_fmamk_f32 v5, v5, 0x3e38aa3b, v110
	v_exp_f32_e32 v98, v4
	v_exp_f32_e32 v20, v5
	v_add_f32_e32 v21, v114, v19
	v_fmamk_f32 v6, v6, 0x3e38aa3b, v110
	v_exp_f32_e32 v115, v6
	v_add_f32_e32 v94, v20, v98
	v_add_f32_e32 v95, v21, v99
	v_fmamk_f32 v21, v22, 0x3e38aa3b, v110
	v_add_f32_e32 v100, v94, v94
	v_add_f32_e32 v101, v94, v95
	v_fmamk_f32 v6, v23, 0x3e38aa3b, v110
	v_exp_f32_e32 v21, v21
	v_exp_f32_e32 v100, v6
	v_fmamk_f32 v6, v7, 0x3e38aa3b, v110
	v_exp_f32_e32 v22, v6
	v_add_f32_e32 v23, v115, v21
	v_fmamk_f32 v8, v8, 0x3e38aa3b, v110
	v_exp_f32_e32 v116, v8
	v_add_f32_e32 v94, v22, v100
	v_add_f32_e32 v95, v23, v101
	v_fmamk_f32 v23, v24, 0x3e38aa3b, v110
	v_add_f32_e32 v102, v94, v94
	v_add_f32_e32 v103, v94, v95
	v_fmamk_f32 v8, v25, 0x3e38aa3b, v110
	v_exp_f32_e32 v23, v23
	v_exp_f32_e32 v102, v8
	v_fmamk_f32 v8, v9, 0x3e38aa3b, v110
	v_exp_f32_e32 v24, v8
	v_add_f32_e32 v25, v116, v23
	v_fmamk_f32 v10, v10, 0x3e38aa3b, v110
	v_exp_f32_e32 v117, v10
	v_add_f32_e32 v94, v24, v102
	v_add_f32_e32 v95, v25, v103
	v_fmamk_f32 v25, v26, 0x3e38aa3b, v110
	v_add_f32_e32 v104, v94, v94
	v_add_f32_e32 v105, v94, v95
	v_fmamk_f32 v10, v27, 0x3e38aa3b, v110
	v_exp_f32_e32 v25, v25
	v_exp_f32_e32 v104, v10
	v_fmamk_f32 v10, v11, 0x3e38aa3b, v110
	v_exp_f32_e32 v26, v10
	v_add_f32_e32 v27, v117, v25
	v_fmamk_f32 v12, v12, 0x3e38aa3b, v110
	v_exp_f32_e32 v118, v12
	v_add_f32_e32 v94, v26, v104
	v_add_f32_e32 v95, v27, v105
	v_fmamk_f32 v27, v28, 0x3e38aa3b, v110
	v_add_f32_e32 v106, v94, v94
	v_add_f32_e32 v107, v94, v95
	v_fmamk_f32 v12, v29, 0x3e38aa3b, v110
	v_exp_f32_e32 v27, v27
; __device__ __forceinline__ unsigned pk2(float lo, float hi) { return pg8::cvt_pk_bf16(lo, hi); }
; __device__ __forceinline__ void tile_qk_fast(const KFr& f, const bf16x8 (&qf)[4], const bf16x8& kx0, const bf16x8& kx1, const bf16x8& qx, u32x4 (&pw)[4],
;                                              f32x16& o0, f32x16& o1, float& m, float& l, float off) {
;     ...
;     float mr = fmaxf(p0[0], p1[0]);
; #pragma unroll
;     for (int r = 1; r < 16; ++r) mr = fmaxf(fmaxf(mr, p0[r]), p1[r]);
;     float mx = fmaf(mr, C2, off);
;     mx = fmaxf(mx, __shfl_xor(mx, 32));
;     const float mn = fmaxf(m, mx);
;     if (__ballot(mn > m) != 0ull) {
;         const float alpha = __builtin_amdgcn_exp2f(m - mn); l *= alpha;
; #pragma unroll
;         for (int r = 0; r < 16; ++r) { o0[r] *= alpha; o1[r] *= alpha; }
;     }
;     m = mn;
;     const float sh = off - mn;
;     float rs = 0.f;
; #pragma unroll
;     for (int r = 0; r < 16; ++r) { p0[r] = __builtin_amdgcn_exp2f(fmaf(p0[r], C2, sh)); p1[r] = __builtin_amdgcn_exp2f(fmaf(p1[r], C2, sh)); rs += p0[r] + p1[r]; }
;     l += rs;
;     pw[0] = (u32x4){pk2(p0[0], p0[1]), pk2(p0[2], p0[3]), pk2(p0[4], p0[5]), pk2(p0[6], p0[7])};
;     pw[1] = (u32x4){pk2(p0[8], p0[9]), pk2(p0[10], p0[11]), pk2(p0[12], p0[13]), pk2(p0[14], p0[15])};
;     pw[2] = (u32x4){pk2(p1[0], p1[1]), pk2(p1[2], p1[3]), pk2(p1[4], p1[5]), pk2(p1[6], p1[7])};
;     pw[3] = (u32x4){pk2(p1[8], p1[9]), pk2(p1[10], p1[11]), pk2(p1[12], p1[13]), pk2(p1[14], p1[15])};
; }
; __device__ __forceinline__ void tile_pv(const VFr& f, const u32x4 (&pw)[4], f32x16& o0, f32x16& o1) {
; #pragma unroll
;     for (int ks = 0; ks < 4; ++ks) {
;         const bf16x8 P = __builtin_bit_cast(bf16x8, pw[ks]);
;         o0 = __builtin_amdgcn_mfma_f32_32x32x16_bf16(f.a[0][ks], P, o0, 0, 0, 0);
;         o1 = __builtin_amdgcn_mfma_f32_32x32x16_bf16(f.a[1][ks], P, o1, 0, 0, 0);
;     }
; }
; __device__ __forceinline__ void moba_unit(int b, int h, int qb, const bf16* qkv, const bf16* KF, const bf16* VF, bf16* Y, const float* kmean, LAS unsigned char* lds) {
;     ...
;             loadK(k1, kp); SB_(); tile_qk_fast(k0, qg, kx0, kx1, qx, pw, a0, a1, m2, l2, sl2 * (float)(kq0)); SB_();
;             tile_pv(v0, pw, a0, a1); SB_();
;             loadV(v0, vp); loadK(k0, kp); SB_(); tile_qk_fast(k1, qg, kx0, kx1, qx, pw, a0, a1, m2, l2, sl2 * (float)(kq0 + 64)); SB_();
	v_exp_f32_e32 v106, v12
	v_fmamk_f32 v12, v13, 0x3e38aa3b, v110
	v_exp_f32_e32 v28, v12
	v_add_f32_e32 v29, v118, v27
	v_fmamk_f32 v14, v14, 0x3e38aa3b, v110
	v_exp_f32_e32 v119, v14
	v_add_f32_e32 v94, v28, v106
	v_add_f32_e32 v95, v29, v107
	v_fmamk_f32 v29, v30, 0x3e38aa3b, v110
	v_add_f32_e32 v108, v94, v94
	v_add_f32_e32 v109, v94, v95
	v_exp_f32_e32 v29, v29
	v_fmamk_f32 v14, v31, 0x3e38aa3b, v110
	v_fmac_f32_e32 v110, 0x3e38aa3b, v15
	v_exp_f32_e32 v108, v14
	v_exp_f32_e32 v30, v110
	v_add_f32_e32 v31, v119, v29
	v_mov_b32_e32 v1, v0
	v_mov_b32_e32 v2, v0
	v_add_f32_e32 v94, v30, v108
	v_add_f32_e32 v95, v31, v109
	v_mov_b32_e32 v3, v0
	v_add_f32_e32 v31, v94, v95
	v_mov_b32_e32 v4, v0
	v_mov_b32_e32 v5, v0
	v_mov_b32_e32 v6, v0
	v_mov_b32_e32 v7, v0
	v_mov_b32_e32 v8, v0
	v_mov_b32_e32 v9, v0
	v_mov_b32_e32 v10, v0
	v_mov_b32_e32 v11, v0
	v_mov_b32_e32 v12, v0
	v_mov_b32_e32 v13, v0
	v_mov_b32_e32 v14, v0
	v_mov_b32_e32 v15, v0
	v_add_f32_e32 v237, v0, v31
	v_cvt_pk_bf16_f32 v94, v111, v64
	v_cvt_pk_bf16_f32 v95, v17, v96
	v_cvt_pk_bf16_f32 v96, v19, v98
	v_cvt_pk_bf16_f32 v97, v21, v100
	v_cvt_pk_bf16_f32 v98, v23, v102
	v_cvt_pk_bf16_f32 v99, v25, v104
	v_cvt_pk_bf16_f32 v100, v27, v106
	v_cvt_pk_bf16_f32 v101, v29, v108
	v_cvt_pk_bf16_f32 v102, v112, v16
	v_cvt_pk_bf16_f32 v103, v113, v18
	v_cvt_pk_bf16_f32 v104, v114, v20
	v_cvt_pk_bf16_f32 v105, v115, v22
	v_cvt_pk_bf16_f32 v106, v116, v24
	v_cvt_pk_bf16_f32 v107, v117, v26
	v_cvt_pk_bf16_f32 v108, v118, v28
	v_cvt_pk_bf16_f32 v109, v119, v30
	s_waitcnt vmcnt(0)
	v_mfma_f32_32x32x16_bf16 v[16:31], v[162:165], v[94:97], v[0:15]
	v_mfma_f32_32x32x16_bf16 v[0:15], v[170:173], v[94:97], v[0:15]
	v_mfma_f32_32x32x16_bf16 v[16:31], v[154:157], v[98:101], v[16:31]
	v_mfma_f32_32x32x16_bf16 v[0:15], v[166:169], v[98:101], v[0:15]
	v_mfma_f32_32x32x16_bf16 v[16:31], v[146:149], v[102:105], v[16:31]
	v_mfma_f32_32x32x16_bf16 v[0:15], v[158:161], v[102:105], v[0:15]
	v_mfma_f32_32x32x16_bf16 v[16:31], v[142:145], v[106:109], v[16:31]
	v_mfma_f32_32x32x16_bf16 v[0:15], v[150:153], v[106:109], v[0:15]
	v_lshl_add_u64 v[94:95], v[216:217], 0, s[56:57]
	global_load_dwordx4 v[162:165], v[216:217], off
	global_load_dwordx4 v[154:157], v[216:217], off offset:1024
	global_load_dwordx4 v[146:149], v[216:217], off offset:2048
	global_load_dwordx4 v[142:145], v[216:217], off offset:3072
	v_lshl_add_u64 v[216:217], v[218:219], 0, s[56:57]
	v_lshl_add_u64 v[214:215], v[94:95], 0, s[56:57]
	global_load_dwordx4 v[170:173], v[94:95], off
	global_load_dwordx4 v[166:169], v[94:95], off offset:1024
	global_load_dwordx4 v[158:161], v[94:95], off offset:2048
	global_load_dwordx4 v[150:153], v[94:95], off offset:3072
	global_load_dwordx4 v[106:109], v[218:219], off
	global_load_dwordx4 v[102:105], v[218:219], off offset:1024
	global_load_dwordx4 v[98:101], v[218:219], off offset:2048
	global_load_dwordx4 v[94:97], v[218:219], off offset:3072
	global_load_dwordx4 v[122:125], v[216:217], off
	global_load_dwordx4 v[118:121], v[216:217], off offset:1024
	global_load_dwordx4 v[114:117], v[216:217], off offset:2048
	global_load_dwordx4 v[110:113], v[216:217], off offset:3072
	v_lshl_add_u64 v[216:217], v[216:217], 0, s[56:57]
	v_mfma_f32_32x32x16_bf16 v[48:63], v[194:197], v[138:141], v[48:63]
	v_add_u32_e32 v64, 64, v236
	v_cvt_f32_i32_e32 v64, v64
	v_mul_f32_e32 v64, v230, v64
	v_mfma_f32_32x32x16_bf16 v[32:47], v[202:205], v[138:141], v[32:47]
	v_mfma_f32_32x32x16_bf16 v[48:63], v[186:189], v[134:137], v[48:63]
	v_mfma_f32_32x32x16_bf16 v[32:47], v[198:201], v[134:137], v[32:47]
	v_mfma_f32_32x32x16_bf16 v[48:63], v[182:185], v[130:133], v[48:63]
	v_mfma_f32_32x32x16_bf16 v[32:47], v[190:193], v[130:133], v[32:47]
	v_mfma_f32_32x32x16_bf16 v[48:63], v[174:177], v[126:129], v[48:63]
	v_mfma_f32_32x32x16_bf16 v[32:47], v[178:181], v[126:129], v[32:47]
	s_nop 10
	v_max_f32_e32 v174, v48, v48
	v_max_f32_e32 v175, v32, v32
	v_max_f32_e32 v174, v174, v175
	v_max3_f32 v174, v174, v49, v33
	v_max3_f32 v174, v174, v50, v34
	v_max3_f32 v174, v174, v51, v35
	v_max3_f32 v174, v174, v52, v36
	v_max3_f32 v174, v174, v53, v37
	v_max3_f32 v174, v174, v54, v38
	v_max3_f32 v174, v174, v55, v39
	v_max3_f32 v174, v174, v56, v40
	v_max3_f32 v174, v174, v57, v41
	v_max3_f32 v174, v174, v58, v42
	v_max3_f32 v174, v174, v59, v43
	v_max3_f32 v174, v174, v60, v44
	v_max3_f32 v174, v174, v61, v45
	v_max3_f32 v174, v174, v62, v46
	v_max3_f32 v174, v174, v63, v47
	v_fmamk_f32 v174, v174, 0x3e38aa3b, v64
	ds_bpermute_b32 v175, v235, v174
	s_waitcnt lgkmcnt(0)
	v_max3_f32 v213, v238, v174, v175
	v_cmp_gt_f32_e32 vcc, v213, v238
	s_cbranch_vccz .LBB0_351
	v_sub_f32_e32 v174, v238, v213
	v_exp_f32_e32 v174, v174
	s_nop 0
	v_mul_f32_e32 v237, v237, v174
	v_mul_f32_e32 v30, v30, v174
	v_mul_f32_e32 v31, v31, v174
	v_mul_f32_e32 v28, v28, v174
	v_mul_f32_e32 v29, v29, v174
	v_mul_f32_e32 v26, v26, v174
	v_mul_f32_e32 v27, v27, v174
	v_mul_f32_e32 v24, v24, v174
	v_mul_f32_e32 v25, v25, v174
	v_mul_f32_e32 v22, v22, v174
	v_mul_f32_e32 v23, v23, v174
	v_mul_f32_e32 v20, v20, v174
	v_mul_f32_e32 v21, v21, v174
	v_mul_f32_e32 v18, v18, v174
	v_mul_f32_e32 v19, v19, v174
	v_mul_f32_e32 v16, v16, v174
	v_mul_f32_e32 v17, v17, v174
	v_mul_f32_e32 v14, v14, v174
	v_mul_f32_e32 v15, v15, v174
	v_mul_f32_e32 v12, v12, v174
	v_mul_f32_e32 v13, v13, v174
	v_mul_f32_e32 v10, v10, v174
	v_mul_f32_e32 v11, v11, v174
	v_mul_f32_e32 v8, v8, v174
	v_mul_f32_e32 v9, v9, v174
	v_mul_f32_e32 v6, v6, v174
	v_mul_f32_e32 v7, v7, v174
	v_mul_f32_e32 v4, v4, v174
	v_mul_f32_e32 v5, v5, v174
	v_mul_f32_e32 v2, v2, v174
	v_mul_f32_e32 v3, v3, v174
	v_mul_f32_e32 v0, v0, v174
	v_mul_f32_e32 v1, v1, v174

; #define LAS __attribute__((address_space(3)))
; __device__ __forceinline__ unsigned pk2(float lo, float hi) { return pg8::cvt_pk_bf16(lo, hi); }
; __device__ __forceinline__ void tile_qk_fast(const KFr& f, const bf16x8 (&qf)[4], const bf16x8& kx0, const bf16x8& kx1, const bf16x8& qx, u32x4 (&pw)[4],
;                                              f32x16& o0, f32x16& o1, float& m, float& l, float off) {
;     ...
;     const float sh = off - mn;
;     float rs = 0.f;
; #pragma unroll
;     for (int r = 0; r < 16; ++r) { p0[r] = __builtin_amdgcn_exp2f(fmaf(p0[r], C2, sh)); p1[r] = __builtin_amdgcn_exp2f(fmaf(p1[r], C2, sh)); rs += p0[r] + p1[r]; }
;     l += rs;
;     pw[0] = (u32x4){pk2(p0[0], p0[1]), pk2(p0[2], p0[3]), pk2(p0[4], p0[5]), pk2(p0[6], p0[7])};
;     pw[1] = (u32x4){pk2(p0[8], p0[9]), pk2(p0[10], p0[11]), pk2(p0[12], p0[13]), pk2(p0[14], p0[15])};
;     pw[2] = (u32x4){pk2(p1[0], p1[1]), pk2(p1[2], p1[3]), pk2(p1[4], p1[5]), pk2(p1[6], p1[7])};
;     pw[3] = (u32x4){pk2(p1[8], p1[9]), pk2(p1[10], p1[11]), pk2(p1[12], p1[13]), pk2(p1[14], p1[15])};
; __device__ __forceinline__ void moba_unit(int b, int h, int qb, const bf16* qkv, const bf16* KF, const bf16* VF, bf16* Y, const float* kmean, LAS unsigned char* lds) {
;     ...
;             loadV(v0, vp);
;             if (have) { TASK_Q(q2n, validn, qn); kp = (const char*)KFh + (size_t)(4 * n) * 8192 + lane * 16; asm volatile("" : "+v"(kp)); loadK(k0, kp); }
;             SB_(); tile_qk_fast(k1, qg, kx0, kx1, qx, pw, a0, a1, m2, l2, sl2 * (float)(kq0 + 192)); SB_();
;             tile_pv(v0, pw, a0, a1);
;             const float l2t = l2 + __shfl_xor(l2, 32), inv = 1.f / l2t;
;             if (valid_c) {
;                 const unsigned sm = SEL[q2_c]; const int slot = __builtin_popcount(sm & ((1u << n_c) - 1u));
;                 LAS unsigned char* op = lds + MB_OP + (slot * 256 + q2_c) * MB_OPROW + 8 * hi;
; #pragma unroll
;                 for (int rg = 0; rg < 4; ++rg) {
;                     *(LAS u32x2*)(op + 16 * rg) = (u32x2){pk2(a0[4 * rg] * inv, a0[4 * rg + 1] * inv), pk2(a0[4 * rg + 2] * inv, a0[4 * rg + 3] * inv)};
;                     *(LAS u32x2*)(op + 64 + 16 * rg) = (u32x2){pk2(a1[4 * rg] * inv, a1[4 * rg + 1] * inv), pk2(a1[4 * rg + 2] * inv, a1[4 * rg + 3] * inv)}; }
;                 if (hi == 0) *(LAS f32x2v*)(lds + MB_ML + (slot * 256 + q2_c) * 8) = (f32x2v){m2, l2t};
;             }
.LBB0_358:
	v_sub_f32_e32 v64, v130, v126
	v_fmamk_f32 v32, v32, 0x3e38aa3b, v64
	v_fmamk_f32 v48, v48, 0x3e38aa3b, v64
	v_exp_f32_e32 v127, v32
	v_fmamk_f32 v32, v49, 0x3e38aa3b, v64
	v_exp_f32_e32 v48, v48
	v_exp_f32_e32 v49, v32
	v_fmamk_f32 v32, v33, 0x3e38aa3b, v64
	v_exp_f32_e32 v33, v32
	v_fmamk_f32 v34, v34, 0x3e38aa3b, v64
	v_exp_f32_e32 v129, v34
	v_fmamk_f32 v34, v51, 0x3e38aa3b, v64
	v_add_f32_e32 v32, v127, v48
	v_exp_f32_e32 v51, v34
	v_fmamk_f32 v34, v35, 0x3e38aa3b, v64
	v_fmamk_f32 v35, v52, 0x3e38aa3b, v64
	v_add_f32_e32 v32, 0, v32
	v_add_f32_e32 v128, v33, v49
	v_exp_f32_e32 v52, v35
	v_fmamk_f32 v35, v36, 0x3e38aa3b, v64
	v_add_f32_e32 v32, v128, v32
	v_exp_f32_e32 v128, v35
	v_fmamk_f32 v35, v53, 0x3e38aa3b, v64
	v_exp_f32_e32 v36, v35
	v_fmamk_f32 v35, v37, 0x3e38aa3b, v64
	v_exp_f32_e32 v53, v35
	v_fmamk_f32 v35, v54, 0x3e38aa3b, v64
	v_exp_f32_e32 v37, v35
	v_fmamk_f32 v35, v38, 0x3e38aa3b, v64
	v_exp_f32_e32 v54, v35
	v_fmamk_f32 v35, v55, 0x3e38aa3b, v64
	v_exp_f32_e32 v38, v35
	v_fmamk_f32 v35, v39, 0x3e38aa3b, v64
	v_exp_f32_e32 v55, v35
	v_fmamk_f32 v35, v56, 0x3e38aa3b, v64
	v_fmamk_f32 v50, v50, 0x3e38aa3b, v64
	v_exp_f32_e32 v39, v35
	v_fmamk_f32 v35, v40, 0x3e38aa3b, v64
	v_exp_f32_e32 v50, v50
	v_exp_f32_e32 v56, v35
	v_fmamk_f32 v35, v57, 0x3e38aa3b, v64
	v_exp_f32_e32 v130, v34
	v_exp_f32_e32 v40, v35
	v_fmamk_f32 v35, v41, 0x3e38aa3b, v64
	v_exp_f32_e32 v57, v35
	v_fmamk_f32 v35, v58, 0x3e38aa3b, v64
	v_exp_f32_e32 v41, v35
	v_fmamk_f32 v35, v42, 0x3e38aa3b, v64
	v_add_f32_e32 v34, v129, v50
	v_exp_f32_e32 v58, v35
	v_fmamk_f32 v35, v59, 0x3e38aa3b, v64
	v_add_f32_e32 v32, v34, v32
	v_add_f32_e32 v34, v130, v51
	v_exp_f32_e32 v42, v35
	v_fmamk_f32 v35, v43, 0x3e38aa3b, v64
	v_add_f32_e32 v32, v34, v32
	v_add_f32_e32 v34, v128, v52
	v_exp_f32_e32 v59, v35
	v_fmamk_f32 v35, v60, 0x3e38aa3b, v64
	v_add_f32_e32 v32, v34, v32
	v_add_f32_e32 v34, v53, v36
	v_exp_f32_e32 v43, v35
	v_fmamk_f32 v35, v44, 0x3e38aa3b, v64
	v_add_f32_e32 v32, v34, v32
	v_add_f32_e32 v34, v54, v37
	v_exp_f32_e32 v60, v35
	v_fmamk_f32 v35, v61, 0x3e38aa3b, v64
	v_add_f32_e32 v32, v34, v32
	v_add_f32_e32 v34, v55, v38
	v_exp_f32_e32 v44, v35
	v_fmamk_f32 v35, v45, 0x3e38aa3b, v64
	v_add_f32_e32 v32, v34, v32
	v_add_f32_e32 v34, v56, v39
	v_exp_f32_e32 v61, v35
	v_fmamk_f32 v35, v62, 0x3e38aa3b, v64
	v_add_f32_e32 v32, v34, v32
	v_add_f32_e32 v34, v57, v40
	v_exp_f32_e32 v45, v35
	v_fmamk_f32 v35, v46, 0x3e38aa3b, v64
	v_add_f32_e32 v32, v34, v32
	v_add_f32_e32 v34, v58, v41
	v_exp_f32_e32 v62, v35
	v_fmamk_f32 v35, v63, 0x3e38aa3b, v64
	v_fmac_f32_e32 v64, 0x3e38aa3b, v47
	v_add_f32_e32 v32, v34, v32
	v_add_f32_e32 v34, v59, v42
	v_exp_f32_e32 v46, v35
	v_exp_f32_e32 v63, v64
	v_add_f32_e32 v32, v34, v32
	v_add_f32_e32 v34, v60, v43
	v_add_f32_e32 v32, v34, v32
	v_add_f32_e32 v34, v61, v44
	v_add_f32_e32 v32, v34, v32
	v_add_f32_e32 v34, v62, v45
	v_add_f32_e32 v32, v34, v32
	v_add_f32_e32 v34, v63, v46
	v_add_f32_e32 v32, v34, v32
	v_add_f32_e32 v32, v32, v213
	v_cvt_pk_bf16_f32 v34, v48, v49
	v_cvt_pk_bf16_f32 v35, v50, v51
	v_cvt_pk_bf16_f32 v36, v52, v36
	v_cvt_pk_bf16_f32 v37, v37, v38
	v_cvt_pk_bf16_f32 v38, v39, v40
	v_cvt_pk_bf16_f32 v39, v41, v42
	v_cvt_pk_bf16_f32 v40, v43, v44
	v_cvt_pk_bf16_f32 v41, v45, v46
	v_cvt_pk_bf16_f32 v42, v127, v33
	v_cvt_pk_bf16_f32 v43, v129, v130
	v_cvt_pk_bf16_f32 v44, v128, v53
	v_cvt_pk_bf16_f32 v45, v54, v55
	v_cvt_pk_bf16_f32 v46, v56, v57
	v_cvt_pk_bf16_f32 v47, v58, v59
	v_cvt_pk_bf16_f32 v48, v60, v61
	v_cvt_pk_bf16_f32 v49, v62, v63
	s_waitcnt vmcnt(0)
	v_mfma_f32_32x32x16_bf16 v[16:31], v[162:165], v[34:37], v[16:31]
	ds_bpermute_b32 v33, v235, v32
	v_mfma_f32_32x32x16_bf16 v[0:15], v[174:177], v[34:37], v[0:15]
	v_mfma_f32_32x32x16_bf16 v[16:31], v[154:157], v[38:41], v[16:31]
	v_mfma_f32_32x32x16_bf16 v[0:15], v[166:169], v[38:41], v[0:15]
	v_mfma_f32_32x32x16_bf16 v[16:31], v[146:149], v[42:45], v[16:31]
	v_mfma_f32_32x32x16_bf16 v[0:15], v[158:161], v[42:45], v[0:15]
	v_mfma_f32_32x32x16_bf16 v[16:31], v[142:145], v[46:49], v[16:31]
	v_mfma_f32_32x32x16_bf16 v[0:15], v[150:153], v[46:49], v[0:15]
	s_and_saveexec_b64 s[16:17], s[12:13]
	s_cbranch_execz .LBB0_329
	s_waitcnt lgkmcnt(0)
	v_add_f32_e32 v127, v32, v33
	v_div_scale_f32 v32, s[12:13], v127, v127, 1.0
	v_rcp_f32_e32 v33, v32
	s_movk_i32 s12, 0x88
	v_fma_f32 v34, -v32, v33, 1.0
	v_fmac_f32_e32 v33, v34, v33
	v_div_scale_f32 v34, vcc, 1.0, v127, 1.0
	v_mul_f32_e32 v35, v34, v33
	v_fma_f32 v36, -v32, v35, v34
	v_fmac_f32_e32 v35, v36, v33
	v_fma_f32 v32, -v32, v35, v34
	v_div_fmas_f32 v32, v32, v33, v35
	v_div_fixup_f32 v34, v32, v127, 1.0
	v_lshl_add_u32 v32, v234, 2, 0
	v_add_u32_e32 v32, 0x1d080, v32
	ds_read_b32 v32, v32
	v_mul_f32_e32 v16, v16, v34
	v_mul_f32_e32 v17, v17, v34
	v_mul_f32_e32 v18, v18, v34
	v_mul_f32_e32 v19, v19, v34
	v_mul_f32_e32 v0, v0, v34
	v_mul_f32_e32 v1, v1, v34
	v_mul_f32_e32 v2, v2, v34
	v_mul_f32_e32 v3, v3, v34
	s_waitcnt lgkmcnt(0)
	v_bfe_u32 v32, v32, 0, s27
	v_bcnt_u32_b32 v32, v32, 0
	v_lshl_add_u32 v32, v32, 8, v234
	v_cvt_pk_bf16_f32 v16, v16, v17
	v_cvt_pk_bf16_f32 v17, v18, v19
	v_cvt_pk_bf16_f32 v0, v0, v1
	v_cvt_pk_bf16_f32 v1, v2, v3
	v_mul_f32_e32 v2, v20, v34
	v_mul_f32_e32 v3, v21, v34
	v_mul_f32_e32 v18, v22, v34
	v_mul_f32_e32 v19, v23, v34
	v_mad_i32_i24 v33, v32, s12, v233
	v_cvt_pk_bf16_f32 v2, v2, v3
	v_cvt_pk_bf16_f32 v3, v18, v19
	ds_write2_b64 v33, v[16:17], v[2:3] offset1:2
	v_mul_f32_e32 v2, v4, v34
	v_mul_f32_e32 v3, v5, v34
	v_mul_f32_e32 v4, v6, v34
	v_mul_f32_e32 v5, v7, v34
	v_cvt_pk_bf16_f32 v2, v2, v3
	v_cvt_pk_bf16_f32 v3, v4, v5
	ds_write2_b64 v33, v[0:1], v[2:3] offset0:8 offset1:10
	v_mul_f32_e32 v0, v24, v34
	v_mul_f32_e32 v1, v25, v34
	v_mul_f32_e32 v2, v26, v34
	v_mul_f32_e32 v3, v27, v34
	v_cvt_pk_bf16_f32 v0, v0, v1
	v_cvt_pk_bf16_f32 v1, v2, v3
	v_mul_f32_e32 v2, v8, v34
	v_mul_f32_e32 v3, v9, v34
	v_mul_f32_e32 v4, v10, v34
	v_mul_f32_e32 v5, v11, v34
	v_cvt_pk_bf16_f32 v2, v2, v3
	v_cvt_pk_bf16_f32 v3, v4, v5
	v_mul_f32_e32 v4, v28, v34
	v_mul_f32_e32 v5, v29, v34
	v_mul_f32_e32 v6, v30, v34
	v_mul_f32_e32 v7, v31, v34
	v_cvt_pk_bf16_f32 v4, v4, v5
	v_cvt_pk_bf16_f32 v5, v6, v7
	ds_write2_b64 v33, v[0:1], v[4:5] offset0:4 offset1:6
	v_mul_f32_e32 v0, v12, v34
	v_mul_f32_e32 v1, v13, v34
	v_mul_f32_e32 v4, v14, v34
	v_mul_f32_e32 v5, v15, v34
	v_cvt_pk_bf16_f32 v0, v0, v1
	v_cvt_pk_bf16_f32 v1, v4, v5
	ds_write2_b64 v33, v[2:3], v[0:1] offset0:12 offset1:14
	s_and_b64 exec, exec, s[0:1]
	s_cbranch_execz .LBB0_329
	v_lshl_add_u32 v0, v32, 3, 0
	v_add_u32_e32 v0, 0x19800, v0
	ds_write_b64 v0, v[126:127]
	s_branch .LBB0_329

; template <int MASK>
; __device__ __forceinline__ void tile_qk(const KFr& f, const bf16x8 (&qf)[4], u32x4 (&pw)[4], f32x16& o0, f32x16& o1, float& m, float& l, int kq, float sl2, int lane) {
;     const int hi = lane >> 5;
;     f32x16 p0, p1;
; #pragma unroll
;     for (int r = 0; r < 16; ++r) { p0[r] = 0.f; p1[r] = 0.f; }
; #pragma unroll
;     for (int d0 = 0; d0 < 4; ++d0) {
;         p0 = __builtin_amdgcn_mfma_f32_32x32x16_bf16(f.a[0][d0], qf[d0], p0, 0, 0, 0);
;         p1 = __builtin_amdgcn_mfma_f32_32x32x16_bf16(f.a[1][d0], qf[d0], p1, 0, 0, 0);
;     }
;     constexpr float C2 = 0.125f * LOG2E;
;     const int dk0 = kq + 4 * hi;
;     float sl = sl2; asm volatile("" : "+v"(sl));
;     const float base = sl * (float)dk0;
;     const float NEG = -INFINITY;
;     float mx = NEG;
; #pragma unroll
;     for (int r = 0; r < 16; ++r) {
;         const int kk = (r & 3) + 8 * (r >> 2);
;         float t0 = fmaf(p0[r], C2, fmaf((float)kk, sl, base)), t1 = fmaf(p1[r], C2, fmaf((float)(kk + 32), sl, base));
;         if (MASK == 1) { if (dk0 + kk > 0) t0 = NEG; if (dk0 + kk + 32 > 0) t1 = NEG; }
;         p0[r] = t0; p1[r] = t1; mx = fmaxf(mx, fmaxf(t0, t1));
; __device__ __forceinline__ void moba_unit(int b, int h, int qb, const bf16* qkv, const bf16* KF, const bf16* VF, bf16* Y, const float* kmean, LAS unsigned char* lds) {
;     ...
;         for (int i = 0; i < nown; ++i) {
;             loadK(k0, kp); loadV(v0, vp);
;             tile_qk<1>(k0, qo, pw, o0, o1, m, l, 64 * i - qloc, sl2, lane); tile_pv(v0, pw, o0, o1);
.LBB0_363:
	v_lshl_add_u64 v[40:41], v[118:119], 0, s[56:57]
	v_mov_b32_e32 v124, v32
	global_load_dwordx4 v[32:35], v[118:119], off
	global_load_dwordx4 v[126:129], v[118:119], off offset:1024
	global_load_dwordx4 v[130:133], v[118:119], off offset:2048
	global_load_dwordx4 v[134:137], v[118:119], off offset:3072
	global_load_dwordx4 v[36:39], v[40:41], off
	global_load_dwordx4 v[138:141], v[40:41], off offset:1024
	global_load_dwordx4 v[142:145], v[40:41], off offset:2048
	global_load_dwordx4 v[146:149], v[40:41], off offset:3072
	v_lshl_add_u64 v[118:119], v[40:41], 0, s[56:57]
	v_lshl_add_u64 v[40:41], v[120:121], 0, s[56:57]
	v_mov_b32_e32 v123, v50
	global_load_dwordx4 v[94:97], v[120:121], off
	global_load_dwordx4 v[90:93], v[120:121], off offset:1024
	global_load_dwordx4 v[86:89], v[120:121], off offset:2048
	global_load_dwordx4 v[82:85], v[120:121], off offset:3072
	global_load_dwordx4 v[110:113], v[40:41], off
	global_load_dwordx4 v[106:109], v[40:41], off offset:1024
	global_load_dwordx4 v[102:105], v[40:41], off offset:2048
	global_load_dwordx4 v[98:101], v[40:41], off offset:3072
	v_lshl_add_u64 v[120:121], v[40:41], 0, s[56:57]
	v_cmp_gt_i32_e32 vcc, 1, v117
	s_add_i32 s0, s0, -1
	s_cmp_eq_u32 s0, 0
	s_waitcnt vmcnt(0) lgkmcnt(0)
	v_mfma_f32_32x32x16_bf16 v[48:63], v[32:35], v[78:81], 0
	v_mfma_f32_32x32x16_bf16 v[32:47], v[36:39], v[78:81], 0
	v_mfma_f32_32x32x16_bf16 v[48:63], v[126:129], v[70:73], v[48:63]
	v_cvt_f32_i32_e32 v126, v117
	v_mov_b32_e32 v129, v230
	v_mfma_f32_32x32x16_bf16 v[32:47], v[138:141], v[70:73], v[32:47]
	v_mfma_f32_32x32x16_bf16 v[48:63], v[130:133], v[66:69], v[48:63]
	v_mul_f32_e32 v130, v129, v126
	v_fma_f32 v125, 0, v129, v130
	v_fmamk_f32 v127, v129, 0x42000000, v130
	v_fma_f32 v126, v129, v126, v129
	v_fmamk_f32 v128, v129, 0x420c0000, v130
	v_mfma_f32_32x32x16_bf16 v[32:47], v[142:145], v[66:69], v[32:47]
	v_mfma_f32_32x32x16_bf16 v[48:63], v[134:137], v[74:77], v[48:63]
	v_mfma_f32_32x32x16_bf16 v[32:47], v[146:149], v[74:77], v[32:47]
	s_nop 10
	v_fmac_f32_e32 v125, 0x3e38aa3b, v48
	v_cndmask_b32_e32 v48, v228, v125, vcc
	v_cmp_gt_i32_e32 vcc, s2, v117
	v_fmac_f32_e32 v126, 0x3e38aa3b, v49
	v_fmac_f32_e32 v127, 0x3e38aa3b, v32
	v_cndmask_b32_e32 v125, v228, v127, vcc
	v_fmamk_f32 v127, v129, 0x42040000, v130
	v_cmp_gt_i32_e32 vcc, 0, v117
	v_fmac_f32_e32 v127, 0x3e38aa3b, v33
	v_max_f32_e32 v32, v48, v125
	v_cndmask_b32_e32 v49, v228, v126, vcc
	v_cmp_gt_i32_e32 vcc, s75, v117
	v_fmac_f32_e32 v128, 0x3e38aa3b, v35
	v_fmamk_f32 v35, v129, 0x42240000, v130
	v_cndmask_b32_e32 v126, v228, v127, vcc
	v_max_f32_e32 v33, v49, v126
	v_max3_f32 v32, v32, s1, v33
	v_fma_f32 v33, 2.0, v129, v130
	v_fmac_f32_e32 v33, 0x3e38aa3b, v50
	v_fmamk_f32 v127, v129, 0x42080000, v130
	v_cmp_gt_i32_e32 vcc, -1, v117
	v_fmac_f32_e32 v127, 0x3e38aa3b, v34
	v_fmamk_f32 v34, v129, 0x40400000, v130
	v_cndmask_b32_e32 v50, v228, v33, vcc
	v_cmp_gt_i32_e32 vcc, s72, v117
	v_fmac_f32_e32 v34, 0x3e38aa3b, v51
	v_fmac_f32_e32 v35, 0x3e38aa3b, v37
	v_cndmask_b32_e32 v127, v228, v127, vcc
	v_cmp_gt_i32_e32 vcc, -2, v117
	v_max_f32_e32 v33, v50, v127
	s_nop 0
	v_cndmask_b32_e32 v51, v228, v34, vcc
	v_cmp_gt_i32_e32 vcc, s74, v117
	s_nop 1
	v_cndmask_b32_e32 v128, v228, v128, vcc
	v_max_f32_e32 v34, v51, v128
	v_max3_f32 v32, v32, v33, v34
	v_fmamk_f32 v33, v129, 0x41000000, v130
	v_fmac_f32_e32 v33, 0x3e38aa3b, v52
	v_fmamk_f32 v34, v129, 0x42200000, v130
	v_cmp_gt_i32_e32 vcc, -7, v117
	v_fmac_f32_e32 v34, 0x3e38aa3b, v36
	s_nop 0
	v_cndmask_b32_e32 v36, v228, v33, vcc
	v_cmp_gt_i32_e32 vcc, s3, v117
	s_nop 1
	v_cndmask_b32_e32 v52, v228, v34, vcc
	v_fmamk_f32 v34, v129, 0x41100000, v130
	v_fmac_f32_e32 v34, 0x3e38aa3b, v53
	v_cmp_gt_i32_e32 vcc, -8, v117
	v_max_f32_e32 v33, v36, v52
	s_nop 0
	v_cndmask_b32_e32 v37, v228, v34, vcc
	v_cmp_gt_i32_e32 vcc, s78, v117
	s_nop 1
	v_cndmask_b32_e32 v53, v228, v35, vcc
	v_max_f32_e32 v34, v37, v53
	v_max3_f32 v32, v32, v33, v34
	v_fmamk_f32 v33, v129, 0x41200000, v130
	v_fmac_f32_e32 v33, 0x3e38aa3b, v54
	v_fmamk_f32 v34, v129, 0x42280000, v130
	v_cmp_gt_i32_e32 vcc, -9, v117
	v_fmac_f32_e32 v34, 0x3e38aa3b, v38
	v_fmamk_f32 v35, v129, 0x422c0000, v130
	v_cndmask_b32_e32 v38, v228, v33, vcc
	v_cmp_gt_i32_e32 vcc, s80, v117
	v_fmac_f32_e32 v35, 0x3e38aa3b, v39
	s_nop 0
	v_cndmask_b32_e32 v54, v228, v34, vcc
	v_fmamk_f32 v34, v129, 0x41300000, v130
	v_fmac_f32_e32 v34, 0x3e38aa3b, v55
	v_cmp_gt_i32_e32 vcc, -10, v117
	v_max_f32_e32 v33, v38, v54
	s_nop 0
	v_cndmask_b32_e32 v39, v228, v34, vcc
	v_cmp_gt_i32_e32 vcc, s73, v117
	s_nop 1
	v_cndmask_b32_e32 v55, v228, v35, vcc
	v_max_f32_e32 v34, v39, v55
	v_max3_f32 v32, v32, v33, v34
	v_fmamk_f32 v33, v129, 0x41800000, v130
	v_fmac_f32_e32 v33, 0x3e38aa3b, v56
	v_fmamk_f32 v34, v129, 0x42400000, v130
	v_cmp_gt_i32_e32 vcc, -15, v117
	v_fmac_f32_e32 v34, 0x3e38aa3b, v40
	v_fmamk_f32 v35, v129, 0x42440000, v130
	v_cndmask_b32_e32 v40, v228, v33, vcc
	v_cmp_gt_i32_e32 vcc, s44, v117
	v_fmac_f32_e32 v35, 0x3e38aa3b, v41
	s_nop 0
	v_cndmask_b32_e32 v56, v228, v34, vcc
	v_fmamk_f32 v34, v129, 0x41880000, v130
	v_fmac_f32_e32 v34, 0x3e38aa3b, v57
	v_cmp_gt_i32_e32 vcc, -16, v117
	v_max_f32_e32 v33, v40, v56
	s_nop 0
	v_cndmask_b32_e32 v41, v228, v34, vcc
	v_cmp_gt_i32_e32 vcc, s76, v117
	s_nop 1
	v_cndmask_b32_e32 v57, v228, v35, vcc
	v_max_f32_e32 v34, v41, v57
	v_max3_f32 v32, v32, v33, v34
	v_fmamk_f32 v33, v129, 0x41900000, v130
	v_fmac_f32_e32 v33, 0x3e38aa3b, v58
	v_fmamk_f32 v34, v129, 0x42480000, v130
	v_cmp_gt_i32_e32 vcc, s88, v117
	v_fmac_f32_e32 v34, 0x3e38aa3b, v42
	v_fmamk_f32 v35, v129, 0x424c0000, v130
	v_cndmask_b32_e32 v42, v228, v33, vcc
; template <int MASK>
; __device__ __forceinline__ void tile_qk(const KFr& f, const bf16x8 (&qf)[4], u32x4 (&pw)[4], f32x16& o0, f32x16& o1, float& m, float& l, int kq, float sl2, int lane) {
;     ...
; #pragma unroll
;     for (int r = 0; r < 16; ++r) {
;         const int kk = (r & 3) + 8 * (r >> 2);
;         float t0 = fmaf(p0[r], C2, fmaf((float)kk, sl, base)), t1 = fmaf(p1[r], C2, fmaf((float)(kk + 32), sl, base));
;         if (MASK == 1) { if (dk0 + kk > 0) t0 = NEG; if (dk0 + kk + 32 > 0) t1 = NEG; }
;         p0[r] = t0; p1[r] = t1; mx = fmaxf(mx, fmaxf(t0, t1));
;     }
;     mx = fmaxf(mx, __shfl_xor(mx, 32));
	v_cmp_gt_i32_e32 vcc, s77, v117
	v_fmac_f32_e32 v35, 0x3e38aa3b, v43
	s_nop 0
	v_cndmask_b32_e32 v58, v228, v34, vcc
	v_fmamk_f32 v34, v129, 0x41980000, v130
	v_fmac_f32_e32 v34, 0x3e38aa3b, v59
	v_cmp_gt_i32_e32 vcc, s90, v117
	v_max_f32_e32 v33, v42, v58
	s_nop 0
	v_cndmask_b32_e32 v43, v228, v34, vcc
	v_cmp_gt_i32_e32 vcc, s79, v117
	s_nop 1
	v_cndmask_b32_e32 v59, v228, v35, vcc
	v_max_f32_e32 v34, v43, v59
	v_max3_f32 v32, v32, v33, v34
	v_fmamk_f32 v33, v129, 0x41c00000, v130
	v_fmac_f32_e32 v33, 0x3e38aa3b, v60
	v_fmamk_f32 v34, v129, 0x42600000, v130
	v_cmp_gt_i32_e32 vcc, s45, v117
	v_fmac_f32_e32 v34, 0x3e38aa3b, v44
	v_fmamk_f32 v35, v129, 0x42640000, v130
	v_cndmask_b32_e32 v44, v228, v33, vcc
	v_cmp_gt_i32_e32 vcc, s52, v117
	v_fmac_f32_e32 v35, 0x3e38aa3b, v45
	s_nop 0
	v_cndmask_b32_e32 v60, v228, v34, vcc
	v_fmamk_f32 v34, v129, 0x41c80000, v130
	v_fmac_f32_e32 v34, 0x3e38aa3b, v61
	v_cmp_gt_i32_e32 vcc, s94, v117
	v_max_f32_e32 v33, v44, v60
	s_nop 0
	v_cndmask_b32_e32 v45, v228, v34, vcc
	v_cmp_gt_i32_e32 vcc, s81, v117
	s_nop 1
	v_cndmask_b32_e32 v61, v228, v35, vcc
	v_max_f32_e32 v34, v45, v61
	v_max3_f32 v32, v32, v33, v34
	v_fmamk_f32 v33, v129, 0x41d00000, v130
	v_fmac_f32_e32 v33, 0x3e38aa3b, v62
	v_fmamk_f32 v34, v129, 0x42680000, v130
	v_cmp_gt_i32_e32 vcc, s96, v117
	v_fmac_f32_e32 v34, 0x3e38aa3b, v46
	s_nop 0
	v_cndmask_b32_e32 v46, v228, v33, vcc
	v_cmp_gt_i32_e32 vcc, s82, v117
	s_nop 1
	v_cndmask_b32_e32 v62, v228, v34, vcc
	v_fmamk_f32 v34, v129, 0x41d80000, v130
	v_fmac_f32_e32 v34, 0x3e38aa3b, v63
	v_fmac_f32_e32 v130, 0x426c0000, v129
	v_cmp_gt_i32_e32 vcc, s83, v117
	v_fmac_f32_e32 v130, 0x3e38aa3b, v47
	v_max_f32_e32 v33, v46, v62
	v_cndmask_b32_e32 v47, v228, v34, vcc
	v_cmp_gt_i32_e32 vcc, s84, v117
	v_add_u32_e32 v117, 64, v117
	s_nop 0
	v_cndmask_b32_e32 v63, v228, v130, vcc
	v_max_f32_e32 v34, v47, v63
	v_max3_f32 v32, v32, v33, v34
	v_mbcnt_hi_u32_b32 v33, -1, v220
	v_and_b32_e32 v35, 64, v33
	v_xor_b32_e32 v34, 32, v33
	v_add_u32_e32 v35, 64, v35
	v_cmp_lt_i32_e32 vcc, v34, v35
	s_nop 1
	v_cndmask_b32_e32 v129, v33, v34, vcc
	v_lshlrev_b32_e32 v129, 2, v129
	ds_bpermute_b32 v129, v129, v32
	s_waitcnt lgkmcnt(0)
; __device__ __forceinline__ unsigned pk2(float lo, float hi) { return pg8::cvt_pk_bf16(lo, hi); }
; template <int MASK>
; __device__ __forceinline__ void tile_qk(const KFr& f, const bf16x8 (&qf)[4], u32x4 (&pw)[4], f32x16& o0, f32x16& o1, float& m, float& l, int kq, float sl2, int lane) {
;     ...
;     mx = fmaxf(mx, __shfl_xor(mx, 32));
;     const float mn = fmaxf(m, mx), alpha = __builtin_amdgcn_exp2f(m - mn); m = mn;
;     float rs = 0.f;
; #pragma unroll
;     for (int r = 0; r < 16; ++r) { p0[r] = __builtin_amdgcn_exp2f(p0[r] - mn); p1[r] = __builtin_amdgcn_exp2f(p1[r] - mn); rs += p0[r] + p1[r]; }
;     l = l * alpha + rs;
; #pragma unroll
;     for (int r = 0; r < 16; ++r) { o0[r] *= alpha; o1[r] *= alpha; }
;     pw[0] = (u32x4){pk2(p0[0], p0[1]), pk2(p0[2], p0[3]), pk2(p0[4], p0[5]), pk2(p0[6], p0[7])};
;     pw[1] = (u32x4){pk2(p0[8], p0[9]), pk2(p0[10], p0[11]), pk2(p0[12], p0[13]), pk2(p0[14], p0[15])};
;     pw[2] = (u32x4){pk2(p1[0], p1[1]), pk2(p1[2], p1[3]), pk2(p1[4], p1[5]), pk2(p1[6], p1[7])};
;     pw[3] = (u32x4){pk2(p1[8], p1[9]), pk2(p1[10], p1[11]), pk2(p1[12], p1[13]), pk2(p1[14], p1[15])};
; __device__ __forceinline__ void tile_pv(const VFr& f, const u32x4 (&pw)[4], f32x16& o0, f32x16& o1) {
; #pragma unroll
;     for (int ks = 0; ks < 4; ++ks) {
;         const bf16x8 P = __builtin_bit_cast(bf16x8, pw[ks]);
;         o0 = __builtin_amdgcn_mfma_f32_32x32x16_bf16(f.a[0][ks], P, o0, 0, 0, 0);
;         o1 = __builtin_amdgcn_mfma_f32_32x32x16_bf16(f.a[1][ks], P, o1, 0, 0, 0);
;     }
; }
	v_max3_f32 v32, v124, v32, v129
	v_sub_f32_e32 v48, v48, v32
	v_exp_f32_e32 v130, v48
	v_sub_f32_e32 v48, v125, v32
	v_sub_f32_e32 v49, v49, v32
	v_exp_f32_e32 v131, v48
	v_exp_f32_e32 v132, v49
	v_sub_f32_e32 v49, v126, v32
	v_exp_f32_e32 v133, v49
	v_add_f32_e32 v48, v131, v130
	v_add_f32_e32 v48, 0, v48
	v_sub_f32_e32 v36, v36, v32
	v_add_f32_e32 v49, v133, v132
	v_add_f32_e32 v48, v49, v48
	v_sub_f32_e32 v49, v50, v32
	v_exp_f32_e32 v134, v49
	v_sub_f32_e32 v49, v127, v32
	v_exp_f32_e32 v135, v49
	v_sub_f32_e32 v129, v124, v32
	v_add_f32_e32 v49, v135, v134
	v_add_f32_e32 v48, v49, v48
	v_sub_f32_e32 v49, v51, v32
	v_exp_f32_e32 v51, v49
	v_sub_f32_e32 v49, v128, v32
	v_exp_f32_e32 v128, v49
	s_nop 0
	v_add_f32_e32 v49, v128, v51
	v_add_f32_e32 v50, v49, v48
	v_exp_f32_e32 v49, v36
	v_sub_f32_e32 v36, v52, v32
	v_exp_f32_e32 v125, v36
	v_sub_f32_e32 v36, v37, v32
	v_exp_f32_e32 v48, v36
	v_sub_f32_e32 v36, v53, v32
	v_exp_f32_e32 v124, v36
	s_nop 0
	v_add_f32_e32 v36, v124, v48
	v_add_f32_e32 v37, v125, v49
	s_nop 0
	v_add_f32_e32 v37, v37, v50
	v_add_f32_e32 v50, v36, v37
	v_sub_f32_e32 v36, v38, v32
	v_exp_f32_e32 v37, v36
	v_sub_f32_e32 v36, v54, v32
	v_exp_f32_e32 v53, v36
	v_sub_f32_e32 v36, v39, v32
	v_sub_f32_e32 v38, v55, v32
	v_exp_f32_e32 v36, v36
	v_exp_f32_e32 v52, v38
	s_nop 0
	v_add_f32_e32 v38, v52, v36
	v_add_f32_e32 v39, v53, v37
	s_nop 0
	v_add_f32_e32 v39, v39, v50
	v_add_f32_e32 v50, v38, v39
	v_sub_f32_e32 v38, v40, v32
	v_exp_f32_e32 v39, v38
	v_sub_f32_e32 v38, v56, v32
	v_exp_f32_e32 v55, v38
	v_sub_f32_e32 v38, v41, v32
	v_sub_f32_e32 v40, v57, v32
	v_exp_f32_e32 v38, v38
	v_exp_f32_e32 v54, v40
	v_pk_mov_b32 v[52:53], v[52:53], v[52:53] op_sel:[1,0]
	v_add_f32_e32 v40, v54, v38
	v_add_f32_e32 v41, v55, v39
	s_nop 0
	v_add_f32_e32 v41, v41, v50
	v_add_f32_e32 v50, v40, v41
	v_sub_f32_e32 v40, v42, v32
	v_exp_f32_e32 v41, v40
	v_sub_f32_e32 v40, v58, v32
	v_exp_f32_e32 v57, v40
	v_sub_f32_e32 v40, v43, v32
	v_sub_f32_e32 v42, v59, v32
	v_exp_f32_e32 v40, v40
	v_exp_f32_e32 v56, v42
	v_pk_mov_b32 v[54:55], v[54:55], v[54:55] op_sel:[1,0]
	v_pk_mov_b32 v[126:127], v[40:41], v[40:41] op_sel:[1,0]
	v_add_f32_e32 v42, v56, v40
	v_add_f32_e32 v43, v57, v41
	v_cvt_pk_bf16_f32 v41, v126, v127
	v_add_f32_e32 v43, v43, v50
	v_add_f32_e32 v50, v42, v43
	v_sub_f32_e32 v42, v44, v32
	v_exp_f32_e32 v43, v42
	v_sub_f32_e32 v42, v60, v32
	v_exp_f32_e32 v59, v42
	v_sub_f32_e32 v42, v45, v32
	v_sub_f32_e32 v44, v61, v32
	v_exp_f32_e32 v42, v42
	v_exp_f32_e32 v58, v44
	v_pk_mov_b32 v[56:57], v[56:57], v[56:57] op_sel:[1,0]
	v_add_f32_e32 v44, v58, v42
	v_add_f32_e32 v45, v59, v43
	s_nop 0
	v_add_f32_e32 v45, v45, v50
	v_add_f32_e32 v50, v44, v45
	v_sub_f32_e32 v44, v46, v32
	v_exp_f32_e32 v45, v44
	v_sub_f32_e32 v44, v62, v32
	v_exp_f32_e32 v61, v44
	v_sub_f32_e32 v44, v47, v32
	v_sub_f32_e32 v46, v63, v32
	v_exp_f32_e32 v44, v44
	v_exp_f32_e32 v60, v46
	v_pk_mov_b32 v[62:63], v[36:37], v[36:37] op_sel:[1,0]
	v_cvt_pk_bf16_f32 v36, v130, v132
	v_cvt_pk_bf16_f32 v37, v134, v51
	v_add_f32_e32 v46, v60, v44
	v_add_f32_e32 v47, v61, v45
	v_pk_mov_b32 v[42:43], v[42:43], v[42:43] op_sel:[1,0]
	v_add_f32_e32 v47, v47, v50
	v_add_f32_e32 v50, v46, v47
	v_exp_f32_e32 v46, v129
	v_pk_mov_b32 v[44:45], v[44:45], v[44:45] op_sel:[1,0]
	v_cvt_pk_bf16_f32 v42, v42, v43
	v_cvt_pk_bf16_f32 v43, v44, v45
	v_fmac_f32_e32 v50, v123, v46
	v_mul_f32_e32 v30, v30, v46
	v_mul_f32_e32 v31, v31, v46
	v_mul_f32_e32 v28, v28, v46
	v_mul_f32_e32 v29, v29, v46
	v_mul_f32_e32 v26, v26, v46
	v_mul_f32_e32 v27, v27, v46
	v_mul_f32_e32 v24, v24, v46
	v_mul_f32_e32 v25, v25, v46
	v_mul_f32_e32 v22, v22, v46
	v_mul_f32_e32 v23, v23, v46
	v_mul_f32_e32 v20, v20, v46
	v_mul_f32_e32 v21, v21, v46
	v_mul_f32_e32 v18, v18, v46
	v_mul_f32_e32 v19, v19, v46
	v_mul_f32_e32 v16, v16, v46
	v_mul_f32_e32 v17, v17, v46
	v_mul_f32_e32 v14, v14, v46
	v_mul_f32_e32 v15, v15, v46
	v_mul_f32_e32 v12, v12, v46
	v_mul_f32_e32 v13, v13, v46
	v_mul_f32_e32 v10, v10, v46
	v_mul_f32_e32 v11, v11, v46
	v_mul_f32_e32 v8, v8, v46
	v_mul_f32_e32 v9, v9, v46
	v_mul_f32_e32 v6, v6, v46
	v_mul_f32_e32 v7, v7, v46
	v_mul_f32_e32 v4, v4, v46
	v_mul_f32_e32 v5, v5, v46
	v_mul_f32_e32 v2, v2, v46
	v_mul_f32_e32 v3, v3, v46
	v_mul_f32_e32 v0, v0, v46
	v_mul_f32_e32 v1, v1, v46
	v_pk_mov_b32 v[46:47], v[48:49], v[48:49] op_sel:[1,0]
	v_pk_mov_b32 v[48:49], v[124:125], v[124:125] op_sel:[1,0]
	v_pk_mov_b32 v[124:125], v[38:39], v[38:39] op_sel:[1,0]
	v_cvt_pk_bf16_f32 v38, v46, v47
	v_cvt_pk_bf16_f32 v39, v62, v63
	v_cvt_pk_bf16_f32 v40, v124, v125
	v_cvt_pk_bf16_f32 v44, v131, v133
	v_mfma_f32_32x32x16_bf16 v[16:31], v[94:97], v[36:39], v[16:31]
	v_cvt_pk_bf16_f32 v45, v135, v128
	v_cvt_pk_bf16_f32 v46, v48, v49
	v_cvt_pk_bf16_f32 v47, v52, v53
	v_pk_mov_b32 v[58:59], v[58:59], v[58:59] op_sel:[1,0]
	v_pk_mov_b32 v[60:61], v[60:61], v[60:61] op_sel:[1,0]
	v_cvt_pk_bf16_f32 v52, v54, v55
	v_cvt_pk_bf16_f32 v53, v56, v57
	v_mfma_f32_32x32x16_bf16 v[0:15], v[110:113], v[36:39], v[0:15]
	v_cvt_pk_bf16_f32 v54, v58, v59
	v_cvt_pk_bf16_f32 v55, v60, v61
	v_mfma_f32_32x32x16_bf16 v[16:31], v[90:93], v[40:43], v[16:31]
	v_mfma_f32_32x32x16_bf16 v[0:15], v[106:109], v[40:43], v[0:15]
	v_mfma_f32_32x32x16_bf16 v[16:31], v[86:89], v[44:47], v[16:31]
	v_mfma_f32_32x32x16_bf16 v[0:15], v[102:105], v[44:47], v[0:15]
	v_mfma_f32_32x32x16_bf16 v[16:31], v[82:85], v[52:55], v[16:31]
	v_mfma_f32_32x32x16_bf16 v[0:15], v[98:101], v[52:55], v[0:15]
	s_cbranch_scc0 .LBB0_363
	s_mov_b64 s[0:1], 0

; #define LAS __attribute__((address_space(3)))
; #define WG_BAR() __syncthreads()
; __device__ __forceinline__ void moba_unit(int b, int h, int qb, const bf16* qkv, const bf16* KF, const bf16* VF, bf16* Y, const float* kmean, LAS unsigned char* lds) {
;     ...
;     WG_BAR();
;     {
;         const float lt = l + __shfl_xor(l, 32);
;         const int nsel = __builtin_popcount(selmask);
;         float mj[3], lj[3]; float M = m;
; #pragma unroll
;         for (int j = 0; j < 3; ++j) { mj[j] = -1e30f; lj[j] = 0.f;
;             if (j < nsel) { const f32x2v v = *(LAS const f32x2v*)(lds + MB_ML + (j * 256 + qloc) * 8); mj[j] = v.x; lj[j] = v.y; }
;             M = fmaxf(M, mj[j]); }
;         const float w0 = __builtin_amdgcn_exp2f(m - M); float den = lt * w0;
; #pragma unroll
;         for (int r = 0; r < 16; ++r) { o0[r] *= w0; o1[r] *= w0; }
.LBB0_367:
	v_cmp_lt_i32_e32 vcc, v34, v35
	s_waitcnt lgkmcnt(0)
	v_cmp_ne_u32_e64 s[6:7], 0, v122
	v_mov_b32_e32 v47, 0
	v_cndmask_b32_e32 v33, v33, v34, vcc
	v_lshlrev_b32_e32 v33, 2, v33
	ds_bpermute_b32 v52, v33, v50
	v_lshlrev_b32_e32 v33, 3, v116
	v_mov_b32_e32 v46, 0xf149f2ca
	v_mov_b32_e32 v48, 0xf149f2ca
	v_mov_b32_e32 v49, 0
	s_waitcnt lgkmcnt(0)
	s_barrier
	s_and_saveexec_b64 s[0:1], s[6:7]
	v_add_u32_e32 v34, 0, v33
	v_add_u32_e32 v34, 0x19800, v34
	ds_read_b64 v[48:49], v34
	s_or_b64 exec, exec, s[0:1]
	v_bcnt_u32_b32 v34, v122, 0
	v_cmp_lt_u32_e64 s[0:1], 1, v34
	s_and_saveexec_b64 s[2:3], s[0:1]
	s_add_i32 s8, 0, 0x19800
	v_add_u32_e32 v35, s8, v33
	ds_read_b64 v[46:47], v35 offset:2048
	s_or_b64 exec, exec, s[2:3]
	v_cmp_lt_u32_e32 vcc, 2, v34
	v_mov_b32_e32 v45, 0
	v_mov_b32_e32 v44, 0xf149f2ca
	s_and_saveexec_b64 s[2:3], vcc
	s_add_i32 s8, 0, 0x19800
	v_add_u32_e32 v33, s8, v33
	ds_read_b64 v[44:45], v33 offset:4096
	s_or_b64 exec, exec, s[2:3]
	s_waitcnt lgkmcnt(0)
	v_max_f32_e32 v33, v48, v48
	v_max_f32_e32 v34, v32, v32
	v_max_f32_e32 v33, v34, v33
	v_max3_f32 v51, v33, v46, v44
	v_sub_f32_e32 v32, v32, v51
	v_exp_f32_e32 v54, v32
	s_nop 0
	v_mul_f32_e32 v36, v0, v54
	v_mul_f32_e32 v37, v1, v54
	v_mul_f32_e32 v0, v12, v54
	v_mul_f32_e32 v1, v13, v54
	v_add_f32_e32 v12, v50, v52
	v_mul_f32_e32 v40, v16, v54
	v_mul_f32_e32 v41, v17, v54
	v_mul_f32_e32 v42, v18, v54
	v_mul_f32_e32 v43, v19, v54
	v_mul_f32_e32 v38, v2, v54
	v_mul_f32_e32 v39, v3, v54
	v_mul_f32_e32 v32, v20, v54
	v_mul_f32_e32 v33, v21, v54
	s_waitcnt vmcnt(0)
	v_mul_f32_e32 v20, v4, v54
	v_mul_f32_e32 v21, v5, v54
	v_mul_f32_e32 v34, v22, v54
	v_mul_f32_e32 v35, v23, v54
	v_mul_f32_e32 v22, v6, v54
	v_mul_f32_e32 v23, v7, v54
	v_mul_f32_e32 v16, v24, v54
	v_mul_f32_e32 v17, v25, v54
	v_mul_f32_e32 v8, v8, v54
	v_mul_f32_e32 v9, v9, v54
	v_mul_f32_e32 v18, v26, v54
	v_mul_f32_e32 v19, v27, v54
	v_mul_f32_e32 v10, v10, v54
	v_mul_f32_e32 v11, v11, v54
	v_mul_f32_e32 v4, v28, v54
	v_mul_f32_e32 v5, v29, v54
	v_mul_f32_e32 v6, v30, v54
	v_mul_f32_e32 v7, v31, v54
	v_mul_f32_e32 v2, v14, v54
	v_mul_f32_e32 v3, v15, v54
	v_mul_f32_e32 v13, v12, v54
	v_add_u32_e32 v12, 0, v64
	s_and_saveexec_b64 s[2:3], s[6:7]
	s_cbranch_execnz .LBB0_376
	s_or_b64 exec, exec, s[2:3]
	s_and_saveexec_b64 s[2:3], s[0:1]
	s_cbranch_execnz .LBB0_377

; #define LAS __attribute__((address_space(3)))
; __device__ __forceinline__ unsigned pk2(float lo, float hi) { return pg8::cvt_pk_bf16(lo, hi); }
; template <int MASK> ...
;     ...
;     const float sh = off - mn;
;     float rs = 0.f;
; #pragma unroll
;     for (int r = 0; r < 16; ++r) { p0[r] = __builtin_amdgcn_exp2f(fmaf(p0[r], C2, sh)); p1[r] = __builtin_amdgcn_exp2f(fmaf(p1[r], C2, sh)); rs += p0[r] + p1[r]; }
;     l += rs;
;     u32x4 pw[4];
;     pw[0] = (u32x4){pk2(p0[0], p0[1]), pk2(p0[2], p0[3]), pk2(p0[4], p0[5]), pk2(p0[6], p0[7])};
;     pw[1] = (u32x4){pk2(p0[8], p0[9]), pk2(p0[10], p0[11]), pk2(p0[12], p0[13]), pk2(p0[14], p0[15])};
;     pw[2] = (u32x4){pk2(p1[0], p1[1]), pk2(p1[2], p1[3]), pk2(p1[4], p1[5]), pk2(p1[6], p1[7])};
;     pw[3] = (u32x4){pk2(p1[8], p1[9]), pk2(p1[10], p1[11]), pk2(p1[12], p1[13]), pk2(p1[14], p1[15])};
;     LAS const unsigned char* vp = Vb + r32 * 136 + hi * 8;
; #pragma unroll
;     for (int ks = 0; ks < 4; ++ks) {
;         const int koff = (32 * (ks >> 1) + 16 * (ks & 1)) * 2;
;         const s16x4 a0l = *(LAS const s16x4*)(vp + koff), a0h = *(LAS const s16x4*)(vp + koff + 16);
;         const s16x4 a1l = *(LAS const s16x4*)(vp + 32 * 136 + koff), a1h = *(LAS const s16x4*)(vp + 32 * 136 + koff + 16);
;         const bf16x8 A0 = (bf16x8){a0l[0], a0l[1], a0l[2], a0l[3], a0h[0], a0h[1], a0h[2], a0h[3]};
;         const bf16x8 A1 = (bf16x8){a1l[0], a1l[1], a1l[2], a1l[3], a1h[0], a1h[1], a1h[2], a1h[3]};
;         const bf16x8 P = __builtin_bit_cast(bf16x8, pw[ks]);
;         o0 = __builtin_amdgcn_mfma_f32_32x32x16_bf16(A0, P, o0, 0, 0, 0);
;         o1 = __builtin_amdgcn_mfma_f32_32x32x16_bf16(A1, P, o1, 0, 0, 0);
;     }
.LBB0_385:
	v_sub_f32_e32 v112, v64, v43
	v_fmamk_f32 v43, v110, 0x3e38aa3b, v112
	v_exp_f32_e32 v110, v43
	v_fmamk_f32 v43, v111, 0x3e38aa3b, v112
	v_exp_f32_e32 v111, v43
	v_fmamk_f32 v43, v108, 0x3e38aa3b, v112
	v_exp_f32_e32 v64, v43
	v_fmamk_f32 v43, v109, 0x3e38aa3b, v112
	v_exp_f32_e32 v56, v43
	v_add_f32_e32 v57, v111, v110
	v_fmamk_f32 v43, v106, 0x3e38aa3b, v112
	v_fmamk_f32 v42, v42, 0x3e38aa3b, v112
	v_add_f32_e32 v44, v56, v64
	v_add_f32_e32 v45, v57, v65
	v_exp_f32_e32 v57, v43
	v_fmamk_f32 v43, v107, 0x3e38aa3b, v112
	v_add_f32_e32 v46, v44, v44
	v_add_f32_e32 v47, v44, v45
	v_exp_f32_e32 v106, v43
	v_fmamk_f32 v43, v104, 0x3e38aa3b, v112
	v_exp_f32_e32 v46, v43
	v_fmamk_f32 v43, v105, 0x3e38aa3b, v112
	v_exp_f32_e32 v58, v43
	v_add_f32_e32 v59, v106, v57
	v_fmamk_f32 v43, v102, 0x3e38aa3b, v112
	v_fmamk_f32 v40, v40, 0x3e38aa3b, v112
	v_add_f32_e32 v44, v58, v46
	v_add_f32_e32 v45, v59, v47
	v_exp_f32_e32 v47, v43
	v_fmamk_f32 v43, v103, 0x3e38aa3b, v112
	v_add_f32_e32 v60, v44, v44
	v_add_f32_e32 v61, v44, v45
	v_exp_f32_e32 v59, v43
	v_fmamk_f32 v43, v100, 0x3e38aa3b, v112
	v_exp_f32_e32 v60, v43
	v_fmamk_f32 v43, v101, 0x3e38aa3b, v112
	v_exp_f32_e32 v62, v43
	v_add_f32_e32 v63, v59, v47
	v_fmamk_f32 v43, v66, 0x3e38aa3b, v112
	v_fmamk_f32 v38, v38, 0x3e38aa3b, v112
	v_add_f32_e32 v44, v62, v60
	v_add_f32_e32 v45, v63, v61
	v_exp_f32_e32 v61, v43
	v_fmamk_f32 v43, v67, 0x3e38aa3b, v112
	v_add_f32_e32 v100, v44, v44
	v_add_f32_e32 v101, v44, v45
	v_exp_f32_e32 v63, v43
	v_fmamk_f32 v43, v53, 0x3e38aa3b, v112
	v_exp_f32_e32 v100, v43
	v_fmamk_f32 v43, v54, 0x3e38aa3b, v112
	v_exp_f32_e32 v54, v43
	v_add_f32_e32 v55, v63, v61
	v_fmamk_f32 v43, v51, 0x3e38aa3b, v112
	v_fmamk_f32 v34, v34, 0x3e38aa3b, v112
	v_add_f32_e32 v44, v54, v100
	v_add_f32_e32 v45, v55, v101
	v_exp_f32_e32 v55, v43
	v_fmamk_f32 v43, v52, 0x3e38aa3b, v112
	v_add_f32_e32 v66, v44, v44
	v_add_f32_e32 v67, v44, v45
	v_exp_f32_e32 v101, v43
	v_fmamk_f32 v43, v49, 0x3e38aa3b, v112
	v_exp_f32_e32 v66, v43
	v_fmamk_f32 v43, v50, 0x3e38aa3b, v112
	v_exp_f32_e32 v50, v43
	v_add_f32_e32 v51, v101, v55
	v_fmamk_f32 v33, v33, 0x3e38aa3b, v112
	v_add_f32_e32 v44, v50, v66
	v_add_f32_e32 v45, v51, v67
	s_nop 0
	v_add_f32_e32 v52, v44, v44
	v_add_f32_e32 v53, v44, v45
	v_exp_f32_e32 v51, v42
	v_fmamk_f32 v42, v48, 0x3e38aa3b, v112
	v_exp_f32_e32 v67, v42
	v_exp_f32_e32 v52, v40
	v_fmamk_f32 v40, v41, 0x3e38aa3b, v112
	v_exp_f32_e32 v48, v40
	v_add_f32_e32 v49, v67, v51
	v_cvt_pk_bf16_f32 v45, v57, v46
	v_cvt_pk_bf16_f32 v46, v47, v60
	v_add_f32_e32 v40, v48, v52
	v_add_f32_e32 v41, v49, v53
	v_exp_f32_e32 v49, v38
	v_add_f32_e32 v42, v40, v40
	v_add_f32_e32 v43, v40, v41
	v_fmamk_f32 v38, v39, 0x3e38aa3b, v112
	v_exp_f32_e32 v53, v38
	v_exp_f32_e32 v42, v34
	v_fmamk_f32 v34, v36, 0x3e38aa3b, v112
	v_exp_f32_e32 v102, v34
	v_add_f32_e32 v103, v53, v49
	v_fmamk_f32 v34, v35, 0x3e38aa3b, v112
	v_fmamk_f32 v35, v37, 0x3e38aa3b, v112
	v_add_f32_e32 v38, v102, v42
	v_add_f32_e32 v39, v103, v43
	v_exp_f32_e32 v34, v34
	v_add_f32_e32 v39, v38, v39
	v_add_f32_e32 v38, v38, v38
	v_exp_f32_e32 v35, v35
	v_fmac_f32_e32 v112, 0x3e38aa3b, v32
	v_exp_f32_e32 v38, v33
	v_exp_f32_e32 v104, v112
	v_add_f32_e32 v105, v35, v34
	v_add_u32_e32 v60, 0xc000, v130
	v_cvt_pk_bf16_f32 v41, v51, v52
	v_add_f32_e32 v32, v104, v38
	v_add_f32_e32 v33, v105, v39
	v_cvt_pk_bf16_f32 v42, v49, v42
	v_add_f32_e32 v32, v32, v33
	v_add_f32_e32 v135, v32, v135
	v_cvt_pk_bf16_f32 v32, v101, v50
	v_cvt_pk_bf16_f32 v33, v67, v48
	ds_read2_b64 v[48:51], v60 offset0:32 offset1:34
	v_cvt_pk_bf16_f32 v47, v61, v100
	v_add_u32_e32 v61, 0xb000, v130
	v_cvt_pk_bf16_f32 v40, v55, v66
	v_cvt_pk_bf16_f32 v43, v34, v38
	v_cvt_pk_bf16_f32 v36, v111, v56
	v_cvt_pk_bf16_f32 v37, v106, v58
	v_cvt_pk_bf16_f32 v38, v59, v62
	v_cvt_pk_bf16_f32 v39, v63, v54
	v_cvt_pk_bf16_f32 v34, v53, v102
	ds_read2_b64 v[52:55], v61 offset1:2
	ds_read2_b64 v[56:59], v61 offset0:4 offset1:6
	v_cvt_pk_bf16_f32 v44, v110, v64
	v_cvt_pk_bf16_f32 v35, v35, v104
	s_waitcnt lgkmcnt(1)
	v_mfma_f32_32x32x16_bf16 v[16:31], v[52:55], v[44:47], v[16:31]
	v_mfma_f32_32x32x16_bf16 v[0:15], v[48:51], v[44:47], v[0:15]
	ds_read2_b64 v[44:47], v60 offset0:36 offset1:38
	s_waitcnt lgkmcnt(1)
	v_mfma_f32_32x32x16_bf16 v[16:31], v[56:59], v[40:43], v[16:31]
	s_waitcnt lgkmcnt(0)
	v_mfma_f32_32x32x16_bf16 v[0:15], v[44:47], v[40:43], v[0:15]
	ds_read2_b64 v[40:43], v61 offset0:8 offset1:10
	ds_read2_b64 v[44:47], v60 offset0:40 offset1:42
	s_waitcnt lgkmcnt(1)
	v_mfma_f32_32x32x16_bf16 v[16:31], v[40:43], v[36:39], v[16:31]
	s_waitcnt lgkmcnt(0)
	v_mfma_f32_32x32x16_bf16 v[0:15], v[44:47], v[36:39], v[0:15]
	ds_read2_b64 v[36:39], v61 offset0:12 offset1:14
	ds_read2_b64 v[40:43], v60 offset0:44 offset1:46
	s_waitcnt lgkmcnt(1)
	v_mfma_f32_32x32x16_bf16 v[16:31], v[36:39], v[32:35], v[16:31]
	s_waitcnt lgkmcnt(0)
	v_mfma_f32_32x32x16_bf16 v[0:15], v[40:43], v[32:35], v[0:15]
; __device__ __forceinline__ unsigned pk2(float lo, float hi) { return pg8::cvt_pk_bf16(lo, hi); }
; #define WG_BAR() __syncthreads()
; __device__ __forceinline__ void attn_store(bf16* yrow, const f32x16& o0, const f32x16& o1, float inv, int hi) {
; #pragma unroll
;     for (int rg = 0; rg < 4; ++rg) {
;         u32x2 w0, w1;
;         w0.x = pk2(o0[4 * rg] * inv, o0[4 * rg + 1] * inv); w0.y = pk2(o0[4 * rg + 2] * inv, o0[4 * rg + 3] * inv);
;         w1.x = pk2(o1[4 * rg] * inv, o1[4 * rg + 1] * inv); w1.y = pk2(o1[4 * rg + 2] * inv, o1[4 * rg + 3] * inv);
;         *(u32x2*)(yrow + 8 * rg + 4 * hi) = w0; *(u32x2*)(yrow + 32 + 8 * rg + 4 * hi) = w1;
;     }
; }
; __device__ __forceinline__ void swa_phase(int first, int stride, const bf16* qkv, bf16* Y, const float* sinks, LAS unsigned char* lds) {
;     ...
;         const float lt = l + __shfl_xor(l, 32);
;         attn_store(Y + row * 1536 + head * 64, o0, o1, 1.f / lt, hi);
;         WG_BAR();
.LBB0_386:
	ds_bpermute_b32 v32, v126, v135
	v_readlane_b32 s0, v252, 9
	v_readlane_b32 s1, v252, 10
	s_movk_i32 s2, 0xc00
	v_lshlrev_b32_e32 v64, 1, v118
	s_waitcnt lgkmcnt(0)
	v_add_f32_e32 v36, v135, v32
	v_mov_b64_e32 v[32:33], s[0:1]
	v_mad_u64_u32 v[32:33], s[0:1], v132, s2, v[32:33]
	v_mov_b32_e32 v34, v33
	v_mad_u64_u32 v[34:35], s[0:1], v133, s2, v[34:35]
	v_mov_b32_e32 v33, v34
	v_div_scale_f32 v34, s[0:1], v36, v36, 1.0
	v_rcp_f32_e32 v35, v34
	v_lshl_add_u64 v[32:33], v[120:121], 1, v[32:33]
	v_lshl_add_u64 v[32:33], v[32:33], 0, v[64:65]
	v_fma_f32 v37, -v34, v35, 1.0
	v_fmac_f32_e32 v35, v37, v35
	v_div_scale_f32 v37, vcc, 1.0, v36, 1.0
	v_mul_f32_e32 v38, v37, v35
	v_fma_f32 v39, -v34, v38, v37
	v_fmac_f32_e32 v38, v39, v35
	v_fma_f32 v34, -v34, v38, v37
	v_div_fmas_f32 v34, v34, v35, v38
	v_div_fixup_f32 v34, v34, v36, 1.0
	v_mul_f32_e32 v16, v16, v34
	v_mul_f32_e32 v17, v17, v34
	v_mul_f32_e32 v18, v18, v34
	v_mul_f32_e32 v19, v19, v34
	v_mul_f32_e32 v0, v0, v34
	v_mul_f32_e32 v1, v1, v34
	v_mul_f32_e32 v2, v2, v34
	v_mul_f32_e32 v3, v3, v34
	v_cvt_pk_bf16_f32 v16, v16, v17
	v_cvt_pk_bf16_f32 v17, v18, v19
	v_cvt_pk_bf16_f32 v0, v0, v1
	v_cvt_pk_bf16_f32 v1, v2, v3
	global_store_dwordx2 v[32:33], v[16:17], off
	global_store_dwordx2 v[32:33], v[0:1], off offset:64
	v_mul_f32_e32 v0, v20, v34
	v_mul_f32_e32 v1, v21, v34
	v_mul_f32_e32 v2, v22, v34
	v_mul_f32_e32 v3, v23, v34
	v_cvt_pk_bf16_f32 v0, v0, v1
	v_cvt_pk_bf16_f32 v1, v2, v3
	v_mul_f32_e32 v2, v4, v34
	v_mul_f32_e32 v3, v5, v34
	v_mul_f32_e32 v4, v6, v34
	v_mul_f32_e32 v5, v7, v34
	v_cvt_pk_bf16_f32 v2, v2, v3
	v_cvt_pk_bf16_f32 v3, v4, v5
	global_store_dwordx2 v[32:33], v[0:1], off offset:16
	global_store_dwordx2 v[32:33], v[2:3], off offset:80
	v_mul_f32_e32 v0, v24, v34
	v_mul_f32_e32 v1, v25, v34
	v_mul_f32_e32 v2, v26, v34
	v_mul_f32_e32 v3, v27, v34
	v_cvt_pk_bf16_f32 v0, v0, v1
	v_cvt_pk_bf16_f32 v1, v2, v3
	v_mul_f32_e32 v2, v8, v34
	v_mul_f32_e32 v3, v9, v34
	v_mul_f32_e32 v4, v10, v34
	v_mul_f32_e32 v5, v11, v34
	v_cvt_pk_bf16_f32 v2, v2, v3
	v_cvt_pk_bf16_f32 v3, v4, v5
	global_store_dwordx2 v[32:33], v[0:1], off offset:32
	global_store_dwordx2 v[32:33], v[2:3], off offset:96
	v_mul_f32_e32 v0, v28, v34
	v_mul_f32_e32 v1, v29, v34
	v_mul_f32_e32 v2, v30, v34
	v_mul_f32_e32 v3, v31, v34
	v_cvt_pk_bf16_f32 v0, v0, v1
	v_cvt_pk_bf16_f32 v1, v2, v3
	v_mul_f32_e32 v2, v12, v34
	v_mul_f32_e32 v3, v13, v34
	v_mul_f32_e32 v4, v14, v34
	v_mul_f32_e32 v5, v15, v34
	s_andn2_b64 vcc, exec, s[54:55]
	v_cvt_pk_bf16_f32 v2, v2, v3
	v_cvt_pk_bf16_f32 v3, v4, v5
	global_store_dwordx2 v[32:33], v[0:1], off offset:48
	global_store_dwordx2 v[32:33], v[2:3], off offset:112
	s_barrier
	s_cbranch_vccz .LBB0_405

; template <int MASK> ...
;     f32x16 p0, p1;
; #pragma unroll
;     for (int r = 0; r < 16; ++r) { p0[r] = 0.f; p1[r] = 0.f; }
;     p0 = __builtin_amdgcn_mfma_f32_32x32x16_bf16(kx0, qx, p0, 0, 0, 0);
;     p1 = __builtin_amdgcn_mfma_f32_32x32x16_bf16(kx1, qx, p1, 0, 0, 0);
;     LAS const unsigned char* kp = Kb + r32 * 144 + hi * 16;
; #pragma unroll
;     for (int d0 = 0; d0 < 4; ++d0) {
;         const bf16x8 a0 = *(LAS const bf16x8*)(kp + d0 * 32), a1 = *(LAS const bf16x8*)(kp + 32 * 144 + d0 * 32);
;         p0 = __builtin_amdgcn_mfma_f32_32x32x16_bf16(a0, qf[d0], p0, 0, 0, 0);
;         p1 = __builtin_amdgcn_mfma_f32_32x32x16_bf16(a1, qf[d0], p1, 0, 0, 0);
;     }
;     constexpr float C2 = 0.125f * LOG2E;
;     const float NEG = -INFINITY;
;     if (MASK != 0) {
;         const int dk0 = kq + 4 * hi;
; #pragma unroll
;         for (int r = 0; r < 16; ++r) { const int kk = (r & 3) + 8 * (r >> 2);
;             if (MASK == 1) { if (dk0 > -kk) p0[r] = NEG; if (dk0 > -(kk + 32)) p1[r] = NEG; }
;             if (MASK == 3) { if (dk0 <= -128 - kk) p0[r] = NEG; if (dk0 <= -160 - kk) p1[r] = NEG; } }
;     }
;     float mr = fmaxf(p0[0], p1[0]);
; #pragma unroll
;     for (int r = 1; r < 16; ++r) mr = fmaxf(fmaxf(mr, p0[r]), p1[r]);
; __device__ __forceinline__ void swa_phase(int first, int stride, const bf16* qkv, bf16* Y, const float* sinks, LAS unsigned char* lds) {
;     ...
;         const float sl2 = exp2f(-0.5f * (float)(head + 1)) * LOG2E;
;         float m = sinks[head] * LOG2E, l = (hi == 0) ? 1.f : 0.f;
;         f32x16 o0, o1;
; #pragma unroll
;         for (int r = 0; r < 16; ++r) { o0[r] = 0.f; o1[r] = 0.f; }
;         bf16x8 kx0, kx1, qx;
;         { const float xs = sl2 * (1.f / (0.125f * LOG2E)); const unsigned shb = pk2(xs, 0.f) & 0xffffu; const float res = xs - __uint_as_float(shb << 16);
;           const unsigned qw = (hi == 0) ? (shb | (pk2(res, 0.f) << 16)) : 0u;
;           const unsigned k0w = (hi == 0) ? pk2((float)r32, (float)r32) : 0u, k1w = (hi == 0) ? pk2((float)(r32 + 32), (float)(r32 + 32)) : 0u;
;           qx = __builtin_bit_cast(bf16x8, (u32x4){qw, 0u, 0u, 0u}); kx0 = __builtin_bit_cast(bf16x8, (u32x4){k0w, 0u, 0u, 0u}); kx1 = __builtin_bit_cast(bf16x8, (u32x4){k1w, 0u, 0u, 0u}); }
;         { const int kq = 64 * tb - qtok; attn_tile_fast<1>(lds, lds + SV0, qf, kx0, kx1, qx, o0, o1, m, l, kq, sl2 * (float)kq, r32, hi); }
.LBB0_396:
	v_ashrrev_i32_e32 v1, 31, v0
	v_lshl_add_u64 v[4:5], v[0:1], 2, s[38:39]
	global_load_dword v33, v[4:5], off
	v_add_u32_e32 v0, 1, v0
	v_cvt_f32_i32_e32 v0, v0
	s_mov_b32 s0, 0xc2fc0000
	s_movk_i32 s13, 0xffc6
	s_movk_i32 s12, 0xffe6
	v_mul_f32_e32 v1, -0.5, v0
	v_cmp_gt_f32_e32 vcc, s0, v1
	v_mov_b32_e32 v64, 0
	s_nop 0
	v_cndmask_b32_e32 v1, 0, v227, vcc
	v_fmac_f32_e32 v1, -0.5, v0
	v_exp_f32_e32 v0, v1
	v_cndmask_b32_e32 v1, 0, v229, vcc
	v_ldexp_f32 v0, v0, v1
	v_mul_f32_e32 v134, 0x3fb8aa3b, v0
	s_and_saveexec_b64 s[0:1], s[4:5]
	v_mul_f32_e32 v0, 0x40b17218, v134
	v_cvt_pk_bf16_f32 v0, v0, 0
	v_and_b32_e32 v1, 0xffff, v0
	v_lshlrev_b32_e32 v0, 16, v0
	s_mov_b32 s3, 0x40b17218
	v_fma_f32 v0, v134, s3, -v0
	v_cvt_pk_bf16_f32 v0, v0, 0
	v_lshl_or_b32 v64, v0, 16, v1
	s_or_b64 exec, exec, s[0:1]
	v_mov_b32_e32 v66, v65
	v_mov_b32_e32 v67, v65
	v_sub_u32_e32 v48, s2, v2
	ds_read_b128 v[36:39], v129 offset:4608
	ds_read_b128 v[40:43], v129
	ds_read_b128 v[44:47], v129 offset:32
	v_mfma_f32_32x32x16_bf16 v[16:31], v[92:95], v[64:67], 0
	s_movk_i32 s0, 0xffdd
	v_cvt_f32_i32_e32 v32, v48
	s_waitcnt vmcnt(0)
	v_mul_f32_e32 v34, 0x3fb8aa3b, v33
	v_mul_f32_e32 v35, v134, v32
	v_mfma_f32_32x32x16_bf16 v[0:15], v[96:99], v[64:67], 0
	s_waitcnt lgkmcnt(1)
	v_mfma_f32_32x32x16_bf16 v[16:31], v[40:43], v[112:115], v[16:31]
	v_mfma_f32_32x32x16_bf16 v[0:15], v[36:39], v[112:115], v[0:15]
	ds_read_b128 v[36:39], v129 offset:4640
	s_waitcnt lgkmcnt(1)
	v_mfma_f32_32x32x16_bf16 v[16:31], v[44:47], v[108:111], v[16:31]
	s_waitcnt lgkmcnt(0)
	v_mfma_f32_32x32x16_bf16 v[0:15], v[36:39], v[108:111], v[0:15]
	ds_read_b128 v[36:39], v129 offset:64
	ds_read_b128 v[40:43], v129 offset:4672
	s_waitcnt lgkmcnt(1)
	v_mfma_f32_32x32x16_bf16 v[16:31], v[36:39], v[104:107], v[16:31]
	s_waitcnt lgkmcnt(0)
	v_mfma_f32_32x32x16_bf16 v[0:15], v[40:43], v[104:107], v[0:15]
	ds_read_b128 v[36:39], v129 offset:96
	ds_read_b128 v[40:43], v129 offset:4704
	s_waitcnt lgkmcnt(1)
	v_mfma_f32_32x32x16_bf16 v[16:31], v[36:39], v[100:103], v[16:31]
	v_add_u32_e32 v38, v48, v118
	v_cmp_lt_i32_e64 s[76:77], s0, v38
	s_movk_i32 s0, 0xffd6
	v_cmp_lt_i32_e64 s[82:83], s0, v38
	s_movk_i32 s0, 0xffd5
	v_cmp_lt_i32_e64 s[84:85], s0, v38
	s_movk_i32 s0, 0xffd0
	v_cmp_lt_i32_e64 s[86:87], s0, v38
	s_movk_i32 s0, 0xffcf
	v_cmp_lt_i32_e64 s[22:23], s88, v38
	v_cmp_lt_i32_e64 s[88:89], s0, v38
	s_movk_i32 s0, 0xffce
	v_cmp_gt_i32_e32 vcc, 1, v38
	v_cmp_gt_i32_e64 s[6:7], 0, v38
	v_cmp_lt_i32_e64 s[24:25], s90, v38
	v_cmp_lt_i32_e64 s[90:91], s0, v38
	s_movk_i32 s0, 0xffed
	s_or_b64 vcc, s[6:7], vcc
	v_cmp_lt_i32_e64 s[26:27], s0, v38
	s_movk_i32 s0, 0xffcd
	v_cndmask_b32_e32 v37, v228, v16, vcc
	v_cndmask_b32_e64 v36, v228, v17, s[6:7]
	v_cmp_lt_i32_e64 s[92:93], s0, v38
	s_movk_i32 s0, 0xffc8
	s_movk_i32 s6, 0xffc7
	v_cmp_lt_i32_e32 vcc, s12, v38
	s_movk_i32 s12, 0xffe5
	v_cmp_lt_i32_e64 s[28:29], s94, v38
	v_cmp_lt_i32_e64 s[94:95], s0, v38
	v_cmp_lt_i32_e64 s[0:1], s96, v38
	v_cmp_lt_i32_e64 s[96:97], s6, v38
	v_cmp_lt_i32_e64 s[6:7], s13, v38
	v_cmp_lt_i32_e64 s[12:13], s12, v38
	s_and_b64 vcc, s[12:13], vcc
	s_and_b64 s[0:1], vcc, s[0:1]
	s_and_b64 s[28:29], s[0:1], s[28:29]
	s_and_b64 s[26:27], s[28:29], s[26:27]
	s_and_b64 s[24:25], s[26:27], s[24:25]
	v_cmp_lt_i32_e64 s[20:21], -16, v38
	s_and_b64 s[22:23], s[24:25], s[22:23]
	v_cmp_lt_i32_e64 s[18:19], -11, v38
	s_and_b64 s[20:21], s[22:23], s[20:21]
	s_waitcnt lgkmcnt(0)
	v_mfma_f32_32x32x16_bf16 v[0:15], v[40:43], v[100:103], v[0:15]
	v_cmp_lt_i32_e64 s[16:17], -10, v38
	s_and_b64 s[18:19], s[20:21], s[18:19]
	v_cmp_lt_i32_e64 s[14:15], -9, v38
	s_and_b64 s[16:17], s[18:19], s[16:17]
	v_cmp_lt_i32_e64 s[10:11], -8, v38
	s_and_b64 s[14:15], s[16:17], s[14:15]
	v_cmp_lt_i32_e64 s[8:9], -3, v38
	s_and_b64 s[10:11], s[14:15], s[10:11]
	v_cmp_lt_i32_e64 s[2:3], -2, v38
	s_and_b64 s[8:9], s[10:11], s[8:9]
	s_and_b64 s[2:3], s[8:9], s[2:3]
	v_cndmask_b32_e64 v29, v29, v228, s[0:1]
	s_movk_i32 s0, 0xffc5
	v_cndmask_b32_e64 v36, v17, v36, s[2:3]
	v_cndmask_b32_e32 v17, v30, v228, vcc
	v_cmp_lt_i32_e32 vcc, s0, v38
	s_and_b64 s[0:1], vcc, s[6:7]
	v_cndmask_b32_e64 v30, v14, v228, s[0:1]
	s_and_b64 s[0:1], s[0:1], s[96:97]
	v_cndmask_b32_e64 v37, v16, v37, s[2:3]
	v_cndmask_b32_e64 v16, v31, v228, s[12:13]
	v_cndmask_b32_e64 v31, v13, v228, s[0:1]
	s_and_b64 s[0:1], s[0:1], s[94:95]
	v_cmp_lt_i32_e64 s[30:31], s75, v38
	v_cmp_lt_i32_e64 s[72:73], s72, v38
	v_cmp_lt_i32_e64 s[74:75], s74, v38
	v_cmp_lt_i32_e64 s[78:79], s78, v38
	v_cmp_lt_i32_e64 s[80:81], s80, v38
	v_cndmask_b32_e64 v38, v12, v228, s[0:1]
	s_and_b64 s[0:1], s[0:1], s[92:93]
	v_cndmask_b32_e64 v39, v11, v228, s[0:1]
	s_and_b64 s[0:1], s[0:1], s[90:91]
	v_cndmask_b32_e64 v40, v10, v228, s[0:1]
	s_and_b64 s[0:1], s[0:1], s[88:89]
	v_cndmask_b32_e64 v41, v9, v228, s[0:1]
	s_and_b64 s[0:1], s[0:1], s[86:87]
	v_cndmask_b32_e64 v42, v8, v228, s[0:1]
	s_and_b64 s[0:1], s[0:1], s[84:85]
	v_cndmask_b32_e64 v43, v7, v228, s[0:1]
	s_and_b64 s[0:1], s[0:1], s[82:83]
	v_cndmask_b32_e64 v44, v6, v228, s[0:1]
	s_and_b64 s[0:1], s[0:1], s[80:81]
	v_cndmask_b32_e64 v45, v5, v228, s[0:1]
	s_and_b64 s[0:1], s[0:1], s[78:79]
	v_cndmask_b32_e64 v46, v4, v228, s[0:1]
	s_and_b64 s[0:1], s[0:1], s[76:77]
	v_cndmask_b32_e64 v47, v3, v228, s[0:1]
	s_and_b64 s[0:1], s[0:1], s[74:75]
	v_cndmask_b32_e64 v48, v2, v228, s[0:1]
	s_and_b64 s[0:1], s[0:1], s[72:73]
	v_cndmask_b32_e64 v49, v1, v228, s[0:1]
	s_and_b64 s[0:1], s[0:1], s[30:31]
	v_cndmask_b32_e64 v50, v0, v228, s[0:1]
	v_max_f32_e32 v0, v37, v37
	v_max_f32_e32 v1, v50, v50
	v_max_f32_e32 v0, v0, v1
	v_cndmask_b32_e64 v18, v18, v228, s[2:3]
	v_max3_f32 v0, v0, v36, v49
	v_cndmask_b32_e64 v19, v19, v228, s[8:9]
	v_max3_f32 v0, v0, v18, v48
	v_cndmask_b32_e64 v20, v20, v228, s[10:11]
	v_max3_f32 v0, v0, v19, v47
	v_cndmask_b32_e64 v21, v21, v228, s[14:15]
	v_max3_f32 v0, v0, v20, v46
	v_cndmask_b32_e64 v22, v22, v228, s[16:17]
	v_max3_f32 v0, v0, v21, v45
	v_cndmask_b32_e64 v23, v23, v228, s[18:19]
	v_max3_f32 v0, v0, v22, v44
	v_cndmask_b32_e64 v24, v24, v228, s[20:21]
	v_max3_f32 v0, v0, v23, v43
	v_cndmask_b32_e64 v25, v25, v228, s[22:23]
	v_max3_f32 v0, v0, v24, v42
	v_cndmask_b32_e64 v26, v26, v228, s[24:25]
	v_max3_f32 v0, v0, v25, v41
	v_cndmask_b32_e64 v27, v27, v228, s[26:27]
	v_max3_f32 v0, v0, v26, v40
	v_cndmask_b32_e64 v28, v28, v228, s[28:29]
	v_max3_f32 v0, v0, v27, v39
	v_max3_f32 v0, v0, v28, v38
	v_max3_f32 v0, v0, v29, v31
	v_cndmask_b32_e32 v60, v15, v228, vcc
	v_max3_f32 v0, v0, v17, v30
	v_max3_f32 v0, v0, v16, v60
	v_fmac_f32_e32 v35, 0x3e38aa3b, v0
	ds_bpermute_b32 v0, v126, v35
	s_mov_b32 s2, 0x3fb8aa3b
	s_waitcnt lgkmcnt(0)
; #define LAS __attribute__((address_space(3)))
; __device__ __forceinline__ unsigned pk2(float lo, float hi) { return pg8::cvt_pk_bf16(lo, hi); }
; template <int MASK> ...
;     ...
;     float mr = fmaxf(p0[0], p1[0]);
; #pragma unroll
;     for (int r = 1; r < 16; ++r) mr = fmaxf(fmaxf(mr, p0[r]), p1[r]);
;     float mx = fmaf(mr, C2, off);
;     mx = fmaxf(mx, __shfl_xor(mx, 32));
;     const float mn = fmaxf(m, mx);
;     if (__ballot(mn > m) != 0ull) {
;         const float alpha = __builtin_amdgcn_exp2f(m - mn); l *= alpha;
; #pragma unroll
;         for (int r = 0; r < 16; ++r) { o0[r] *= alpha; o1[r] *= alpha; }
;     }
;     m = mn;
;     const float sh = off - mn;
;     float rs = 0.f;
; #pragma unroll
;     for (int r = 0; r < 16; ++r) { p0[r] = __builtin_amdgcn_exp2f(fmaf(p0[r], C2, sh)); p1[r] = __builtin_amdgcn_exp2f(fmaf(p1[r], C2, sh)); rs += p0[r] + p1[r]; }
;     l += rs;
;     u32x4 pw[4];
;     pw[0] = (u32x4){pk2(p0[0], p0[1]), pk2(p0[2], p0[3]), pk2(p0[4], p0[5]), pk2(p0[6], p0[7])};
;     pw[1] = (u32x4){pk2(p0[8], p0[9]), pk2(p0[10], p0[11]), pk2(p0[12], p0[13]), pk2(p0[14], p0[15])};
;     pw[2] = (u32x4){pk2(p1[0], p1[1]), pk2(p1[2], p1[3]), pk2(p1[4], p1[5]), pk2(p1[6], p1[7])};
;     pw[3] = (u32x4){pk2(p1[8], p1[9]), pk2(p1[10], p1[11]), pk2(p1[12], p1[13]), pk2(p1[14], p1[15])};
;     LAS const unsigned char* vp = Vb + r32 * 136 + hi * 8;
; #pragma unroll
;     for (int ks = 0; ks < 4; ++ks) {
;         const int koff = (32 * (ks >> 1) + 16 * (ks & 1)) * 2;
;         const s16x4 a0l = *(LAS const s16x4*)(vp + koff), a0h = *(LAS const s16x4*)(vp + koff + 16);
;         const s16x4 a1l = *(LAS const s16x4*)(vp + 32 * 136 + koff), a1h = *(LAS const s16x4*)(vp + 32 * 136 + koff + 16);
;         const bf16x8 A0 = (bf16x8){a0l[0], a0l[1], a0l[2], a0l[3], a0h[0], a0h[1], a0h[2], a0h[3]};
;         const bf16x8 A1 = (bf16x8){a1l[0], a1l[1], a1l[2], a1l[3], a1h[0], a1h[1], a1h[2], a1h[3]};
;         const bf16x8 P = __builtin_bit_cast(bf16x8, pw[ks]);
;         o0 = __builtin_amdgcn_mfma_f32_32x32x16_bf16(A0, P, o0, 0, 0, 0);
;         o1 = __builtin_amdgcn_mfma_f32_32x32x16_bf16(A1, P, o1, 0, 0, 0);
;     }
	v_max3_f32 v137, v34, v35, v0
	v_fma_f32 v62, v134, v32, -v137
	v_fmamk_f32 v32, v37, 0x3e38aa3b, v62
	v_exp_f32_e32 v63, v32
	v_fmamk_f32 v32, v50, 0x3e38aa3b, v62
	v_exp_f32_e32 v136, v32
	v_fmamk_f32 v32, v36, 0x3e38aa3b, v62
	v_cmp_gt_f32_e32 vcc, v137, v34
	v_exp_f32_e32 v34, v32
	v_fmamk_f32 v32, v49, 0x3e38aa3b, v62
	v_exp_f32_e32 v32, v32
	v_fma_f32 v0, v33, s2, -v137
	v_add_f32_e32 v33, v136, v63
	v_mov_b32_e32 v35, v65
	v_fmamk_f32 v18, v18, 0x3e38aa3b, v62
	v_add_f32_e32 v36, v32, v34
	v_add_f32_e32 v37, v33, v35
	v_exp_f32_e32 v33, v18
	v_fmamk_f32 v18, v48, 0x3e38aa3b, v62
	v_add_f32_e32 v37, v36, v37
	v_add_f32_e32 v36, v36, v36
	v_exp_f32_e32 v35, v18
	v_fmamk_f32 v18, v19, 0x3e38aa3b, v62
	v_exp_f32_e32 v36, v18
	v_fmamk_f32 v18, v47, 0x3e38aa3b, v62
	v_exp_f32_e32 v48, v18
	v_add_f32_e32 v49, v35, v33
	v_fmamk_f32 v17, v17, 0x3e38aa3b, v62
	v_fmamk_f32 v16, v16, 0x3e38aa3b, v62
	v_add_f32_e32 v18, v48, v36
	v_add_f32_e32 v19, v49, v37
	v_exp_f32_e32 v0, v0
	v_add_f32_e32 v19, v18, v19
	v_add_f32_e32 v18, v18, v18
	v_fmamk_f32 v18, v20, 0x3e38aa3b, v62
	v_exp_f32_e32 v37, v18
	v_fmamk_f32 v18, v46, 0x3e38aa3b, v62
	v_exp_f32_e32 v49, v18
	v_fmamk_f32 v18, v21, 0x3e38aa3b, v62
	v_fmamk_f32 v20, v45, 0x3e38aa3b, v62
	v_exp_f32_e32 v18, v18
	v_exp_f32_e32 v50, v20
	v_add_f32_e32 v51, v49, v37
	s_cmp_eq_u64 vcc, 0
	v_cvt_pk_bf16_f32 v46, v37, v18
	v_add_f32_e32 v20, v50, v18
	v_add_f32_e32 v21, v51, v19
	v_fmamk_f32 v19, v22, 0x3e38aa3b, v62
	v_add_f32_e32 v21, v20, v21
	v_add_f32_e32 v20, v20, v20
	v_fmamk_f32 v20, v44, 0x3e38aa3b, v62
	v_exp_f32_e32 v19, v19
	v_exp_f32_e32 v51, v20
	v_fmamk_f32 v20, v23, 0x3e38aa3b, v62
	v_fmamk_f32 v22, v43, 0x3e38aa3b, v62
	v_exp_f32_e32 v20, v20
	v_exp_f32_e32 v52, v22
	v_add_f32_e32 v53, v51, v19
	v_cvt_pk_bf16_f32 v37, v35, v48
	s_cselect_b64 s[0:1], -1, 0
	v_add_f32_e32 v22, v52, v20
	v_add_f32_e32 v23, v53, v21
	v_fmamk_f32 v21, v24, 0x3e38aa3b, v62
	v_add_f32_e32 v23, v22, v23
	v_add_f32_e32 v22, v22, v22
	v_fmamk_f32 v22, v42, 0x3e38aa3b, v62
	v_exp_f32_e32 v21, v21
	v_exp_f32_e32 v53, v22
	v_fmamk_f32 v22, v25, 0x3e38aa3b, v62
	v_fmamk_f32 v24, v41, 0x3e38aa3b, v62
	v_exp_f32_e32 v22, v22
	v_exp_f32_e32 v54, v24
	v_add_f32_e32 v55, v53, v21
	v_cndmask_b32_e64 v61, v0, 1.0, s[0:1]
	v_cvt_pk_bf16_f32 v44, v63, v34
	v_add_f32_e32 v24, v54, v22
	v_add_f32_e32 v25, v55, v23
	v_fmamk_f32 v23, v26, 0x3e38aa3b, v62
	v_add_f32_e32 v25, v24, v25
	v_add_f32_e32 v24, v24, v24
	v_fmamk_f32 v24, v40, 0x3e38aa3b, v62
	v_exp_f32_e32 v23, v23
	v_exp_f32_e32 v55, v24
	v_fmamk_f32 v24, v27, 0x3e38aa3b, v62
	v_fmamk_f32 v26, v39, 0x3e38aa3b, v62
	v_exp_f32_e32 v24, v24
	v_exp_f32_e32 v56, v26
	v_add_f32_e32 v57, v55, v23
	v_cvt_pk_bf16_f32 v39, v51, v52
	v_cvt_pk_bf16_f32 v45, v33, v36
	v_add_f32_e32 v26, v56, v24
	v_add_f32_e32 v27, v57, v25
	v_fmamk_f32 v25, v28, 0x3e38aa3b, v62
	v_add_f32_e32 v27, v26, v27
	v_add_f32_e32 v26, v26, v26
	v_fmamk_f32 v26, v38, 0x3e38aa3b, v62
	v_exp_f32_e32 v25, v25
	v_exp_f32_e32 v57, v26
	v_fmamk_f32 v26, v29, 0x3e38aa3b, v62
	v_fmamk_f32 v28, v31, 0x3e38aa3b, v62
	v_exp_f32_e32 v26, v26
	v_exp_f32_e32 v58, v28
	v_add_f32_e32 v59, v57, v25
	v_cvt_pk_bf16_f32 v38, v49, v50
	v_cvt_pk_bf16_f32 v36, v136, v32
	v_add_f32_e32 v28, v58, v26
	v_add_f32_e32 v29, v59, v27
	v_exp_f32_e32 v27, v17
	v_fmamk_f32 v17, v30, 0x3e38aa3b, v62
	v_add_f32_e32 v29, v28, v29
	v_add_f32_e32 v28, v28, v28
	v_exp_f32_e32 v59, v17
	v_fmac_f32_e32 v62, 0x3e38aa3b, v60
	v_exp_f32_e32 v28, v16
	v_exp_f32_e32 v16, v62
	v_add_u32_e32 v60, 0x7800, v130
	ds_read2_b64 v[48:51], v60 offset0:160 offset1:162
	v_add_f32_e32 v17, v59, v27
	v_add_f32_e32 v30, v16, v28
	v_add_f32_e32 v31, v17, v29
	v_cvt_pk_bf16_f32 v32, v53, v54
	v_add_f32_e32 v135, v30, v31
	v_fmac_f32_e32 v135, v125, v61
	v_add_u32_e32 v61, 0x6800, v130
	v_cvt_pk_bf16_f32 v33, v55, v56
	v_cvt_pk_bf16_f32 v34, v57, v58
	v_cvt_pk_bf16_f32 v35, v59, v16
	ds_read2_b64 v[52:55], v61 offset0:128 offset1:130
	ds_read2_b64 v[56:59], v61 offset0:132 offset1:134
	v_mul_f32_e32 v1, 0, v0
	v_cndmask_b32_e64 v0, v1, 0, s[0:1]
	v_mov_b32_e32 v1, v0
	v_mov_b32_e32 v2, v0
	v_mov_b32_e32 v3, v0
	v_mov_b32_e32 v4, v0
	v_mov_b32_e32 v5, v0
	v_mov_b32_e32 v6, v0
	v_mov_b32_e32 v7, v0
	v_mov_b32_e32 v8, v0
	v_mov_b32_e32 v9, v0
	v_mov_b32_e32 v10, v0
	v_mov_b32_e32 v11, v0
	v_mov_b32_e32 v12, v0
	v_mov_b32_e32 v13, v0
	v_mov_b32_e32 v14, v0
	v_mov_b32_e32 v15, v0
	v_cvt_pk_bf16_f32 v47, v19, v20
	v_cvt_pk_bf16_f32 v40, v21, v22
	v_cvt_pk_bf16_f32 v41, v23, v24
	v_cvt_pk_bf16_f32 v42, v25, v26
	v_cvt_pk_bf16_f32 v43, v27, v28
	s_waitcnt lgkmcnt(1)
	v_mfma_f32_32x32x16_bf16 v[16:31], v[52:55], v[44:47], v[0:15]
	s_andn2_b64 vcc, exec, s[44:45]
	v_mfma_f32_32x32x16_bf16 v[0:15], v[48:51], v[44:47], v[0:15]
	ds_read2_b64 v[44:47], v60 offset0:164 offset1:166
	s_waitcnt lgkmcnt(1)
	v_mfma_f32_32x32x16_bf16 v[16:31], v[56:59], v[40:43], v[16:31]
	s_waitcnt lgkmcnt(0)
	v_mfma_f32_32x32x16_bf16 v[0:15], v[44:47], v[40:43], v[0:15]
	ds_read2_b64 v[40:43], v61 offset0:136 offset1:138
	ds_read2_b64 v[44:47], v60 offset0:168 offset1:170
	s_waitcnt lgkmcnt(1)
	v_mfma_f32_32x32x16_bf16 v[16:31], v[40:43], v[36:39], v[16:31]
	s_waitcnt lgkmcnt(0)
	v_mfma_f32_32x32x16_bf16 v[0:15], v[44:47], v[36:39], v[0:15]
	ds_read2_b64 v[36:39], v61 offset0:140 offset1:142
	ds_read2_b64 v[40:43], v60 offset0:172 offset1:174
	s_waitcnt lgkmcnt(1)
	v_mfma_f32_32x32x16_bf16 v[16:31], v[36:39], v[32:35], v[16:31]
	s_waitcnt lgkmcnt(0)
	v_mfma_f32_32x32x16_bf16 v[0:15], v[40:43], v[32:35], v[0:15]
	s_cbranch_vccnz .LBB0_402
; #define LAS __attribute__((address_space(3)))
; template <int MASK> ...
;     f32x16 p0, p1;
; #pragma unroll
;     for (int r = 0; r < 16; ++r) { p0[r] = 0.f; p1[r] = 0.f; }
;     p0 = __builtin_amdgcn_mfma_f32_32x32x16_bf16(kx0, qx, p0, 0, 0, 0);
;     p1 = __builtin_amdgcn_mfma_f32_32x32x16_bf16(kx1, qx, p1, 0, 0, 0);
;     LAS const unsigned char* kp = Kb + r32 * 144 + hi * 16;
; #pragma unroll
;     for (int d0 = 0; d0 < 4; ++d0) {
;         const bf16x8 a0 = *(LAS const bf16x8*)(kp + d0 * 32), a1 = *(LAS const bf16x8*)(kp + 32 * 144 + d0 * 32);
;         p0 = __builtin_amdgcn_mfma_f32_32x32x16_bf16(a0, qf[d0], p0, 0, 0, 0);
;         p1 = __builtin_amdgcn_mfma_f32_32x32x16_bf16(a1, qf[d0], p1, 0, 0, 0);
;     }
;     constexpr float C2 = 0.125f * LOG2E;
;     const float NEG = -INFINITY;
;     if (MASK != 0) {
;         const int dk0 = kq + 4 * hi;
; #pragma unroll
;         for (int r = 0; r < 16; ++r) { const int kk = (r & 3) + 8 * (r >> 2);
;             if (MASK == 1) { if (dk0 > -kk) p0[r] = NEG; if (dk0 > -(kk + 32)) p1[r] = NEG; }
;             if (MASK == 3) { if (dk0 <= -128 - kk) p0[r] = NEG; if (dk0 <= -160 - kk) p1[r] = NEG; } }
;     }
;     float mr = fmaxf(p0[0], p1[0]);
; #pragma unroll
;     for (int r = 1; r < 16; ++r) mr = fmaxf(fmaxf(mr, p0[r]), p1[r]);
;     float mx = fmaf(mr, C2, off);
;     mx = fmaxf(mx, __shfl_xor(mx, 32));
;     const float mn = fmaxf(m, mx);
;     if (__ballot(mn > m) != 0ull) {
;         const float alpha = __builtin_amdgcn_exp2f(m - mn); l *= alpha;
; #pragma unroll
;         for (int r = 0; r < 16; ++r) { o0[r] *= alpha; o1[r] *= alpha; }
;     }
	ds_read_b128 v[138:141], v129 offset:9216
	v_mfma_f32_32x32x16_bf16 v[48:63], v[92:95], v[64:67], 0
	s_waitcnt lgkmcnt(0)
	v_mfma_f32_32x32x16_bf16 v[48:63], v[138:141], v[112:115], v[48:63]
	ds_read_b128 v[138:141], v129 offset:13824
	v_mfma_f32_32x32x16_bf16 v[32:47], v[96:99], v[64:67], 0
	s_waitcnt lgkmcnt(0)
	v_mfma_f32_32x32x16_bf16 v[32:47], v[138:141], v[112:115], v[32:47]
	ds_read_b128 v[138:141], v129 offset:9248
	s_waitcnt lgkmcnt(0)
	v_mfma_f32_32x32x16_bf16 v[48:63], v[138:141], v[108:111], v[48:63]
	ds_read_b128 v[138:141], v129 offset:13856
	s_waitcnt lgkmcnt(0)
	v_mfma_f32_32x32x16_bf16 v[32:47], v[138:141], v[108:111], v[32:47]
	ds_read_b128 v[138:141], v129 offset:9280
	s_waitcnt lgkmcnt(0)
	v_mfma_f32_32x32x16_bf16 v[48:63], v[138:141], v[104:107], v[48:63]
	ds_read_b128 v[138:141], v129 offset:13888
	s_waitcnt lgkmcnt(0)
	v_mfma_f32_32x32x16_bf16 v[32:47], v[138:141], v[104:107], v[32:47]
	ds_read_b128 v[138:141], v129 offset:13920
	s_waitcnt lgkmcnt(0)
	v_mfma_f32_32x32x16_bf16 v[32:47], v[138:141], v[100:103], v[32:47]
	ds_read_b128 v[140:143], v129 offset:9312
	v_mul_f32_e32 v138, v134, v127
	s_waitcnt lgkmcnt(0)
	v_mfma_f32_32x32x16_bf16 v[48:63], v[140:143], v[100:103], v[48:63]
	s_nop 7
	v_max_f32_e32 v136, v32, v32
	s_nop 2
	v_max_f32_e32 v139, v48, v48
	v_max_f32_e32 v136, v139, v136
	v_max3_f32 v136, v136, v49, v33
	v_max3_f32 v136, v136, v50, v34
	v_max3_f32 v136, v136, v51, v35
	v_max3_f32 v136, v136, v52, v36
	v_max3_f32 v136, v136, v53, v37
	v_max3_f32 v136, v136, v54, v38
	v_max3_f32 v136, v136, v55, v39
	v_max3_f32 v136, v136, v56, v40
	v_max3_f32 v136, v136, v57, v41
	v_max3_f32 v136, v136, v58, v42
	v_max3_f32 v136, v136, v59, v43
	v_max3_f32 v136, v136, v60, v44
	v_max3_f32 v136, v136, v61, v45
	v_max3_f32 v136, v136, v62, v46
	v_max3_f32 v136, v136, v63, v47
	v_fmamk_f32 v136, v136, 0x3e38aa3b, v138
	ds_bpermute_b32 v139, v126, v136
	s_waitcnt lgkmcnt(0)
	v_max3_f32 v136, v137, v136, v139
	v_cmp_gt_f32_e32 vcc, v136, v137
	s_cbranch_vccz .LBB0_401
	v_sub_f32_e32 v137, v137, v136
	v_exp_f32_e32 v140, v137
	s_nop 0
	v_mul_f32_e32 v135, v135, v140
	v_mul_f32_e32 v30, v30, v140
	v_mul_f32_e32 v31, v31, v140
	v_mul_f32_e32 v28, v28, v140
	v_mul_f32_e32 v29, v29, v140
	v_mul_f32_e32 v26, v26, v140
	v_mul_f32_e32 v27, v27, v140
	v_mul_f32_e32 v24, v24, v140
	v_mul_f32_e32 v25, v25, v140
	v_mul_f32_e32 v22, v22, v140
	v_mul_f32_e32 v23, v23, v140
	v_mul_f32_e32 v20, v20, v140
	v_mul_f32_e32 v21, v21, v140
	v_mul_f32_e32 v18, v18, v140
	v_mul_f32_e32 v19, v19, v140
	v_mul_f32_e32 v16, v16, v140
	v_mul_f32_e32 v17, v17, v140
	v_mul_f32_e32 v14, v14, v140
	v_mul_f32_e32 v15, v15, v140
	v_mul_f32_e32 v12, v12, v140
	v_mul_f32_e32 v13, v13, v140
	v_mul_f32_e32 v10, v10, v140
	v_mul_f32_e32 v11, v11, v140
	v_mul_f32_e32 v8, v8, v140
	v_mul_f32_e32 v9, v9, v140
	v_mul_f32_e32 v6, v6, v140
	v_mul_f32_e32 v7, v7, v140
	v_mul_f32_e32 v4, v4, v140
	v_mul_f32_e32 v5, v5, v140
	v_mul_f32_e32 v2, v2, v140
	v_mul_f32_e32 v3, v3, v140
	v_mul_f32_e32 v0, v0, v140
	v_mul_f32_e32 v1, v1, v140
; #define LAS __attribute__((address_space(3)))
; __device__ __forceinline__ unsigned pk2(float lo, float hi) { return pg8::cvt_pk_bf16(lo, hi); }
; template <int MASK> ...
;     ...
;     m = mn;
;     const float sh = off - mn;
;     float rs = 0.f;
; #pragma unroll
;     for (int r = 0; r < 16; ++r) { p0[r] = __builtin_amdgcn_exp2f(fmaf(p0[r], C2, sh)); p1[r] = __builtin_amdgcn_exp2f(fmaf(p1[r], C2, sh)); rs += p0[r] + p1[r]; }
;     l += rs;
;     u32x4 pw[4];
;     pw[0] = (u32x4){pk2(p0[0], p0[1]), pk2(p0[2], p0[3]), pk2(p0[4], p0[5]), pk2(p0[6], p0[7])};
;     pw[1] = (u32x4){pk2(p0[8], p0[9]), pk2(p0[10], p0[11]), pk2(p0[12], p0[13]), pk2(p0[14], p0[15])};
;     pw[2] = (u32x4){pk2(p1[0], p1[1]), pk2(p1[2], p1[3]), pk2(p1[4], p1[5]), pk2(p1[6], p1[7])};
;     pw[3] = (u32x4){pk2(p1[8], p1[9]), pk2(p1[10], p1[11]), pk2(p1[12], p1[13]), pk2(p1[14], p1[15])};
;     LAS const unsigned char* vp = Vb + r32 * 136 + hi * 8;
; #pragma unroll
;     for (int ks = 0; ks < 4; ++ks) {
;         const int koff = (32 * (ks >> 1) + 16 * (ks & 1)) * 2;
;         const s16x4 a0l = *(LAS const s16x4*)(vp + koff), a0h = *(LAS const s16x4*)(vp + koff + 16);
;         const s16x4 a1l = *(LAS const s16x4*)(vp + 32 * 136 + koff), a1h = *(LAS const s16x4*)(vp + 32 * 136 + koff + 16);
;         const bf16x8 A0 = (bf16x8){a0l[0], a0l[1], a0l[2], a0l[3], a0h[0], a0h[1], a0h[2], a0h[3]};
;         const bf16x8 A1 = (bf16x8){a1l[0], a1l[1], a1l[2], a1l[3], a1h[0], a1h[1], a1h[2], a1h[3]};
;         const bf16x8 P = __builtin_bit_cast(bf16x8, pw[ks]);
;         o0 = __builtin_amdgcn_mfma_f32_32x32x16_bf16(A0, P, o0, 0, 0, 0);
;         o1 = __builtin_amdgcn_mfma_f32_32x32x16_bf16(A1, P, o1, 0, 0, 0);
;     }
.LBB0_401:
	v_sub_f32_e32 v137, v138, v136
	v_fmamk_f32 v48, v48, 0x3e38aa3b, v137
	v_fmamk_f32 v32, v32, 0x3e38aa3b, v137
	v_exp_f32_e32 v146, v48
	v_exp_f32_e32 v147, v32
	v_fmamk_f32 v32, v49, 0x3e38aa3b, v137
	v_fmamk_f32 v33, v33, 0x3e38aa3b, v137
	v_exp_f32_e32 v32, v32
	v_exp_f32_e32 v138, v33
	v_add_f32_e32 v139, v147, v146
	v_mov_b32_e32 v33, v65
	v_fmamk_f32 v34, v34, 0x3e38aa3b, v137
	v_add_f32_e32 v48, v138, v32
	v_add_f32_e32 v49, v139, v33
	v_fmamk_f32 v33, v50, 0x3e38aa3b, v137
	v_add_f32_e32 v49, v48, v49
	v_add_f32_e32 v48, v48, v48
	v_exp_f32_e32 v139, v34
	v_fmamk_f32 v34, v51, 0x3e38aa3b, v137
	v_exp_f32_e32 v33, v33
	v_exp_f32_e32 v48, v34
	v_fmamk_f32 v34, v35, 0x3e38aa3b, v137
	v_exp_f32_e32 v140, v34
	v_add_f32_e32 v141, v139, v33
	s_movk_i32 s75, 0xffe0
	s_movk_i32 s72, 0xffdf
	v_add_f32_e32 v34, v140, v48
	v_add_f32_e32 v35, v141, v49
	s_movk_i32 s74, 0xffde
	v_add_f32_e32 v35, v34, v35
	v_add_f32_e32 v34, v34, v34
	v_fmamk_f32 v34, v52, 0x3e38aa3b, v137
	v_exp_f32_e32 v49, v34
	v_fmamk_f32 v34, v36, 0x3e38aa3b, v137
	v_exp_f32_e32 v141, v34
	v_fmamk_f32 v34, v53, 0x3e38aa3b, v137
	v_fmamk_f32 v36, v37, 0x3e38aa3b, v137
	v_exp_f32_e32 v34, v34
	v_exp_f32_e32 v50, v36
	v_add_f32_e32 v51, v141, v49
	s_movk_i32 s78, 0xffd8
	s_movk_i32 s80, 0xffd7
	v_add_f32_e32 v36, v50, v34
	v_add_f32_e32 v37, v51, v35
	v_fmamk_f32 v35, v54, 0x3e38aa3b, v137
	v_add_f32_e32 v37, v36, v37
	v_add_f32_e32 v36, v36, v36
	v_fmamk_f32 v36, v38, 0x3e38aa3b, v137
	v_exp_f32_e32 v35, v35
	v_exp_f32_e32 v51, v36
	v_fmamk_f32 v36, v55, 0x3e38aa3b, v137
	v_fmamk_f32 v38, v39, 0x3e38aa3b, v137
	v_exp_f32_e32 v36, v36
	v_exp_f32_e32 v52, v38
	v_add_f32_e32 v53, v51, v35
	s_movk_i32 s73, 0xffd6
	s_movk_i32 s76, 0xffd0
	v_add_f32_e32 v38, v52, v36
	v_add_f32_e32 v39, v53, v37
	v_fmamk_f32 v37, v56, 0x3e38aa3b, v137
	v_add_f32_e32 v39, v38, v39
	v_add_f32_e32 v38, v38, v38
	v_fmamk_f32 v38, v40, 0x3e38aa3b, v137
	v_exp_f32_e32 v37, v37
	v_exp_f32_e32 v53, v38
	v_fmamk_f32 v38, v57, 0x3e38aa3b, v137
	v_fmamk_f32 v40, v41, 0x3e38aa3b, v137
	v_exp_f32_e32 v38, v38
	v_exp_f32_e32 v54, v40
	v_add_f32_e32 v55, v53, v37
	s_movk_i32 s88, 0xffef
	s_movk_i32 s77, 0xffcf
	v_add_f32_e32 v40, v54, v38
	v_add_f32_e32 v41, v55, v39
	v_fmamk_f32 v39, v58, 0x3e38aa3b, v137
	v_add_f32_e32 v56, v40, v40
	v_add_f32_e32 v57, v40, v41
	v_fmamk_f32 v40, v42, 0x3e38aa3b, v137
	v_exp_f32_e32 v55, v40
	v_fmamk_f32 v40, v59, 0x3e38aa3b, v137
	v_exp_f32_e32 v39, v39
	v_exp_f32_e32 v56, v40
	v_fmamk_f32 v40, v43, 0x3e38aa3b, v137
	v_exp_f32_e32 v142, v40
	v_add_f32_e32 v143, v55, v39
	s_movk_i32 s90, 0xffee
	s_movk_i32 s79, 0xffce
	v_add_f32_e32 v40, v142, v56
	v_add_f32_e32 v41, v143, v57
	s_movk_i32 s94, 0xffe8
	v_add_f32_e32 v42, v40, v40
	v_add_f32_e32 v43, v40, v41
	v_fmamk_f32 v40, v60, 0x3e38aa3b, v137
	v_exp_f32_e32 v57, v40
	v_fmamk_f32 v40, v44, 0x3e38aa3b, v137
	v_exp_f32_e32 v143, v40
	v_fmamk_f32 v40, v61, 0x3e38aa3b, v137
	v_exp_f32_e32 v42, v40
	v_fmamk_f32 v40, v45, 0x3e38aa3b, v137
	v_exp_f32_e32 v58, v40
	v_add_f32_e32 v59, v143, v57
	v_cvt_pk_bf16_f32 v45, v33, v48
	v_cvt_pk_bf16_f32 v44, v146, v32
	v_add_f32_e32 v40, v58, v42
	v_add_f32_e32 v41, v59, v43
	v_cvt_pk_bf16_f32 v42, v57, v42
	v_add_f32_e32 v60, v40, v40
	v_add_f32_e32 v61, v40, v41
	v_fmamk_f32 v40, v62, 0x3e38aa3b, v137
	v_exp_f32_e32 v43, v40
	v_fmamk_f32 v40, v46, 0x3e38aa3b, v137
	v_exp_f32_e32 v59, v40
	v_fmamk_f32 v40, v63, 0x3e38aa3b, v137
	v_fmac_f32_e32 v137, 0x3e38aa3b, v47
	v_exp_f32_e32 v60, v40
	v_exp_f32_e32 v144, v137
	v_add_f32_e32 v145, v59, v43
	v_cvt_pk_bf16_f32 v46, v49, v34
	v_cvt_pk_bf16_f32 v43, v43, v60
	v_add_f32_e32 v40, v144, v60
	v_add_f32_e32 v41, v145, v61
	v_add_u32_e32 v60, 0x9800, v130
	v_add_f32_e32 v40, v40, v41
	v_add_f32_e32 v135, v40, v135
	v_cvt_pk_bf16_f32 v40, v37, v38
	v_cvt_pk_bf16_f32 v41, v39, v56
	v_cvt_pk_bf16_f32 v38, v141, v50
	v_cvt_pk_bf16_f32 v39, v51, v52
	ds_read2_b64 v[48:51], v60 offset0:224 offset1:226
	v_add_u32_e32 v61, 0x8800, v130
	v_cvt_pk_bf16_f32 v47, v35, v36
	v_cvt_pk_bf16_f32 v32, v53, v54
	v_cvt_pk_bf16_f32 v33, v55, v142
	v_cvt_pk_bf16_f32 v34, v143, v58
	v_cvt_pk_bf16_f32 v35, v59, v144
	ds_read2_b64 v[52:55], v61 offset0:192 offset1:194
	ds_read2_b64 v[56:59], v61 offset0:196 offset1:198
	s_waitcnt lgkmcnt(1)
	v_mfma_f32_32x32x16_bf16 v[16:31], v[52:55], v[44:47], v[16:31]
	v_cvt_pk_bf16_f32 v36, v147, v138
	v_cvt_pk_bf16_f32 v37, v139, v140
	s_movk_i32 s81, 0xffc8
	s_movk_i32 s96, 0xffe7
	s_movk_i32 s82, 0xffc7
	s_movk_i32 s83, 0xffe6
	s_movk_i32 s84, 0xffc6
	v_mfma_f32_32x32x16_bf16 v[0:15], v[48:51], v[44:47], v[0:15]
	ds_read2_b64 v[44:47], v60 offset0:228 offset1:230
	s_waitcnt lgkmcnt(1)
	v_mfma_f32_32x32x16_bf16 v[16:31], v[56:59], v[40:43], v[16:31]
	s_waitcnt lgkmcnt(0)
	v_mfma_f32_32x32x16_bf16 v[0:15], v[44:47], v[40:43], v[0:15]
	ds_read2_b64 v[40:43], v61 offset0:200 offset1:202
	ds_read2_b64 v[44:47], v60 offset0:232 offset1:234
	s_waitcnt lgkmcnt(1)
	v_mfma_f32_32x32x16_bf16 v[16:31], v[40:43], v[36:39], v[16:31]
	s_waitcnt lgkmcnt(0)
	v_mfma_f32_32x32x16_bf16 v[0:15], v[44:47], v[36:39], v[0:15]
	ds_read2_b64 v[36:39], v61 offset0:204 offset1:206
	ds_read2_b64 v[40:43], v60 offset0:236 offset1:238
	s_waitcnt lgkmcnt(1)
	v_mfma_f32_32x32x16_bf16 v[16:31], v[36:39], v[32:35], v[16:31]
	s_waitcnt lgkmcnt(0)
	v_mfma_f32_32x32x16_bf16 v[0:15], v[40:43], v[32:35], v[0:15]
	s_cmp_lt_u32 s34, 2
	s_cbranch_scc1 .LBB0_386
	s_branch .LBB0_403
